# FFN-up epilogue GELU: sign handled as 0.5*x + |x|*(0.5 - q) instead of compare/select between x*q and x - x*q (same erf form, f32)
# speedup vs baseline: 1.0035x; 1.0035x over previous
; __device__ __forceinline__ f32x4 gelu4(f32x4 v) { const f32x2 a = gelu_pk((f32x2){v[0], v[1]}), b = gelu_pk((f32x2){v[2], v[3]}); return (f32x4){a.x, a.y, b.x, b.y}; }
; __device__ __forceinline__ f32x4 ror1v(f32x4 v) { return (f32x4){dpp_ror1(v[0]), dpp_ror1(v[1]), dpp_ror1(v[2]), dpp_ror1(v[3])}; }
; __device__ __forceinline__ f32x4 ror2v(f32x4 v) { return (f32x4){dpp_ror2(v[0]), dpp_ror2(v[1]), dpp_ror2(v[2]), dpp_ror2(v[3])}; }
; __device__ __forceinline__ u32x2 pack4(f32x4 v) { return (u32x2){pk2(v[0], v[1]), pk2(v[2], v[3])}; }
; __device__ __forceinline__ f32x2 gelu_pk(f32x2 v) {
;     const f32x2 av = __builtin_elementwise_abs(v), d = av * 0.2316418882f + 1.0f;
;     f32x2 t; t.x = __builtin_amdgcn_rcpf(d.x); t.y = __builtin_amdgcn_rcpf(d.y);
;     f32x2 q = t * 0.5307027145f + (-0.7265760135f); q = q * t + 0.7107068705f; q = q * t + (-0.142248368f); q = q * t + 0.127414796f; q = q * t;
;     const f32x2 s = (v * v) * (-0.72134752044f);
;     f32x2 e; e.x = __builtin_amdgcn_exp2f(s.x); e.y = __builtin_amdgcn_exp2f(s.y);
;     const f32x2 m = v * (q * e), r = v - m;
;     f32x2 o; o.x = v.x < 0.f ? m.x : r.x; o.y = v.y < 0.f ? m.y : r.y; return o;
;     __device__ __forceinline__ void operator()(AccRef acc, const Unit& u, int wr, int wc, int fr, int fq) const {
;     ...
;                     const f32x4 wg0 = *(const f32x4*)(cw + jn), wg1 = *(const f32x4*)(cw + (UPN + jn)), wg2 = *(const f32x4*)(cw + (2 * UPN + jn)), bg = *(const f32x4*)(cb + jn);
;                     f32x4 pg1 = (f32x4){0.f, 0.f, 0.f, 0.f}, pg2 = pg1;
; #pragma unroll
;                     for (int m = 0; m < 4; ++m) { const int row = rowg + m * 16 + fr;
;                         const f32x4 ag = unpack4(pa[ai][0][m][n]);
;                         const f32x4 rg1 = ror1v(ag), rg2 = ror2v(ag);
;                         const f32x4 g1 = fr >= 1 ? rg1 : pg1, g2 = fr >= 2 ? rg2 : pg2;
;                         if (m == 0 && fr < 2) *(f32x4*)(edge + (unsigned)((grp * 4 + fr) * UPN + jn)) = ag;
;                         if (m == 3 && fr >= 14) *(f32x4*)(edge + (unsigned)((grp * 4 + (fr - 12)) * UPN + jn)) = ag;
;                         const f32x4 o = gelu4(bg + wg0 * g2 + wg1 * g1 + wg2 * ag) * cu[m];
;                         if (!(m == 0 && fr < 2)) *(u32x2*)(act + (unsigned)(row * DFF + jn)) = pack4(o);
.LBB0_553:
	s_or_b64 exec, exec, s[0:1]
	v_mov_b32_e32 v45, v137
	v_add_u32_e32 v136, 0x1600, v44
	v_lshlrev_b64 v[32:33], 2, v[44:45]
	v_lshl_add_u64 v[60:61], v[136:137], 2, s[66:67]
	v_add_u32_e32 v136, 0x2c00, v44
	v_lshl_add_u64 v[46:47], s[66:67], 0, v[32:33]
	v_lshl_add_u64 v[64:65], v[136:137], 2, s[66:67]
	v_lshl_add_u64 v[48:49], s[36:37], 0, v[32:33]
	global_load_dwordx4 v[28:31], v[46:47], off
	global_load_dwordx4 v[20:23], v[60:61], off
	global_load_dwordx4 v[24:27], v[64:65], off
	global_load_dwordx4 v[32:35], v[48:49], off
	v_lshlrev_b32_e32 v40, 16, v190
	v_and_b32_e32 v41, 0xffff0000, v190
	v_lshlrev_b32_e32 v42, 16, v189
	v_and_b32_e32 v43, 0xffff0000, v189
	s_nop 1
	v_cmp_lt_i32_e64 s[8:9], 0, v166
	v_cmp_lt_i32_e64 s[6:7], 1, v166
	v_mov_b32_dpp v70, v40 row_ror:1 row_mask:0xf bank_mask:0xf
	v_mov_b32_dpp v71, v41 row_ror:1 row_mask:0xf bank_mask:0xf
	v_mov_b32_dpp v72, v42 row_ror:1 row_mask:0xf bank_mask:0xf
	v_mov_b32_dpp v73, v43 row_ror:1 row_mask:0xf bank_mask:0xf
	v_mov_b32_dpp v74, v40 row_ror:2 row_mask:0xf bank_mask:0xf
	v_mov_b32_dpp v75, v41 row_ror:2 row_mask:0xf bank_mask:0xf
	v_mov_b32_dpp v76, v42 row_ror:2 row_mask:0xf bank_mask:0xf
	v_mov_b32_dpp v77, v43 row_ror:2 row_mask:0xf bank_mask:0xf
	s_and_saveexec_b64 s[0:1], s[10:11]
	s_xor_b64 s[76:77], exec, s[0:1]
	s_cbranch_execz .LBB0_555
	v_cndmask_b32_e64 v213, 0, v204, s[6:7]
	v_cndmask_b32_e64 v212, 0, v201, s[6:7]
	v_cndmask_b32_e64 v211, 0, v196, s[8:9]
	v_cndmask_b32_e64 v210, 0, v192, s[8:9]
	s_waitcnt vmcnt(4)
	v_pk_fma_f32 v[212:213], v[10:11], v[212:213], v[14:15]
	v_cndmask_b32_e64 v215, 0, v197, s[6:7]
	v_pk_fma_f32 v[210:211], v[2:3], v[210:211], v[212:213]
	v_cndmask_b32_e64 v214, 0, v193, s[6:7]
	v_pk_fma_f32 v[38:39], v[6:7], v[38:39], v[210:211]
	s_waitcnt vmcnt(0)
	v_pk_fma_f32 v[210:211], v[28:29], v[74:75], v[32:33]
	v_cndmask_b32_e64 v209, 0, v194, s[8:9]
	v_pk_fma_f32 v[210:211], v[20:21], v[70:71], v[210:211]
	v_cndmask_b32_e64 v208, 0, v191, s[8:9]
	v_pk_fma_f32 v[40:41], v[24:25], v[40:41], v[210:211]
	v_pk_fma_f32 v[214:215], v[8:9], v[214:215], v[12:13]
	v_and_b32_e32 v213, 0x7fffffff, v41
	v_and_b32_e32 v212, 0x7fffffff, v40
	v_pk_fma_f32 v[212:213], v[212:213], s[42:43], 1.0 op_sel_hi:[1,0,0]
	v_pk_fma_f32 v[208:209], v[0:1], v[208:209], v[214:215]
	v_rcp_f32_e32 v212, v212
	v_rcp_f32_e32 v213, v213
	v_pk_mul_f32 v[210:211], v[40:41], v[40:41]
	v_mov_b64_e32 v[214:215], s[54:55]
	v_pk_mul_f32 v[210:211], v[210:211], s[38:39] op_sel_hi:[1,0]
	v_pk_fma_f32 v[216:217], v[212:213], s[52:53], v[214:215] op_sel_hi:[1,0,0]
	v_exp_f32_e32 v210, v210
	v_exp_f32_e32 v211, v211
	v_pk_fma_f32 v[216:217], v[212:213], v[216:217], s[56:57] op_sel_hi:[1,1,0]
	v_pk_fma_f32 v[36:37], v[4:5], v[36:37], v[208:209]
	v_pk_fma_f32 v[216:217], v[212:213], v[216:217], s[62:63] op_sel_hi:[1,1,0]
	v_pk_fma_f32 v[208:209], v[30:31], v[76:77], v[34:35]
	v_pk_fma_f32 v[216:217], v[212:213], v[216:217], s[64:65] op_sel_hi:[1,1,0]
	v_pk_fma_f32 v[208:209], v[22:23], v[72:73], v[208:209]
	v_pk_mul_f32 v[212:213], v[212:213], v[216:217]
	s_nop 0
	v_pk_fma_f32 v[210:211], v[210:211], v[212:213], 0.5 op_sel_hi:[1,1,0] neg_lo:[1,0,0] neg_hi:[1,0,0]
	v_pk_fma_f32 v[42:43], v[26:27], v[42:43], v[208:209]
	v_mul_f32_e64 v212, |v40|, v210
	v_mul_f32_e64 v213, |v41|, v211
	v_pk_mul_f32 v[208:209], v[42:43], v[42:43]
	s_nop 0
	v_and_b32_e32 v210, 0x7fffffff, v42
	v_pk_mul_f32 v[208:209], v[208:209], s[38:39] op_sel_hi:[1,0]
	v_pk_fma_f32 v[40:41], v[40:41], 0.5, v[212:213] op_sel_hi:[1,0,1]
	v_and_b32_e32 v211, 0x7fffffff, v43
	v_pk_fma_f32 v[210:211], v[210:211], s[42:43], 1.0 op_sel_hi:[1,0,0]
	v_exp_f32_e32 v208, v208
	v_rcp_f32_e32 v210, v210
	v_rcp_f32_e32 v211, v211
	v_exp_f32_e32 v209, v209
	s_nop 0
	v_pk_mul_f32 v[36:37], v[36:37], v[40:41]
	v_pk_fma_f32 v[212:213], v[210:211], s[52:53], v[214:215] op_sel_hi:[1,0,0]
	v_cvt_pk_bf16_f32 v36, v36, v37
	s_nop 0
	v_pk_fma_f32 v[212:213], v[210:211], v[212:213], s[56:57] op_sel_hi:[1,1,0]
	s_nop 0
	v_pk_fma_f32 v[212:213], v[210:211], v[212:213], s[62:63] op_sel_hi:[1,1,0]
	s_nop 0
	v_pk_fma_f32 v[212:213], v[210:211], v[212:213], s[64:65] op_sel_hi:[1,1,0]
	s_nop 0
	v_pk_mul_f32 v[210:211], v[210:211], v[212:213]
	s_nop 0
	v_pk_fma_f32 v[208:209], v[208:209], v[210:211], 0.5 op_sel_hi:[1,1,0] neg_lo:[1,0,0] neg_hi:[1,0,0]
	s_nop 0
	v_mul_f32_e64 v210, |v42|, v208
	v_mul_f32_e64 v211, |v43|, v209
	v_pk_fma_f32 v[42:43], v[42:43], 0.5, v[210:211] op_sel_hi:[1,0,1]
	v_pk_mul_f32 v[38:39], v[38:39], v[42:43]
	s_nop 0
	v_cvt_pk_bf16_f32 v37, v38, v39
	v_mad_u64_u32 v[38:39], s[0:1], v146, s88, v[44:45]
	v_mov_b32_e32 v39, v137
	v_lshl_add_u64 v[38:39], v[38:39], 1, s[26:27]
	global_store_dwordx2 v[38:39], v[36:37], off

; __device__ __forceinline__ f32x2 gelu_pk(f32x2 v) {
;     const f32x2 av = __builtin_elementwise_abs(v), d = av * 0.2316418882f + 1.0f;
;     f32x2 t; t.x = __builtin_amdgcn_rcpf(d.x); t.y = __builtin_amdgcn_rcpf(d.y);
;     __device__ __forceinline__ void operator()(AccRef acc, const Unit& u, int wr, int wc, int fr, int fq) const {
;     ...
;                     const f32x4 wu0 = *(const f32x4*)(cw + (DFF + jn)), wu1 = *(const f32x4*)(cw + (UPN + DFF + jn)), wu2 = *(const f32x4*)(cw + (2 * UPN + DFF + jn)), bu = *(const f32x4*)(cb + (DFF + jn));
;                     f32x4 pu1 = (f32x4){0.f, 0.f, 0.f, 0.f}, pu2 = pu1;
; #pragma unroll
;                     for (int m = 0; m < 4; ++m) {
;                         const f32x4 au = unpack4(pa[ai][1][m][n]);
;                         const f32x4 ru1 = ror1v(au), ru2 = ror2v(au);
;                         const f32x4 u1 = fr >= 1 ? ru1 : pu1, u2 = fr >= 2 ? ru2 : pu2;
;                         if (m == 0 && fr < 2) *(f32x4*)(edge + (unsigned)((grp * 4 + fr) * UPN + DFF + jn)) = au;
;                         if (m == 3 && fr >= 14) *(f32x4*)(edge + (unsigned)((grp * 4 + (fr - 12)) * UPN + DFF + jn)) = au;
;                         cu[m] = bu + wu0 * u2 + wu1 * u1 + wu2 * au;
;                         pu1 = ru1; pu2 = ru2; }
;                 }
;                 {
;                     const f32x4 wg0 = *(const f32x4*)(cw + jn), wg1 = *(const f32x4*)(cw + (UPN + jn)), wg2 = *(const f32x4*)(cw + (2 * UPN + jn)), bg = *(const f32x4*)(cb + jn);
;                     f32x4 pg1 = (f32x4){0.f, 0.f, 0.f, 0.f}, pg2 = pg1;
; #pragma unroll
;                     for (int m = 0; m < 4; ++m) { const int row = rowg + m * 16 + fr;
;                         const f32x4 ag = unpack4(pa[ai][0][m][n]);
;                         const f32x4 rg1 = ror1v(ag), rg2 = ror2v(ag);
;                         const f32x4 g1 = fr >= 1 ? rg1 : pg1, g2 = fr >= 2 ? rg2 : pg2;
;                         if (m == 0 && fr < 2) *(f32x4*)(edge + (unsigned)((grp * 4 + fr) * UPN + jn)) = ag;
;                         if (m == 3 && fr >= 14) *(f32x4*)(edge + (unsigned)((grp * 4 + (fr - 12)) * UPN + jn)) = ag;
;                         const f32x4 o = gelu4(bg + wg0 * g2 + wg1 * g1 + wg2 * ag) * cu[m];
;                         if (!(m == 0 && fr < 2)) *(u32x2*)(act + (unsigned)(row * DFF + jn)) = pack4(o);
.LBB0_557:
	s_or_b64 exec, exec, s[0:1]
	s_nop 0
	v_cndmask_b32_e64 v43, v197, v203, s[6:7]
	v_cndmask_b32_e64 v42, v193, v199, s[6:7]
	v_cndmask_b32_e64 v37, v194, v200, s[8:9]
	v_cndmask_b32_e64 v36, v191, v195, s[8:9]
	v_cndmask_b32_e64 v41, v204, v206, s[6:7]
	v_cndmask_b32_e64 v40, v201, v205, s[6:7]
	s_waitcnt vmcnt(4)
	v_pk_fma_f32 v[42:43], v[8:9], v[42:43], v[12:13]
	v_cndmask_b32_e64 v39, v196, v202, s[8:9]
	v_cndmask_b32_e64 v38, v192, v198, s[8:9]
	v_pk_fma_f32 v[40:41], v[10:11], v[40:41], v[14:15]
	v_pk_fma_f32 v[36:37], v[0:1], v[36:37], v[42:43]
	v_pk_fma_f32 v[38:39], v[2:3], v[38:39], v[40:41]
	v_pk_fma_f32 v[36:37], v[4:5], v[68:69], v[36:37]
	v_cndmask_b32_e64 v69, v203, v178, s[6:7]
	v_cndmask_b32_e64 v68, v199, v83, s[6:7]
	v_pk_fma_f32 v[38:39], v[6:7], v[66:67], v[38:39]
	v_cndmask_b32_e64 v41, v200, v87, s[8:9]
	v_cndmask_b32_e64 v40, v195, v79, s[8:9]
	v_cndmask_b32_e64 v67, v206, v180, s[6:7]
	v_cndmask_b32_e64 v66, v205, v179, s[6:7]
	v_pk_fma_f32 v[68:69], v[8:9], v[68:69], v[12:13]
	v_cndmask_b32_e64 v43, v202, v177, s[8:9]
	v_cndmask_b32_e64 v42, v198, v82, s[8:9]
	v_pk_fma_f32 v[66:67], v[10:11], v[66:67], v[14:15]
	v_pk_fma_f32 v[40:41], v[0:1], v[40:41], v[68:69]
	v_pk_fma_f32 v[42:43], v[2:3], v[42:43], v[66:67]
	v_pk_fma_f32 v[68:69], v[4:5], v[62:63], v[40:41]
	v_lshlrev_b32_e32 v40, 16, v175
	v_and_b32_e32 v41, 0xffff0000, v175
	s_nop 1
	v_pk_fma_f32 v[190:191], v[6:7], v[50:51], v[42:43]
	v_lshlrev_b32_e32 v42, 16, v174
	v_and_b32_e32 v43, 0xffff0000, v174
	s_nop 1
	v_mov_b32_dpp v193, v40 row_ror:2 row_mask:0xf bank_mask:0xf
	v_mov_b32_dpp v194, v41 row_ror:2 row_mask:0xf bank_mask:0xf
	v_mov_b32_dpp v174, v40 row_ror:1 row_mask:0xf bank_mask:0xf
	v_mov_b32_dpp v175, v41 row_ror:1 row_mask:0xf bank_mask:0xf
	v_cndmask_b32_e64 v67, v75, v194, s[6:7]
	v_cndmask_b32_e64 v66, v74, v193, s[6:7]
	v_cndmask_b32_e64 v63, v71, v175, s[8:9]
	v_cndmask_b32_e64 v62, v70, v174, s[8:9]
	s_waitcnt vmcnt(2)
	v_pk_fma_f32 v[66:67], v[28:29], v[66:67], v[32:33]
	s_nop 1
	v_pk_fma_f32 v[62:63], v[20:21], v[62:63], v[66:67]
	s_nop 1
	v_pk_fma_f32 v[40:41], v[24:25], v[40:41], v[62:63]
	s_nop 1
	v_and_b32_e32 v67, 0x7fffffff, v41
	v_and_b32_e32 v66, 0x7fffffff, v40
	v_pk_fma_f32 v[66:67], v[66:67], s[42:43], 1.0 op_sel_hi:[1,0,0]
	s_nop 1
	v_mov_b32_dpp v195, v42 row_ror:2 row_mask:0xf bank_mask:0xf
	v_mov_b32_dpp v196, v43 row_ror:2 row_mask:0xf bank_mask:0xf
	v_rcp_f32_e32 v66, v66
	v_rcp_f32_e32 v67, v67
	v_mov_b32_dpp v189, v42 row_ror:1 row_mask:0xf bank_mask:0xf
	v_mov_b32_dpp v192, v43 row_ror:1 row_mask:0xf bank_mask:0xf
	v_cndmask_b32_e64 v71, v77, v196, s[6:7]
	v_cndmask_b32_e64 v70, v76, v195, s[6:7]
	v_cndmask_b32_e64 v51, v73, v192, s[8:9]
	v_cndmask_b32_e64 v50, v72, v189, s[8:9]
	v_pk_fma_f32 v[70:71], v[30:31], v[70:71], v[34:35]
	v_pk_mul_f32 v[62:63], v[40:41], v[40:41]
	v_pk_fma_f32 v[50:51], v[22:23], v[50:51], v[70:71]
	v_mov_b64_e32 v[70:71], s[54:55]
	v_pk_mul_f32 v[62:63], v[62:63], s[38:39] op_sel_hi:[1,0]
	v_pk_fma_f32 v[72:73], v[66:67], s[52:53], v[70:71] op_sel_hi:[1,0,0]
	v_exp_f32_e32 v62, v62
	v_exp_f32_e32 v63, v63
	v_pk_fma_f32 v[72:73], v[66:67], v[72:73], s[56:57] op_sel_hi:[1,1,0]
	s_nop 0
	v_pk_fma_f32 v[72:73], v[66:67], v[72:73], s[62:63] op_sel_hi:[1,1,0]
	v_pk_fma_f32 v[42:43], v[26:27], v[42:43], v[50:51]
	v_pk_fma_f32 v[72:73], v[66:67], v[72:73], s[64:65] op_sel_hi:[1,1,0]
	v_pk_mul_f32 v[50:51], v[42:43], v[42:43]
	v_pk_mul_f32 v[66:67], v[66:67], v[72:73]
	v_pk_mul_f32 v[50:51], v[50:51], s[38:39] op_sel_hi:[1,0]
	v_pk_fma_f32 v[62:63], v[62:63], v[66:67], 0.5 op_sel_hi:[1,1,0] neg_lo:[1,0,0] neg_hi:[1,0,0]
	v_exp_f32_e32 v50, v50
	v_mul_f32_e64 v66, |v40|, v62
	v_mul_f32_e64 v67, |v41|, v63
	v_exp_f32_e32 v51, v51
	v_and_b32_e32 v62, 0x7fffffff, v42
	v_mul_lo_u32 v45, v148, s88
	v_pk_fma_f32 v[40:41], v[40:41], 0.5, v[66:67] op_sel_hi:[1,0,1]
	v_and_b32_e32 v63, 0x7fffffff, v43
	v_pk_fma_f32 v[62:63], v[62:63], s[42:43], 1.0 op_sel_hi:[1,0,0]
	s_nop 0
	v_rcp_f32_e32 v62, v62
	v_rcp_f32_e32 v63, v63
	v_pk_mul_f32 v[36:37], v[36:37], v[40:41]
	v_add_u32_e32 v136, v45, v44
	v_cvt_pk_bf16_f32 v36, v36, v37
	v_pk_fma_f32 v[66:67], v[62:63], s[52:53], v[70:71] op_sel_hi:[1,0,0]
	s_nop 1
	v_pk_fma_f32 v[66:67], v[62:63], v[66:67], s[56:57] op_sel_hi:[1,1,0]
	s_nop 1
	v_pk_fma_f32 v[66:67], v[62:63], v[66:67], s[62:63] op_sel_hi:[1,1,0]
	s_nop 0
	v_pk_fma_f32 v[66:67], v[62:63], v[66:67], s[64:65] op_sel_hi:[1,1,0]
	s_nop 0
	v_pk_mul_f32 v[62:63], v[62:63], v[66:67]
	s_nop 1
	v_pk_fma_f32 v[50:51], v[50:51], v[62:63], 0.5 op_sel_hi:[1,1,0] neg_lo:[1,0,0] neg_hi:[1,0,0]
	s_nop 1
	v_mul_f32_e64 v62, |v42|, v50
	v_mul_f32_e64 v63, |v43|, v51
	v_pk_fma_f32 v[42:43], v[42:43], 0.5, v[62:63] op_sel_hi:[1,0,1]
	v_pk_mul_f32 v[38:39], v[38:39], v[42:43]
	s_nop 1
	v_cvt_pk_bf16_f32 v37, v38, v39
	v_lshl_add_u64 v[38:39], v[136:137], 1, s[26:27]
	global_store_dwordx2 v[38:39], v[36:37], off
	v_lshlrev_b32_e32 v36, 16, v173
	v_and_b32_e32 v37, 0xffff0000, v173
	s_nop 1
	v_mov_b32_dpp v43, v36 row_ror:2 row_mask:0xf bank_mask:0xf
	v_mov_b32_dpp v40, v36 row_ror:1 row_mask:0xf bank_mask:0xf
	v_mov_b32_dpp v63, v37 row_ror:2 row_mask:0xf bank_mask:0xf
	v_mov_b32_dpp v41, v37 row_ror:1 row_mask:0xf bank_mask:0xf
	v_cndmask_b32_e64 v77, v194, v63, s[6:7]
	v_cndmask_b32_e64 v76, v193, v43, s[6:7]
	v_cndmask_b32_e64 v75, v175, v41, s[8:9]
	v_cndmask_b32_e64 v74, v174, v40, s[8:9]
	v_pk_fma_f32 v[76:77], v[28:29], v[76:77], v[32:33]
	v_lshlrev_b32_e32 v38, 16, v172
	v_pk_fma_f32 v[74:75], v[20:21], v[74:75], v[76:77]
	v_and_b32_e32 v39, 0xffff0000, v172
	v_pk_fma_f32 v[36:37], v[24:25], v[36:37], v[74:75]
; __device__ __forceinline__ f32x4 gelu4(f32x4 v) { const f32x2 a = gelu_pk((f32x2){v[0], v[1]}), b = gelu_pk((f32x2){v[2], v[3]}); return (f32x4){a.x, a.y, b.x, b.y}; }
; __device__ __forceinline__ f32x4 ror1v(f32x4 v) { return (f32x4){dpp_ror1(v[0]), dpp_ror1(v[1]), dpp_ror1(v[2]), dpp_ror1(v[3])}; }
; __device__ __forceinline__ f32x4 ror2v(f32x4 v) { return (f32x4){dpp_ror2(v[0]), dpp_ror2(v[1]), dpp_ror2(v[2]), dpp_ror2(v[3])}; }
; __device__ __forceinline__ u32x2 pack4(f32x4 v) { return (u32x2){pk2(v[0], v[1]), pk2(v[2], v[3])}; }
; __device__ __forceinline__ f32x4 unpack4(u32x2 w) { return (f32x4){bflo(w.x), bfhi(w.x), bflo(w.y), bfhi(w.y)}; }
; __device__ __forceinline__ f32x2 gelu_pk(f32x2 v) {
;     const f32x2 av = __builtin_elementwise_abs(v), d = av * 0.2316418882f + 1.0f;
;     f32x2 t; t.x = __builtin_amdgcn_rcpf(d.x); t.y = __builtin_amdgcn_rcpf(d.y);
;     f32x2 q = t * 0.5307027145f + (-0.7265760135f); q = q * t + 0.7107068705f; q = q * t + (-0.142248368f); q = q * t + 0.127414796f; q = q * t;
;     const f32x2 s = (v * v) * (-0.72134752044f);
;     f32x2 e; e.x = __builtin_amdgcn_exp2f(s.x); e.y = __builtin_amdgcn_exp2f(s.y);
;     const f32x2 m = v * (q * e), r = v - m;
;     f32x2 o; o.x = v.x < 0.f ? m.x : r.x; o.y = v.y < 0.f ? m.y : r.y; return o;
;     __device__ __forceinline__ void operator()(AccRef acc, const Unit& u, int wr, int wc, int fr, int fq) const {
;     ...
;                     for (int m = 0; m < 4; ++m) { const int row = rowg + m * 16 + fr;
;                         const f32x4 ag = unpack4(pa[ai][0][m][n]);
;                         const f32x4 rg1 = ror1v(ag), rg2 = ror2v(ag);
;                         const f32x4 g1 = fr >= 1 ? rg1 : pg1, g2 = fr >= 2 ? rg2 : pg2;
;                         if (m == 0 && fr < 2) *(f32x4*)(edge + (unsigned)((grp * 4 + fr) * UPN + jn)) = ag;
;                         if (m == 3 && fr >= 14) *(f32x4*)(edge + (unsigned)((grp * 4 + (fr - 12)) * UPN + jn)) = ag;
;                         const f32x4 o = gelu4(bg + wg0 * g2 + wg1 * g1 + wg2 * ag) * cu[m];
;                         if (!(m == 0 && fr < 2)) *(u32x2*)(act + (unsigned)(row * DFF + jn)) = pack4(o);
	s_nop 1
	v_and_b32_e32 v77, 0x7fffffff, v37
	v_and_b32_e32 v76, 0x7fffffff, v36
	v_pk_fma_f32 v[76:77], v[76:77], s[42:43], 1.0 op_sel_hi:[1,0,0]
	v_mov_b32_dpp v50, v38 row_ror:2 row_mask:0xf bank_mask:0xf
	v_rcp_f32_e32 v76, v76
	v_rcp_f32_e32 v77, v77
	v_mov_b32_dpp v66, v39 row_ror:2 row_mask:0xf bank_mask:0xf
	v_mov_b32_dpp v42, v38 row_ror:1 row_mask:0xf bank_mask:0xf
	v_mov_b32_dpp v62, v39 row_ror:1 row_mask:0xf bank_mask:0xf
	v_cndmask_b32_e64 v173, v196, v66, s[6:7]
	v_cndmask_b32_e64 v172, v195, v50, s[6:7]
	v_cndmask_b32_e64 v73, v192, v62, s[8:9]
	v_cndmask_b32_e64 v72, v189, v42, s[8:9]
	v_pk_fma_f32 v[172:173], v[30:31], v[172:173], v[34:35]
	v_pk_mul_f32 v[74:75], v[36:37], v[36:37]
	v_pk_fma_f32 v[72:73], v[22:23], v[72:73], v[172:173]
	v_pk_mul_f32 v[74:75], v[74:75], s[38:39] op_sel_hi:[1,0]
	v_pk_fma_f32 v[172:173], v[76:77], s[52:53], v[70:71] op_sel_hi:[1,0,0]
	v_exp_f32_e32 v74, v74
	v_exp_f32_e32 v75, v75
	v_pk_fma_f32 v[172:173], v[76:77], v[172:173], s[56:57] op_sel_hi:[1,1,0]
	s_nop 0
	v_pk_fma_f32 v[172:173], v[76:77], v[172:173], s[62:63] op_sel_hi:[1,1,0]
	v_pk_fma_f32 v[38:39], v[26:27], v[38:39], v[72:73]
	v_pk_fma_f32 v[172:173], v[76:77], v[172:173], s[64:65] op_sel_hi:[1,1,0]
	v_pk_mul_f32 v[72:73], v[38:39], v[38:39]
	v_pk_mul_f32 v[76:77], v[76:77], v[172:173]
	v_pk_mul_f32 v[72:73], v[72:73], s[38:39] op_sel_hi:[1,0]
	v_pk_fma_f32 v[74:75], v[74:75], v[76:77], 0.5 op_sel_hi:[1,1,0] neg_lo:[1,0,0] neg_hi:[1,0,0]
	v_exp_f32_e32 v72, v72
	v_mul_f32_e64 v76, |v36|, v74
	v_mul_f32_e64 v77, |v37|, v75
	v_exp_f32_e32 v73, v73
	v_and_b32_e32 v74, 0x7fffffff, v38
	v_add_u32_e32 v51, 0xb000, v45
	v_pk_fma_f32 v[36:37], v[36:37], 0.5, v[76:77] op_sel_hi:[1,0,1]
	v_and_b32_e32 v75, 0x7fffffff, v39
	v_pk_fma_f32 v[74:75], v[74:75], s[42:43], 1.0 op_sel_hi:[1,0,0]
	s_nop 0
	v_rcp_f32_e32 v74, v74
	v_rcp_f32_e32 v75, v75
	v_pk_mul_f32 v[36:37], v[68:69], v[36:37]
	v_add_u32_e32 v136, v51, v44
	v_cvt_pk_bf16_f32 v36, v36, v37
	v_pk_fma_f32 v[70:71], v[74:75], s[52:53], v[70:71] op_sel_hi:[1,0,0]
	s_nop 1
	v_pk_fma_f32 v[70:71], v[74:75], v[70:71], s[56:57] op_sel_hi:[1,1,0]
	s_nop 1
	v_pk_fma_f32 v[70:71], v[74:75], v[70:71], s[62:63] op_sel_hi:[1,1,0]
	s_nop 0
	v_pk_fma_f32 v[70:71], v[74:75], v[70:71], s[64:65] op_sel_hi:[1,1,0]
	s_nop 0
	v_pk_mul_f32 v[70:71], v[74:75], v[70:71]
	s_nop 1
	v_pk_fma_f32 v[70:71], v[72:73], v[70:71], 0.5 op_sel_hi:[1,1,0] neg_lo:[1,0,0] neg_hi:[1,0,0]
	s_nop 0
	v_mul_f32_e64 v72, |v38|, v70
	v_mul_f32_e64 v73, |v39|, v71
	v_pk_fma_f32 v[38:39], v[38:39], 0.5, v[72:73] op_sel_hi:[1,0,1]
	v_pk_mul_f32 v[38:39], v[190:191], v[38:39]
	s_nop 1
	v_cvt_pk_bf16_f32 v37, v38, v39
	v_lshl_add_u64 v[38:39], v[136:137], 1, s[26:27]
	global_store_dwordx2 v[38:39], v[36:37], off
	v_lshlrev_b32_e32 v36, 16, v80
	v_and_b32_e32 v37, 0xffff0000, v80
	v_lshlrev_b32_e32 v38, 16, v81
	v_and_b32_e32 v39, 0xffff0000, v81
	s_nop 1
	v_mov_b32_dpp v67, v36 row_ror:1 row_mask:0xf bank_mask:0xf
	v_mov_b32_dpp v68, v37 row_ror:1 row_mask:0xf bank_mask:0xf
	v_mov_b32_dpp v69, v38 row_ror:1 row_mask:0xf bank_mask:0xf
	v_mov_b32_dpp v72, v39 row_ror:1 row_mask:0xf bank_mask:0xf
	v_mov_b32_dpp v70, v36 row_ror:2 row_mask:0xf bank_mask:0xf
	v_mov_b32_dpp v73, v37 row_ror:2 row_mask:0xf bank_mask:0xf
	v_mov_b32_dpp v71, v38 row_ror:2 row_mask:0xf bank_mask:0xf
	v_mov_b32_dpp v74, v39 row_ror:2 row_mask:0xf bank_mask:0xf
	s_and_saveexec_b64 s[0:1], vcc
	s_cbranch_execz .LBB0_559
	v_add_u32_e32 v136, v150, v44
	v_lshl_add_u64 v[76:77], v[136:137], 2, s[28:29]
	global_store_dwordx4 v[76:77], v[36:39], off
; __device__ __forceinline__ f32x2 gelu_pk(f32x2 v) {
;     const f32x2 av = __builtin_elementwise_abs(v), d = av * 0.2316418882f + 1.0f;
;     __device__ __forceinline__ void operator()(AccRef acc, const Unit& u, int wr, int wc, int fr, int fq) const {
;     ...
;             for (int n = 0; n < 2; ++n) { const unsigned jn = (unsigned)(j0 + 4 * n);
;                 f32x4 cu[4];
;                 {
;                     const f32x4 wu0 = *(const f32x4*)(cw + (DFF + jn)), wu1 = *(const f32x4*)(cw + (UPN + DFF + jn)), wu2 = *(const f32x4*)(cw + (2 * UPN + DFF + jn)), bu = *(const f32x4*)(cb + (DFF + jn));
;                     f32x4 pu1 = (f32x4){0.f, 0.f, 0.f, 0.f}, pu2 = pu1;
; #pragma unroll
;                     for (int m = 0; m < 4; ++m) {
;                         const f32x4 au = unpack4(pa[ai][1][m][n]);
;                         const f32x4 ru1 = ror1v(au), ru2 = ror2v(au);
;                         const f32x4 u1 = fr >= 1 ? ru1 : pu1, u2 = fr >= 2 ? ru2 : pu2;
;                         if (m == 0 && fr < 2) *(f32x4*)(edge + (unsigned)((grp * 4 + fr) * UPN + DFF + jn)) = au;
;                         if (m == 3 && fr >= 14) *(f32x4*)(edge + (unsigned)((grp * 4 + (fr - 12)) * UPN + DFF + jn)) = au;
;                         cu[m] = bu + wu0 * u2 + wu1 * u1 + wu2 * au;
;                         pu1 = ru1; pu2 = ru2; }
;                 }
;                 {
;                     const f32x4 wg0 = *(const f32x4*)(cw + jn), wg1 = *(const f32x4*)(cw + (UPN + jn)), wg2 = *(const f32x4*)(cw + (2 * UPN + jn)), bg = *(const f32x4*)(cb + jn);
;                     f32x4 pg1 = (f32x4){0.f, 0.f, 0.f, 0.f}, pg2 = pg1;
; #pragma unroll
;                     for (int m = 0; m < 4; ++m) { const int row = rowg + m * 16 + fr;
;                         const f32x4 ag = unpack4(pa[ai][0][m][n]);
;                         const f32x4 rg1 = ror1v(ag), rg2 = ror2v(ag);
;                         const f32x4 g1 = fr >= 1 ? rg1 : pg1, g2 = fr >= 2 ? rg2 : pg2;
;                         if (m == 0 && fr < 2) *(f32x4*)(edge + (unsigned)((grp * 4 + fr) * UPN + jn)) = ag;
;                         if (m == 3 && fr >= 14) *(f32x4*)(edge + (unsigned)((grp * 4 + (fr - 12)) * UPN + jn)) = ag;
;                         const f32x4 o = gelu4(bg + wg0 * g2 + wg1 * g1 + wg2 * ag) * cu[m];
;                         if (!(m == 0 && fr < 2)) *(u32x2*)(act + (unsigned)(row * DFF + jn)) = pack4(o);
.LBB0_559:
	s_or_b64 exec, exec, s[0:1]
	v_cndmask_b32_e64 v77, v62, v72, s[8:9]
	v_cndmask_b32_e64 v76, v42, v69, s[8:9]
	v_cndmask_b32_e64 v62, v43, v70, s[6:7]
	v_cndmask_b32_e64 v42, v50, v71, s[6:7]
	v_cndmask_b32_e64 v71, v180, v188, s[6:7]
	v_cndmask_b32_e64 v70, v179, v187, s[6:7]
	v_cndmask_b32_e64 v41, v41, v68, s[8:9]
	v_cndmask_b32_e64 v69, v177, v185, s[8:9]
	v_cndmask_b32_e64 v68, v82, v182, s[8:9]
	v_pk_fma_f32 v[10:11], v[10:11], v[70:71], v[14:15]
	v_cndmask_b32_e64 v63, v63, v73, s[6:7]
	v_pk_fma_f32 v[2:3], v[2:3], v[68:69], v[10:11]
	v_cndmask_b32_e64 v40, v40, v67, s[8:9]
	v_pk_fma_f32 v[2:3], v[6:7], v[18:19], v[2:3]
	v_pk_fma_f32 v[6:7], v[28:29], v[62:63], v[32:33]
	v_cndmask_b32_e64 v73, v178, v186, s[6:7]
	v_pk_fma_f32 v[6:7], v[20:21], v[40:41], v[6:7]
	v_cndmask_b32_e64 v72, v83, v183, s[6:7]
	v_pk_fma_f32 v[6:7], v[24:25], v[36:37], v[6:7]
	v_pk_fma_f32 v[8:9], v[8:9], v[72:73], v[12:13]
	v_and_b32_e32 v13, 0x7fffffff, v7
	v_and_b32_e32 v12, 0x7fffffff, v6
	v_pk_fma_f32 v[12:13], v[12:13], s[42:43], 1.0 op_sel_hi:[1,0,0]
	v_cndmask_b32_e64 v43, v66, v74, s[6:7]
	v_rcp_f32_e32 v12, v12
	v_rcp_f32_e32 v13, v13
	v_cndmask_b32_e64 v67, v87, v184, s[8:9]
	v_cndmask_b32_e64 v66, v79, v181, s[8:9]
	v_pk_fma_f32 v[0:1], v[0:1], v[66:67], v[8:9]
	v_pk_mul_f32 v[10:11], v[6:7], v[6:7]
	v_mov_b64_e32 v[14:15], s[54:55]
	v_pk_fma_f32 v[0:1], v[4:5], v[16:17], v[0:1]
	v_pk_mul_f32 v[10:11], v[10:11], s[38:39] op_sel_hi:[1,0]
	v_pk_fma_f32 v[16:17], v[12:13], s[52:53], v[14:15] op_sel_hi:[1,0,0]
	v_exp_f32_e32 v10, v10
	v_exp_f32_e32 v11, v11
	v_pk_fma_f32 v[16:17], v[12:13], v[16:17], s[56:57] op_sel_hi:[1,1,0]
	v_pk_fma_f32 v[4:5], v[30:31], v[42:43], v[34:35]
	v_pk_fma_f32 v[16:17], v[12:13], v[16:17], s[62:63] op_sel_hi:[1,1,0]
	v_pk_fma_f32 v[4:5], v[22:23], v[76:77], v[4:5]
	v_pk_fma_f32 v[16:17], v[12:13], v[16:17], s[64:65] op_sel_hi:[1,1,0]
	s_nop 0
	v_pk_mul_f32 v[12:13], v[12:13], v[16:17]
	v_pk_fma_f32 v[4:5], v[26:27], v[38:39], v[4:5]
	v_pk_fma_f32 v[10:11], v[10:11], v[12:13], 0.5 op_sel_hi:[1,1,0] neg_lo:[1,0,0] neg_hi:[1,0,0]
	v_pk_mul_f32 v[8:9], v[4:5], v[4:5]
	v_mul_f32_e64 v12, |v6|, v10
	v_mul_f32_e64 v13, |v7|, v11
	v_pk_mul_f32 v[8:9], v[8:9], s[38:39] op_sel_hi:[1,0]
	s_nop 0
	v_and_b32_e32 v10, 0x7fffffff, v4
	v_exp_f32_e32 v8, v8
	v_pk_fma_f32 v[6:7], v[6:7], 0.5, v[12:13] op_sel_hi:[1,0,1]
	v_and_b32_e32 v11, 0x7fffffff, v5
	v_pk_fma_f32 v[10:11], v[10:11], s[42:43], 1.0 op_sel_hi:[1,0,0]
	v_exp_f32_e32 v9, v9
	v_rcp_f32_e32 v10, v10
	v_rcp_f32_e32 v11, v11
	v_add_u32_e32 v148, 0xb000, v51
	v_pk_mul_f32 v[0:1], v[0:1], v[6:7]
	v_pk_fma_f32 v[12:13], v[10:11], s[52:53], v[14:15] op_sel_hi:[1,0,0]
	v_add_u32_e32 v136, v148, v44
	v_pk_fma_f32 v[12:13], v[10:11], v[12:13], s[56:57] op_sel_hi:[1,1,0]
	v_cvt_pk_bf16_f32 v0, v0, v1
	v_lshlrev_b32_e32 v36, 16, v170
	v_pk_fma_f32 v[12:13], v[10:11], v[12:13], s[62:63] op_sel_hi:[1,1,0]
	v_and_b32_e32 v37, 0xffff0000, v170
	v_pk_fma_f32 v[12:13], v[10:11], v[12:13], s[64:65] op_sel_hi:[1,1,0]
	v_lshlrev_b32_e32 v38, 16, v171
	v_pk_mul_f32 v[10:11], v[10:11], v[12:13]
	v_and_b32_e32 v39, 0xffff0000, v171
	v_pk_fma_f32 v[8:9], v[8:9], v[10:11], 0.5 op_sel_hi:[1,1,0] neg_lo:[1,0,0] neg_hi:[1,0,0]
	s_nop 1
	v_mul_f32_e64 v10, |v4|, v8
	v_mul_f32_e64 v11, |v5|, v9
	v_pk_fma_f32 v[4:5], v[4:5], 0.5, v[10:11] op_sel_hi:[1,0,1]
	v_pk_mul_f32 v[2:3], v[2:3], v[4:5]
	s_nop 1
	v_cvt_pk_bf16_f32 v1, v2, v3
	v_lshl_add_u64 v[2:3], v[136:137], 1, s[26:27]
	v_add_u32_e32 v136, 0xb04, v44
	v_lshlrev_b64 v[12:13], 2, v[136:137]
	v_add_u32_e32 v136, 0x2104, v44
	v_lshl_add_u64 v[66:67], v[136:137], 2, s[66:67]
	v_add_u32_e32 v136, 0x3704, v44
	global_store_dwordx2 v[2:3], v[0:1], off
	v_lshl_add_u64 v[62:63], s[66:67], 0, v[12:13]
	v_lshl_add_u64 v[68:69], v[136:137], 2, s[66:67]
	v_lshl_add_u64 v[70:71], s[36:37], 0, v[12:13]
	global_load_dwordx4 v[8:11], v[62:63], off
	global_load_dwordx4 v[0:3], v[66:67], off
	global_load_dwordx4 v[4:7], v[68:69], off
	global_load_dwordx4 v[12:15], v[70:71], off
	s_nop 1
	v_or_b32_e32 v50, 4, v44
	v_mov_b32_dpp v188, v36 row_ror:1 row_mask:0xf bank_mask:0xf
	v_mov_b32_dpp v194, v37 row_ror:1 row_mask:0xf bank_mask:0xf
	v_mov_b32_dpp v191, v38 row_ror:1 row_mask:0xf bank_mask:0xf
	v_mov_b32_dpp v197, v39 row_ror:1 row_mask:0xf bank_mask:0xf
	v_mov_b32_dpp v192, v36 row_ror:2 row_mask:0xf bank_mask:0xf
	v_mov_b32_dpp v198, v37 row_ror:2 row_mask:0xf bank_mask:0xf
	v_mov_b32_dpp v200, v38 row_ror:2 row_mask:0xf bank_mask:0xf
	v_mov_b32_dpp v202, v39 row_ror:2 row_mask:0xf bank_mask:0xf
	s_and_saveexec_b64 s[0:1], s[12:13]
	s_cbranch_execz .LBB0_561
	v_add_u32_e32 v136, v50, v78
	v_lshl_add_u64 v[16:17], v[136:137], 2, s[28:29]
	global_store_dwordx4 v[16:17], v[36:39], off

; __device__ __forceinline__ f32x4 gelu4(f32x4 v) { const f32x2 a = gelu_pk((f32x2){v[0], v[1]}), b = gelu_pk((f32x2){v[2], v[3]}); return (f32x4){a.x, a.y, b.x, b.y}; }
; __device__ __forceinline__ f32x4 ror1v(f32x4 v) { return (f32x4){dpp_ror1(v[0]), dpp_ror1(v[1]), dpp_ror1(v[2]), dpp_ror1(v[3])}; }
; __device__ __forceinline__ f32x4 ror2v(f32x4 v) { return (f32x4){dpp_ror2(v[0]), dpp_ror2(v[1]), dpp_ror2(v[2]), dpp_ror2(v[3])}; }
; __device__ __forceinline__ u32x2 pack4(f32x4 v) { return (u32x2){pk2(v[0], v[1]), pk2(v[2], v[3])}; }
; __device__ __forceinline__ f32x2 gelu_pk(f32x2 v) {
;     const f32x2 av = __builtin_elementwise_abs(v), d = av * 0.2316418882f + 1.0f;
;     f32x2 t; t.x = __builtin_amdgcn_rcpf(d.x); t.y = __builtin_amdgcn_rcpf(d.y);
;     f32x2 q = t * 0.5307027145f + (-0.7265760135f); q = q * t + 0.7107068705f; q = q * t + (-0.142248368f); q = q * t + 0.127414796f; q = q * t;
;     const f32x2 s = (v * v) * (-0.72134752044f);
;     f32x2 e; e.x = __builtin_amdgcn_exp2f(s.x); e.y = __builtin_amdgcn_exp2f(s.y);
;     const f32x2 m = v * (q * e), r = v - m;
;     f32x2 o; o.x = v.x < 0.f ? m.x : r.x; o.y = v.y < 0.f ? m.y : r.y; return o;
;     __device__ __forceinline__ void operator()(AccRef acc, const Unit& u, int wr, int wc, int fr, int fq) const {
;     ...
;                     const f32x4 wg0 = *(const f32x4*)(cw + jn), wg1 = *(const f32x4*)(cw + (UPN + jn)), wg2 = *(const f32x4*)(cw + (2 * UPN + jn)), bg = *(const f32x4*)(cb + jn);
;                     f32x4 pg1 = (f32x4){0.f, 0.f, 0.f, 0.f}, pg2 = pg1;
; #pragma unroll
;                     for (int m = 0; m < 4; ++m) { const int row = rowg + m * 16 + fr;
;                         const f32x4 ag = unpack4(pa[ai][0][m][n]);
;                         const f32x4 rg1 = ror1v(ag), rg2 = ror2v(ag);
;                         const f32x4 g1 = fr >= 1 ? rg1 : pg1, g2 = fr >= 2 ? rg2 : pg2;
;                         if (m == 0 && fr < 2) *(f32x4*)(edge + (unsigned)((grp * 4 + fr) * UPN + jn)) = ag;
;                         if (m == 3 && fr >= 14) *(f32x4*)(edge + (unsigned)((grp * 4 + (fr - 12)) * UPN + jn)) = ag;
;                         const f32x4 o = gelu4(bg + wg0 * g2 + wg1 * g1 + wg2 * ag) * cu[m];
;                         if (!(m == 0 && fr < 2)) *(u32x2*)(act + (unsigned)(row * DFF + jn)) = pack4(o);
.LBB0_563:
	s_or_b64 exec, exec, s[0:1]
	v_add_u32_e32 v136, 0x1604, v44
	v_lshl_add_u64 v[72:73], v[136:137], 2, s[66:67]
	v_add_u32_e32 v136, 0x2c04, v44
	global_load_dwordx4 v[20:23], v[46:47], off offset:16
	v_lshl_add_u64 v[74:75], v[136:137], 2, s[66:67]
	global_load_dwordx4 v[28:31], v[72:73], off
	global_load_dwordx4 v[24:27], v[74:75], off
	global_load_dwordx4 v[32:35], v[48:49], off offset:16
	v_lshlrev_b32_e32 v40, 16, v169
	v_and_b32_e32 v41, 0xffff0000, v169
	v_lshlrev_b32_e32 v42, 16, v168
	v_and_b32_e32 v43, 0xffff0000, v168
	s_nop 1
	v_mov_b32_dpp v84, v40 row_ror:1 row_mask:0xf bank_mask:0xf
	v_mov_b32_dpp v85, v41 row_ror:1 row_mask:0xf bank_mask:0xf
	v_mov_b32_dpp v86, v42 row_ror:1 row_mask:0xf bank_mask:0xf
	v_mov_b32_dpp v87, v43 row_ror:1 row_mask:0xf bank_mask:0xf
	v_mov_b32_dpp v88, v40 row_ror:2 row_mask:0xf bank_mask:0xf
	v_mov_b32_dpp v89, v41 row_ror:2 row_mask:0xf bank_mask:0xf
	v_mov_b32_dpp v90, v42 row_ror:2 row_mask:0xf bank_mask:0xf
	v_mov_b32_dpp v91, v43 row_ror:2 row_mask:0xf bank_mask:0xf
	s_and_saveexec_b64 s[0:1], s[10:11]
	s_xor_b64 s[76:77], exec, s[0:1]
	s_cbranch_execz .LBB0_565
	v_cndmask_b32_e64 v207, 0, v202, s[6:7]
	v_cndmask_b32_e64 v206, 0, v200, s[6:7]
	v_cndmask_b32_e64 v205, 0, v197, s[8:9]
	v_cndmask_b32_e64 v204, 0, v191, s[8:9]
	s_waitcnt vmcnt(4)
	v_pk_fma_f32 v[206:207], v[10:11], v[206:207], v[14:15]
	v_cndmask_b32_e64 v209, 0, v198, s[6:7]
	v_pk_fma_f32 v[204:205], v[2:3], v[204:205], v[206:207]
	v_cndmask_b32_e64 v208, 0, v192, s[6:7]
	v_pk_fma_f32 v[38:39], v[6:7], v[38:39], v[204:205]
	s_waitcnt vmcnt(0)
	v_pk_fma_f32 v[204:205], v[20:21], v[88:89], v[32:33]
	v_cndmask_b32_e64 v169, 0, v194, s[8:9]
	v_pk_fma_f32 v[204:205], v[28:29], v[84:85], v[204:205]
	v_cndmask_b32_e64 v168, 0, v188, s[8:9]
	v_pk_fma_f32 v[40:41], v[24:25], v[40:41], v[204:205]
	v_pk_fma_f32 v[208:209], v[8:9], v[208:209], v[12:13]
	v_and_b32_e32 v207, 0x7fffffff, v41
	v_and_b32_e32 v206, 0x7fffffff, v40
	v_pk_fma_f32 v[206:207], v[206:207], s[42:43], 1.0 op_sel_hi:[1,0,0]
	v_pk_fma_f32 v[168:169], v[0:1], v[168:169], v[208:209]
	v_rcp_f32_e32 v206, v206
	v_rcp_f32_e32 v207, v207
	v_pk_mul_f32 v[204:205], v[40:41], v[40:41]
	v_mov_b64_e32 v[208:209], s[54:55]
	v_pk_mul_f32 v[204:205], v[204:205], s[38:39] op_sel_hi:[1,0]
	v_pk_fma_f32 v[210:211], v[206:207], s[52:53], v[208:209] op_sel_hi:[1,0,0]
	v_exp_f32_e32 v204, v204
	v_exp_f32_e32 v205, v205
	v_pk_fma_f32 v[210:211], v[206:207], v[210:211], s[56:57] op_sel_hi:[1,1,0]
	v_pk_fma_f32 v[36:37], v[4:5], v[36:37], v[168:169]
	v_pk_fma_f32 v[210:211], v[206:207], v[210:211], s[62:63] op_sel_hi:[1,1,0]
	v_pk_fma_f32 v[168:169], v[22:23], v[90:91], v[34:35]
	v_pk_fma_f32 v[210:211], v[206:207], v[210:211], s[64:65] op_sel_hi:[1,1,0]
	v_pk_fma_f32 v[168:169], v[30:31], v[86:87], v[168:169]
	v_pk_mul_f32 v[206:207], v[206:207], v[210:211]
	s_nop 0
	v_pk_fma_f32 v[204:205], v[204:205], v[206:207], 0.5 op_sel_hi:[1,1,0] neg_lo:[1,0,0] neg_hi:[1,0,0]
	v_pk_fma_f32 v[42:43], v[26:27], v[42:43], v[168:169]
	v_mul_f32_e64 v206, |v40|, v204
	v_mul_f32_e64 v207, |v41|, v205
	v_pk_mul_f32 v[168:169], v[42:43], v[42:43]
	s_nop 0
	v_and_b32_e32 v204, 0x7fffffff, v42
	v_pk_mul_f32 v[168:169], v[168:169], s[38:39] op_sel_hi:[1,0]
	v_pk_fma_f32 v[40:41], v[40:41], 0.5, v[206:207] op_sel_hi:[1,0,1]
	v_and_b32_e32 v205, 0x7fffffff, v43
	v_pk_fma_f32 v[204:205], v[204:205], s[42:43], 1.0 op_sel_hi:[1,0,0]
	v_exp_f32_e32 v168, v168
	v_rcp_f32_e32 v204, v204
	v_rcp_f32_e32 v205, v205
	v_exp_f32_e32 v169, v169
	s_nop 0
	v_pk_mul_f32 v[36:37], v[36:37], v[40:41]
	v_pk_fma_f32 v[206:207], v[204:205], s[52:53], v[208:209] op_sel_hi:[1,0,0]
	v_cvt_pk_bf16_f32 v36, v36, v37
	s_nop 0
	v_pk_fma_f32 v[206:207], v[204:205], v[206:207], s[56:57] op_sel_hi:[1,1,0]
	s_nop 0
	v_pk_fma_f32 v[206:207], v[204:205], v[206:207], s[62:63] op_sel_hi:[1,1,0]
	s_nop 0
	v_pk_fma_f32 v[206:207], v[204:205], v[206:207], s[64:65] op_sel_hi:[1,1,0]
	s_nop 0
	v_pk_mul_f32 v[204:205], v[204:205], v[206:207]
	s_nop 0
	v_pk_fma_f32 v[168:169], v[168:169], v[204:205], 0.5 op_sel_hi:[1,1,0] neg_lo:[1,0,0] neg_hi:[1,0,0]
	s_nop 0
	v_mul_f32_e64 v204, |v42|, v168
	v_mul_f32_e64 v205, |v43|, v169
	v_pk_fma_f32 v[42:43], v[42:43], 0.5, v[204:205] op_sel_hi:[1,0,1]
	v_pk_mul_f32 v[38:39], v[38:39], v[42:43]
	s_nop 0
	v_cvt_pk_bf16_f32 v37, v38, v39
	v_mad_u64_u32 v[38:39], s[0:1], v146, s88, v[50:51]
	v_mov_b32_e32 v39, v137
	v_lshl_add_u64 v[38:39], v[38:39], 1, s[26:27]
	global_store_dwordx2 v[38:39], v[36:37], off

; __device__ __forceinline__ f32x2 gelu_pk(f32x2 v) {
;     const f32x2 av = __builtin_elementwise_abs(v), d = av * 0.2316418882f + 1.0f;
;     f32x2 t; t.x = __builtin_amdgcn_rcpf(d.x); t.y = __builtin_amdgcn_rcpf(d.y);
;     __device__ __forceinline__ void operator()(AccRef acc, const Unit& u, int wr, int wc, int fr, int fq) const {
;     ...
;                     const f32x4 wu0 = *(const f32x4*)(cw + (DFF + jn)), wu1 = *(const f32x4*)(cw + (UPN + DFF + jn)), wu2 = *(const f32x4*)(cw + (2 * UPN + DFF + jn)), bu = *(const f32x4*)(cb + (DFF + jn));
;                     f32x4 pu1 = (f32x4){0.f, 0.f, 0.f, 0.f}, pu2 = pu1;
; #pragma unroll
;                     for (int m = 0; m < 4; ++m) {
;                         const f32x4 au = unpack4(pa[ai][1][m][n]);
;                         const f32x4 ru1 = ror1v(au), ru2 = ror2v(au);
;                         const f32x4 u1 = fr >= 1 ? ru1 : pu1, u2 = fr >= 2 ? ru2 : pu2;
;                         if (m == 0 && fr < 2) *(f32x4*)(edge + (unsigned)((grp * 4 + fr) * UPN + DFF + jn)) = au;
;                         if (m == 3 && fr >= 14) *(f32x4*)(edge + (unsigned)((grp * 4 + (fr - 12)) * UPN + DFF + jn)) = au;
;                         cu[m] = bu + wu0 * u2 + wu1 * u1 + wu2 * au;
;                         pu1 = ru1; pu2 = ru2; }
;                 }
;                 {
;                     const f32x4 wg0 = *(const f32x4*)(cw + jn), wg1 = *(const f32x4*)(cw + (UPN + jn)), wg2 = *(const f32x4*)(cw + (2 * UPN + jn)), bg = *(const f32x4*)(cb + jn);
;                     f32x4 pg1 = (f32x4){0.f, 0.f, 0.f, 0.f}, pg2 = pg1;
; #pragma unroll
;                     for (int m = 0; m < 4; ++m) { const int row = rowg + m * 16 + fr;
;                         const f32x4 ag = unpack4(pa[ai][0][m][n]);
;                         const f32x4 rg1 = ror1v(ag), rg2 = ror2v(ag);
;                         const f32x4 g1 = fr >= 1 ? rg1 : pg1, g2 = fr >= 2 ? rg2 : pg2;
;                         if (m == 0 && fr < 2) *(f32x4*)(edge + (unsigned)((grp * 4 + fr) * UPN + jn)) = ag;
;                         if (m == 3 && fr >= 14) *(f32x4*)(edge + (unsigned)((grp * 4 + (fr - 12)) * UPN + jn)) = ag;
;                         const f32x4 o = gelu4(bg + wg0 * g2 + wg1 * g1 + wg2 * ag) * cu[m];
;                         if (!(m == 0 && fr < 2)) *(u32x2*)(act + (unsigned)(row * DFF + jn)) = pack4(o);
;                         pg1 = rg1; pg2 = rg2; }
.LBB0_567:
	s_or_b64 exec, exec, s[0:1]
	s_nop 0
	v_cndmask_b32_e64 v41, v202, v201, s[6:7]
	v_cndmask_b32_e64 v40, v200, v199, s[6:7]
	v_cndmask_b32_e64 v43, v198, v196, s[6:7]
	v_cndmask_b32_e64 v42, v192, v190, s[6:7]
	v_cndmask_b32_e64 v37, v194, v193, s[8:9]
	v_cndmask_b32_e64 v36, v188, v187, s[8:9]
	v_cndmask_b32_e64 v39, v197, v195, s[8:9]
	v_cndmask_b32_e64 v38, v191, v189, s[8:9]
	s_waitcnt vmcnt(4)
	v_pk_fma_f32 v[42:43], v[8:9], v[42:43], v[12:13]
	v_pk_fma_f32 v[40:41], v[10:11], v[40:41], v[14:15]
	v_pk_fma_f32 v[36:37], v[0:1], v[36:37], v[42:43]
	v_pk_fma_f32 v[38:39], v[2:3], v[38:39], v[40:41]
	v_pk_fma_f32 v[36:37], v[4:5], v[82:83], v[36:37]
	v_pk_fma_f32 v[38:39], v[6:7], v[80:81], v[38:39]
	v_cndmask_b32_e64 v81, v201, v178, s[6:7]
	v_cndmask_b32_e64 v80, v199, v177, s[6:7]
	v_cndmask_b32_e64 v83, v196, v175, s[6:7]
	v_cndmask_b32_e64 v82, v190, v172, s[6:7]
	v_cndmask_b32_e64 v41, v193, v173, s[8:9]
	v_cndmask_b32_e64 v40, v187, v170, s[8:9]
	v_cndmask_b32_e64 v43, v195, v174, s[8:9]
	v_cndmask_b32_e64 v42, v189, v171, s[8:9]
	v_pk_fma_f32 v[82:83], v[8:9], v[82:83], v[12:13]
	v_pk_fma_f32 v[80:81], v[10:11], v[80:81], v[14:15]
	v_pk_fma_f32 v[40:41], v[0:1], v[40:41], v[82:83]
	v_pk_fma_f32 v[42:43], v[2:3], v[42:43], v[80:81]
	v_pk_fma_f32 v[80:81], v[4:5], v[78:79], v[40:41]
	v_pk_fma_f32 v[82:83], v[6:7], v[76:77], v[42:43]
	v_lshlrev_b32_e32 v40, 16, v167
	v_and_b32_e32 v41, 0xffff0000, v167
	v_lshlrev_b32_e32 v42, 16, v149
	v_and_b32_e32 v43, 0xffff0000, v149
	s_nop 1
	v_mov_b32_dpp v146, v40 row_ror:1 row_mask:0xf bank_mask:0xf
	v_mov_b32_dpp v149, v41 row_ror:1 row_mask:0xf bank_mask:0xf
	v_mov_b32_dpp v168, v40 row_ror:2 row_mask:0xf bank_mask:0xf
	v_mov_b32_dpp v169, v41 row_ror:2 row_mask:0xf bank_mask:0xf
	v_cndmask_b32_e64 v79, v85, v149, s[8:9]
	v_cndmask_b32_e64 v78, v84, v146, s[8:9]
	v_cndmask_b32_e64 v85, v89, v169, s[6:7]
	v_cndmask_b32_e64 v84, v88, v168, s[6:7]
	s_waitcnt vmcnt(2)
	v_pk_fma_f32 v[84:85], v[20:21], v[84:85], v[32:33]
	s_nop 1
	v_pk_fma_f32 v[78:79], v[28:29], v[78:79], v[84:85]
	s_nop 1
	v_pk_fma_f32 v[40:41], v[24:25], v[40:41], v[78:79]
	s_nop 1
	v_and_b32_e32 v85, 0x7fffffff, v41
	v_and_b32_e32 v84, 0x7fffffff, v40
	s_nop 1
	v_pk_fma_f32 v[84:85], v[84:85], s[42:43], 1.0 op_sel_hi:[1,0,0]
	v_mov_b32_dpp v152, v42 row_ror:1 row_mask:0xf bank_mask:0xf
	v_mov_b32_dpp v167, v43 row_ror:1 row_mask:0xf bank_mask:0xf
	v_mov_b32_dpp v187, v42 row_ror:2 row_mask:0xf bank_mask:0xf
	v_mov_b32_dpp v188, v43 row_ror:2 row_mask:0xf bank_mask:0xf
	v_rcp_f32_e32 v84, v84
	v_rcp_f32_e32 v85, v85
	v_cndmask_b32_e64 v77, v87, v167, s[8:9]
	v_cndmask_b32_e64 v76, v86, v152, s[8:9]
	v_cndmask_b32_e64 v87, v91, v188, s[6:7]
	v_cndmask_b32_e64 v86, v90, v187, s[6:7]
	v_pk_fma_f32 v[86:87], v[22:23], v[86:87], v[34:35]
	v_pk_mul_f32 v[78:79], v[40:41], v[40:41]
	v_pk_fma_f32 v[76:77], v[30:31], v[76:77], v[86:87]
	v_mov_b64_e32 v[86:87], s[54:55]
	v_pk_mul_f32 v[78:79], v[78:79], s[38:39] op_sel_hi:[1,0]
	v_pk_fma_f32 v[88:89], v[84:85], s[52:53], v[86:87] op_sel_hi:[1,0,0]
	v_exp_f32_e32 v78, v78
	v_exp_f32_e32 v79, v79
	v_pk_fma_f32 v[88:89], v[84:85], v[88:89], s[56:57] op_sel_hi:[1,1,0]
	s_nop 0
	v_pk_fma_f32 v[88:89], v[84:85], v[88:89], s[62:63] op_sel_hi:[1,1,0]
	v_pk_fma_f32 v[42:43], v[26:27], v[42:43], v[76:77]
	v_pk_fma_f32 v[88:89], v[84:85], v[88:89], s[64:65] op_sel_hi:[1,1,0]
	v_pk_mul_f32 v[76:77], v[42:43], v[42:43]
	v_pk_mul_f32 v[84:85], v[84:85], v[88:89]
	v_pk_mul_f32 v[76:77], v[76:77], s[38:39] op_sel_hi:[1,0]
	v_pk_fma_f32 v[78:79], v[78:79], v[84:85], 0.5 op_sel_hi:[1,1,0] neg_lo:[1,0,0] neg_hi:[1,0,0]
	v_exp_f32_e32 v76, v76
	v_mul_f32_e64 v84, |v40|, v78
	v_mul_f32_e64 v85, |v41|, v79
	v_exp_f32_e32 v77, v77
	v_and_b32_e32 v78, 0x7fffffff, v42
	v_add_u32_e32 v136, v45, v50
	v_pk_fma_f32 v[40:41], v[40:41], 0.5, v[84:85] op_sel_hi:[1,0,1]
	v_and_b32_e32 v79, 0x7fffffff, v43
	v_pk_fma_f32 v[78:79], v[78:79], s[42:43], 1.0 op_sel_hi:[1,0,0]
	s_nop 0
	v_rcp_f32_e32 v78, v78
	v_rcp_f32_e32 v79, v79
	v_pk_mul_f32 v[36:37], v[36:37], v[40:41]
	s_nop 1
	v_cvt_pk_bf16_f32 v36, v36, v37
	v_pk_fma_f32 v[84:85], v[78:79], s[52:53], v[86:87] op_sel_hi:[1,0,0]
	s_nop 1
	v_pk_fma_f32 v[84:85], v[78:79], v[84:85], s[56:57] op_sel_hi:[1,1,0]
	s_nop 1
	v_pk_fma_f32 v[84:85], v[78:79], v[84:85], s[62:63] op_sel_hi:[1,1,0]
	s_nop 0
	v_pk_fma_f32 v[84:85], v[78:79], v[84:85], s[64:65] op_sel_hi:[1,1,0]
	s_nop 0
	v_pk_mul_f32 v[78:79], v[78:79], v[84:85]
	s_nop 0
	v_pk_fma_f32 v[76:77], v[76:77], v[78:79], 0.5 op_sel_hi:[1,1,0] neg_lo:[1,0,0] neg_hi:[1,0,0]
	s_nop 0
	v_mul_f32_e64 v78, |v42|, v76
	v_mul_f32_e64 v79, |v43|, v77
	v_pk_fma_f32 v[42:43], v[42:43], 0.5, v[78:79] op_sel_hi:[1,0,1]
	v_pk_mul_f32 v[38:39], v[38:39], v[42:43]
	s_nop 1
	v_cvt_pk_bf16_f32 v37, v38, v39
	v_lshl_add_u64 v[38:39], v[136:137], 1, s[26:27]
	global_store_dwordx2 v[38:39], v[36:37], off
	v_lshlrev_b32_e32 v36, 16, v127
	v_and_b32_e32 v37, 0xffff0000, v127
	s_nop 1
	v_mov_b32_dpp v43, v36 row_ror:2 row_mask:0xf bank_mask:0xf
	v_mov_b32_dpp v40, v36 row_ror:1 row_mask:0xf bank_mask:0xf
	v_mov_b32_dpp v77, v37 row_ror:2 row_mask:0xf bank_mask:0xf
	v_mov_b32_dpp v41, v37 row_ror:1 row_mask:0xf bank_mask:0xf
	v_cndmask_b32_e64 v91, v169, v77, s[6:7]
	v_cndmask_b32_e64 v90, v168, v43, s[6:7]
	v_cndmask_b32_e64 v89, v149, v41, s[8:9]
	v_cndmask_b32_e64 v88, v146, v40, s[8:9]
	v_pk_fma_f32 v[90:91], v[20:21], v[90:91], v[32:33]
	v_lshlrev_b32_e32 v38, 16, v147
	v_pk_fma_f32 v[88:89], v[28:29], v[88:89], v[90:91]
	v_and_b32_e32 v39, 0xffff0000, v147
	v_pk_fma_f32 v[36:37], v[24:25], v[36:37], v[88:89]
	s_nop 1
; __device__ __forceinline__ f32x4 gelu4(f32x4 v) { const f32x2 a = gelu_pk((f32x2){v[0], v[1]}), b = gelu_pk((f32x2){v[2], v[3]}); return (f32x4){a.x, a.y, b.x, b.y}; }
; __device__ __forceinline__ f32x4 ror1v(f32x4 v) { return (f32x4){dpp_ror1(v[0]), dpp_ror1(v[1]), dpp_ror1(v[2]), dpp_ror1(v[3])}; }
; __device__ __forceinline__ f32x4 ror2v(f32x4 v) { return (f32x4){dpp_ror2(v[0]), dpp_ror2(v[1]), dpp_ror2(v[2]), dpp_ror2(v[3])}; }
; __device__ __forceinline__ u32x2 pack4(f32x4 v) { return (u32x2){pk2(v[0], v[1]), pk2(v[2], v[3])}; }
; __device__ __forceinline__ f32x2 gelu_pk(f32x2 v) {
;     const f32x2 av = __builtin_elementwise_abs(v), d = av * 0.2316418882f + 1.0f;
;     f32x2 t; t.x = __builtin_amdgcn_rcpf(d.x); t.y = __builtin_amdgcn_rcpf(d.y);
;     f32x2 q = t * 0.5307027145f + (-0.7265760135f); q = q * t + 0.7107068705f; q = q * t + (-0.142248368f); q = q * t + 0.127414796f; q = q * t;
;     const f32x2 s = (v * v) * (-0.72134752044f);
;     f32x2 e; e.x = __builtin_amdgcn_exp2f(s.x); e.y = __builtin_amdgcn_exp2f(s.y);
;     const f32x2 m = v * (q * e), r = v - m;
;     f32x2 o; o.x = v.x < 0.f ? m.x : r.x; o.y = v.y < 0.f ? m.y : r.y; return o;
;     __device__ __forceinline__ void operator()(AccRef acc, const Unit& u, int wr, int wc, int fr, int fq) const {
;     ...
;                     const f32x4 wg0 = *(const f32x4*)(cw + jn), wg1 = *(const f32x4*)(cw + (UPN + jn)), wg2 = *(const f32x4*)(cw + (2 * UPN + jn)), bg = *(const f32x4*)(cb + jn);
;                     f32x4 pg1 = (f32x4){0.f, 0.f, 0.f, 0.f}, pg2 = pg1;
; #pragma unroll
;                     for (int m = 0; m < 4; ++m) { const int row = rowg + m * 16 + fr;
;                         const f32x4 ag = unpack4(pa[ai][0][m][n]);
;                         const f32x4 rg1 = ror1v(ag), rg2 = ror2v(ag);
;                         const f32x4 g1 = fr >= 1 ? rg1 : pg1, g2 = fr >= 2 ? rg2 : pg2;
;                         if (m == 0 && fr < 2) *(f32x4*)(edge + (unsigned)((grp * 4 + fr) * UPN + jn)) = ag;
;                         if (m == 3 && fr >= 14) *(f32x4*)(edge + (unsigned)((grp * 4 + (fr - 12)) * UPN + jn)) = ag;
;                         const f32x4 o = gelu4(bg + wg0 * g2 + wg1 * g1 + wg2 * ag) * cu[m];
;                         if (!(m == 0 && fr < 2)) *(u32x2*)(act + (unsigned)(row * DFF + jn)) = pack4(o);
;                         pg1 = rg1; pg2 = rg2; }
	v_and_b32_e32 v91, 0x7fffffff, v37
	v_and_b32_e32 v90, 0x7fffffff, v36
	v_pk_fma_f32 v[90:91], v[90:91], s[42:43], 1.0 op_sel_hi:[1,0,0]
	v_mov_b32_dpp v45, v38 row_ror:2 row_mask:0xf bank_mask:0xf
	v_rcp_f32_e32 v90, v90
	v_rcp_f32_e32 v91, v91
	v_mov_b32_dpp v78, v39 row_ror:2 row_mask:0xf bank_mask:0xf
	v_mov_b32_dpp v42, v38 row_ror:1 row_mask:0xf bank_mask:0xf
	v_mov_b32_dpp v76, v39 row_ror:1 row_mask:0xf bank_mask:0xf
	v_cndmask_b32_e64 v147, v188, v78, s[6:7]
	v_cndmask_b32_e64 v146, v187, v45, s[6:7]
	v_cndmask_b32_e64 v85, v167, v76, s[8:9]
	v_cndmask_b32_e64 v84, v152, v42, s[8:9]
	v_pk_fma_f32 v[146:147], v[22:23], v[146:147], v[34:35]
	v_pk_mul_f32 v[88:89], v[36:37], v[36:37]
	v_pk_fma_f32 v[84:85], v[30:31], v[84:85], v[146:147]
	v_pk_mul_f32 v[88:89], v[88:89], s[38:39] op_sel_hi:[1,0]
	v_pk_fma_f32 v[146:147], v[90:91], s[52:53], v[86:87] op_sel_hi:[1,0,0]
	v_exp_f32_e32 v88, v88
	v_exp_f32_e32 v89, v89
	v_pk_fma_f32 v[146:147], v[90:91], v[146:147], s[56:57] op_sel_hi:[1,1,0]
	s_nop 0
	v_pk_fma_f32 v[146:147], v[90:91], v[146:147], s[62:63] op_sel_hi:[1,1,0]
	v_pk_fma_f32 v[38:39], v[26:27], v[38:39], v[84:85]
	v_pk_fma_f32 v[146:147], v[90:91], v[146:147], s[64:65] op_sel_hi:[1,1,0]
	v_pk_mul_f32 v[84:85], v[38:39], v[38:39]
	v_pk_mul_f32 v[90:91], v[90:91], v[146:147]
	v_pk_mul_f32 v[84:85], v[84:85], s[38:39] op_sel_hi:[1,0]
	v_pk_fma_f32 v[88:89], v[88:89], v[90:91], 0.5 op_sel_hi:[1,1,0] neg_lo:[1,0,0] neg_hi:[1,0,0]
	v_exp_f32_e32 v84, v84
	v_mul_f32_e64 v90, |v36|, v88
	v_mul_f32_e64 v91, |v37|, v89
	v_exp_f32_e32 v85, v85
	v_and_b32_e32 v88, 0x7fffffff, v38
	v_add_u32_e32 v136, v51, v50
	v_pk_fma_f32 v[36:37], v[36:37], 0.5, v[90:91] op_sel_hi:[1,0,1]
	v_and_b32_e32 v89, 0x7fffffff, v39
	v_pk_fma_f32 v[88:89], v[88:89], s[42:43], 1.0 op_sel_hi:[1,0,0]
	s_nop 0
	v_rcp_f32_e32 v88, v88
	v_rcp_f32_e32 v89, v89
	v_pk_mul_f32 v[36:37], v[80:81], v[36:37]
	s_nop 1
	v_cvt_pk_bf16_f32 v36, v36, v37
	v_pk_fma_f32 v[86:87], v[88:89], s[52:53], v[86:87] op_sel_hi:[1,0,0]
	s_nop 1
	v_pk_fma_f32 v[86:87], v[88:89], v[86:87], s[56:57] op_sel_hi:[1,1,0]
	s_nop 1
	v_pk_fma_f32 v[86:87], v[88:89], v[86:87], s[62:63] op_sel_hi:[1,1,0]
	s_nop 1
	v_pk_fma_f32 v[86:87], v[88:89], v[86:87], s[64:65] op_sel_hi:[1,1,0]
	s_nop 0
	v_pk_mul_f32 v[86:87], v[88:89], v[86:87]
	s_nop 0
	v_pk_fma_f32 v[84:85], v[84:85], v[86:87], 0.5 op_sel_hi:[1,1,0] neg_lo:[1,0,0] neg_hi:[1,0,0]
	s_nop 0
	v_mul_f32_e64 v86, |v38|, v84
	v_mul_f32_e64 v87, |v39|, v85
	v_pk_fma_f32 v[38:39], v[38:39], 0.5, v[86:87] op_sel_hi:[1,0,1]
	v_pk_mul_f32 v[38:39], v[82:83], v[38:39]
	s_nop 1
	v_cvt_pk_bf16_f32 v37, v38, v39
	v_lshl_add_u64 v[38:39], v[136:137], 1, s[26:27]
	global_store_dwordx2 v[38:39], v[36:37], off
	v_lshlrev_b32_e32 v36, 16, v124
	v_and_b32_e32 v37, 0xffff0000, v124
	v_lshlrev_b32_e32 v38, 16, v125
	v_and_b32_e32 v39, 0xffff0000, v125
	s_nop 1
	v_mov_b32_dpp v51, v36 row_ror:1 row_mask:0xf bank_mask:0xf
	v_mov_b32_dpp v79, v37 row_ror:1 row_mask:0xf bank_mask:0xf
	v_mov_b32_dpp v80, v38 row_ror:1 row_mask:0xf bank_mask:0xf
	v_mov_b32_dpp v83, v39 row_ror:1 row_mask:0xf bank_mask:0xf
	v_mov_b32_dpp v81, v36 row_ror:2 row_mask:0xf bank_mask:0xf
	v_mov_b32_dpp v84, v37 row_ror:2 row_mask:0xf bank_mask:0xf
	v_mov_b32_dpp v82, v38 row_ror:2 row_mask:0xf bank_mask:0xf
	v_mov_b32_dpp v85, v39 row_ror:2 row_mask:0xf bank_mask:0xf
	s_and_saveexec_b64 s[0:1], vcc
	s_cbranch_execz .LBB0_569
	v_add_u32_e32 v136, v50, v150
	v_lshl_add_u64 v[86:87], v[136:137], 2, s[28:29]
	global_store_dwordx4 v[86:87], v[36:39], off
; __device__ __forceinline__ f32x4 gelu4(f32x4 v) { const f32x2 a = gelu_pk((f32x2){v[0], v[1]}), b = gelu_pk((f32x2){v[2], v[3]}); return (f32x4){a.x, a.y, b.x, b.y}; }
; __device__ __forceinline__ f32x2 gelu_pk(f32x2 v) {
;     const f32x2 av = __builtin_elementwise_abs(v), d = av * 0.2316418882f + 1.0f;
;     f32x2 t; t.x = __builtin_amdgcn_rcpf(d.x); t.y = __builtin_amdgcn_rcpf(d.y);
;     f32x2 q = t * 0.5307027145f + (-0.7265760135f); q = q * t + 0.7107068705f; q = q * t + (-0.142248368f); q = q * t + 0.127414796f; q = q * t;
;     const f32x2 s = (v * v) * (-0.72134752044f);
;     f32x2 e; e.x = __builtin_amdgcn_exp2f(s.x); e.y = __builtin_amdgcn_exp2f(s.y);
;     const f32x2 m = v * (q * e), r = v - m;
;     f32x2 o; o.x = v.x < 0.f ? m.x : r.x; o.y = v.y < 0.f ? m.y : r.y; return o;
;     __device__ __forceinline__ void operator()(AccRef acc, const Unit& u, int wr, int wc, int fr, int fq) const {
;     ...
;             for (int n = 0; n < 2; ++n) { const unsigned jn = (unsigned)(j0 + 4 * n);
;                 f32x4 cu[4];
;                 {
;                     const f32x4 wu0 = *(const f32x4*)(cw + (DFF + jn)), wu1 = *(const f32x4*)(cw + (UPN + DFF + jn)), wu2 = *(const f32x4*)(cw + (2 * UPN + DFF + jn)), bu = *(const f32x4*)(cb + (DFF + jn));
;     ...
;                     const f32x4 wg0 = *(const f32x4*)(cw + jn), wg1 = *(const f32x4*)(cw + (UPN + jn)), wg2 = *(const f32x4*)(cw + (2 * UPN + jn)), bg = *(const f32x4*)(cb + jn);
;                     f32x4 pg1 = (f32x4){0.f, 0.f, 0.f, 0.f}, pg2 = pg1;
; #pragma unroll
;                     for (int m = 0; m < 4; ++m) { const int row = rowg + m * 16 + fr;
;                         const f32x4 ag = unpack4(pa[ai][0][m][n]);
;                         const f32x4 rg1 = ror1v(ag), rg2 = ror2v(ag);
;                         const f32x4 g1 = fr >= 1 ? rg1 : pg1, g2 = fr >= 2 ? rg2 : pg2;
;                         if (m == 0 && fr < 2) *(f32x4*)(edge + (unsigned)((grp * 4 + fr) * UPN + jn)) = ag;
;                         if (m == 3 && fr >= 14) *(f32x4*)(edge + (unsigned)((grp * 4 + (fr - 12)) * UPN + jn)) = ag;
;                         const f32x4 o = gelu4(bg + wg0 * g2 + wg1 * g1 + wg2 * ag) * cu[m];
;                         if (!(m == 0 && fr < 2)) *(u32x2*)(act + (unsigned)(row * DFF + jn)) = pack4(o);
;                         pg1 = rg1; pg2 = rg2; }
.LBB0_569:
	s_or_b64 exec, exec, s[0:1]
	v_cndmask_b32_e64 v87, v76, v83, s[8:9]
	v_cndmask_b32_e64 v86, v42, v80, s[8:9]
	v_cndmask_b32_e64 v42, v45, v82, s[6:7]
	v_cndmask_b32_e64 v83, v178, v186, s[6:7]
	v_cndmask_b32_e64 v82, v177, v185, s[6:7]
	v_cndmask_b32_e64 v76, v43, v81, s[6:7]
	v_cndmask_b32_e64 v81, v174, v183, s[8:9]
	v_cndmask_b32_e64 v80, v171, v180, s[8:9]
	v_pk_fma_f32 v[10:11], v[10:11], v[82:83], v[14:15]
	v_cndmask_b32_e64 v77, v77, v84, s[6:7]
	v_pk_fma_f32 v[2:3], v[2:3], v[80:81], v[10:11]
	v_cndmask_b32_e64 v41, v41, v79, s[8:9]
	v_cndmask_b32_e64 v40, v40, v51, s[8:9]
	v_pk_fma_f32 v[2:3], v[6:7], v[18:19], v[2:3]
	v_pk_fma_f32 v[6:7], v[20:21], v[76:77], v[32:33]
	v_cndmask_b32_e64 v43, v78, v85, s[6:7]
	v_pk_fma_f32 v[6:7], v[28:29], v[40:41], v[6:7]
	v_cndmask_b32_e64 v85, v175, v184, s[6:7]
	v_cndmask_b32_e64 v84, v172, v181, s[6:7]
	v_pk_fma_f32 v[6:7], v[24:25], v[36:37], v[6:7]
	v_pk_fma_f32 v[8:9], v[8:9], v[84:85], v[12:13]
	v_and_b32_e32 v13, 0x7fffffff, v7
	v_and_b32_e32 v12, 0x7fffffff, v6
	v_pk_fma_f32 v[12:13], v[12:13], s[42:43], 1.0 op_sel_hi:[1,0,0]
	v_cndmask_b32_e64 v79, v173, v182, s[8:9]
	v_rcp_f32_e32 v12, v12
	v_rcp_f32_e32 v13, v13
	v_cndmask_b32_e64 v78, v170, v179, s[8:9]
	v_pk_fma_f32 v[0:1], v[0:1], v[78:79], v[8:9]
	v_pk_mul_f32 v[10:11], v[6:7], v[6:7]
	v_mov_b64_e32 v[14:15], s[54:55]
	v_pk_fma_f32 v[0:1], v[4:5], v[16:17], v[0:1]
	v_pk_mul_f32 v[10:11], v[10:11], s[38:39] op_sel_hi:[1,0]
	v_pk_fma_f32 v[16:17], v[12:13], s[52:53], v[14:15] op_sel_hi:[1,0,0]
	v_exp_f32_e32 v10, v10
	v_exp_f32_e32 v11, v11
	v_pk_fma_f32 v[16:17], v[12:13], v[16:17], s[56:57] op_sel_hi:[1,1,0]
	v_pk_fma_f32 v[4:5], v[22:23], v[42:43], v[34:35]
	v_pk_fma_f32 v[16:17], v[12:13], v[16:17], s[62:63] op_sel_hi:[1,1,0]
	v_pk_fma_f32 v[4:5], v[30:31], v[86:87], v[4:5]
	v_pk_fma_f32 v[16:17], v[12:13], v[16:17], s[64:65] op_sel_hi:[1,1,0]
	s_nop 0
	v_pk_mul_f32 v[12:13], v[12:13], v[16:17]
	v_pk_fma_f32 v[4:5], v[26:27], v[38:39], v[4:5]
	v_pk_fma_f32 v[10:11], v[10:11], v[12:13], 0.5 op_sel_hi:[1,1,0] neg_lo:[1,0,0] neg_hi:[1,0,0]
	v_pk_mul_f32 v[8:9], v[4:5], v[4:5]
	v_mul_f32_e64 v12, |v6|, v10
	v_mul_f32_e64 v13, |v7|, v11
	v_pk_mul_f32 v[8:9], v[8:9], s[38:39] op_sel_hi:[1,0]
	s_nop 0
	v_and_b32_e32 v10, 0x7fffffff, v4
	v_exp_f32_e32 v8, v8
	v_pk_fma_f32 v[6:7], v[6:7], 0.5, v[12:13] op_sel_hi:[1,0,1]
	v_and_b32_e32 v11, 0x7fffffff, v5
	v_pk_fma_f32 v[10:11], v[10:11], s[42:43], 1.0 op_sel_hi:[1,0,0]
	v_exp_f32_e32 v9, v9
	v_rcp_f32_e32 v10, v10
	v_rcp_f32_e32 v11, v11
	v_pk_mul_f32 v[0:1], v[0:1], v[6:7]
	v_add_u32_e32 v136, v148, v50
	v_pk_fma_f32 v[12:13], v[10:11], s[52:53], v[14:15] op_sel_hi:[1,0,0]
	v_cvt_pk_bf16_f32 v0, v0, v1
	s_addk_i32 s69, 0x80
	v_pk_fma_f32 v[12:13], v[10:11], v[12:13], s[56:57] op_sel_hi:[1,1,0]
	s_ashr_i32 s71, s69, 4
	v_pk_fma_f32 v[12:13], v[10:11], v[12:13], s[62:63] op_sel_hi:[1,1,0]
	v_add_u32_e32 v16, s71, v166
	v_pk_fma_f32 v[12:13], v[10:11], v[12:13], s[64:65] op_sel_hi:[1,1,0]
	v_mul_lo_u32 v80, v16, s87
	v_pk_mul_f32 v[10:11], v[10:11], v[12:13]
	v_lshlrev_b32_e32 v36, 16, v116
	v_pk_fma_f32 v[8:9], v[8:9], v[10:11], 0.5 op_sel_hi:[1,1,0] neg_lo:[1,0,0] neg_hi:[1,0,0]
	v_and_b32_e32 v37, 0xffff0000, v116
	v_mul_f32_e64 v10, |v4|, v8
	v_mul_f32_e64 v11, |v5|, v9
	v_lshlrev_b32_e32 v38, 16, v117
	v_and_b32_e32 v39, 0xffff0000, v117
	s_nop 1
	v_pk_fma_f32 v[4:5], v[4:5], 0.5, v[10:11] op_sel_hi:[1,0,1]
	v_pk_mul_f32 v[2:3], v[2:3], v[4:5]
	s_nop 1
	v_cvt_pk_bf16_f32 v1, v2, v3
	v_lshl_add_u64 v[2:3], v[136:137], 1, s[26:27]
	global_store_dwordx2 v[2:3], v[0:1], off
	global_load_dwordx4 v[8:11], v[52:53], off
	global_load_dwordx4 v[4:7], v[54:55], off
	s_nop 0
	global_load_dwordx4 v[0:3], v[56:57], off
	global_load_dwordx4 v[12:15], v[58:59], off
	s_nop 1
	v_add_u32_e32 v45, 0xb00, v80
	v_mov_b32_dpp v124, v36 row_ror:1 row_mask:0xf bank_mask:0xf
	v_mov_b32_dpp v146, v37 row_ror:1 row_mask:0xf bank_mask:0xf
	v_mov_b32_dpp v125, v38 row_ror:1 row_mask:0xf bank_mask:0xf
	v_mov_b32_dpp v149, v39 row_ror:1 row_mask:0xf bank_mask:0xf
	v_mov_b32_dpp v127, v36 row_ror:2 row_mask:0xf bank_mask:0xf
	v_mov_b32_dpp v150, v37 row_ror:2 row_mask:0xf bank_mask:0xf
	v_mov_b32_dpp v169, v38 row_ror:2 row_mask:0xf bank_mask:0xf
	v_mov_b32_dpp v171, v39 row_ror:2 row_mask:0xf bank_mask:0xf
	s_and_saveexec_b64 s[0:1], s[12:13]
	s_cbranch_execz .LBB0_571
	v_add_u32_e32 v136, v45, v44
	v_lshl_add_u64 v[16:17], v[136:137], 2, s[28:29]
	global_store_dwordx4 v[16:17], v[36:39], off

; __device__ __forceinline__ f32x4 gelu4(f32x4 v) { const f32x2 a = gelu_pk((f32x2){v[0], v[1]}), b = gelu_pk((f32x2){v[2], v[3]}); return (f32x4){a.x, a.y, b.x, b.y}; }
; __device__ __forceinline__ f32x4 ror1v(f32x4 v) { return (f32x4){dpp_ror1(v[0]), dpp_ror1(v[1]), dpp_ror1(v[2]), dpp_ror1(v[3])}; }
; __device__ __forceinline__ f32x4 ror2v(f32x4 v) { return (f32x4){dpp_ror2(v[0]), dpp_ror2(v[1]), dpp_ror2(v[2]), dpp_ror2(v[3])}; }
; __device__ __forceinline__ u32x2 pack4(f32x4 v) { return (u32x2){pk2(v[0], v[1]), pk2(v[2], v[3])}; }
; __device__ __forceinline__ f32x2 gelu_pk(f32x2 v) {
;     const f32x2 av = __builtin_elementwise_abs(v), d = av * 0.2316418882f + 1.0f;
;     f32x2 t; t.x = __builtin_amdgcn_rcpf(d.x); t.y = __builtin_amdgcn_rcpf(d.y);
;     f32x2 q = t * 0.5307027145f + (-0.7265760135f); q = q * t + 0.7107068705f; q = q * t + (-0.142248368f); q = q * t + 0.127414796f; q = q * t;
;     const f32x2 s = (v * v) * (-0.72134752044f);
;     f32x2 e; e.x = __builtin_amdgcn_exp2f(s.x); e.y = __builtin_amdgcn_exp2f(s.y);
;     const f32x2 m = v * (q * e), r = v - m;
;     f32x2 o; o.x = v.x < 0.f ? m.x : r.x; o.y = v.y < 0.f ? m.y : r.y; return o;
;     __device__ __forceinline__ void operator()(AccRef acc, const Unit& u, int wr, int wc, int fr, int fq) const {
;     ...
;                     const f32x4 wg0 = *(const f32x4*)(cw + jn), wg1 = *(const f32x4*)(cw + (UPN + jn)), wg2 = *(const f32x4*)(cw + (2 * UPN + jn)), bg = *(const f32x4*)(cb + jn);
;                     f32x4 pg1 = (f32x4){0.f, 0.f, 0.f, 0.f}, pg2 = pg1;
; #pragma unroll
;                     for (int m = 0; m < 4; ++m) { const int row = rowg + m * 16 + fr;
;                         const f32x4 ag = unpack4(pa[ai][0][m][n]);
;                         const f32x4 rg1 = ror1v(ag), rg2 = ror2v(ag);
;                         const f32x4 g1 = fr >= 1 ? rg1 : pg1, g2 = fr >= 2 ? rg2 : pg2;
;                         if (m == 0 && fr < 2) *(f32x4*)(edge + (unsigned)((grp * 4 + fr) * UPN + jn)) = ag;
;                         if (m == 3 && fr >= 14) *(f32x4*)(edge + (unsigned)((grp * 4 + (fr - 12)) * UPN + jn)) = ag;
;                         const f32x4 o = gelu4(bg + wg0 * g2 + wg1 * g1 + wg2 * ag) * cu[m];
;                         if (!(m == 0 && fr < 2)) *(u32x2*)(act + (unsigned)(row * DFF + jn)) = pack4(o);
;                         pg1 = rg1; pg2 = rg2; }
.LBB0_573:
	s_or_b64 exec, exec, s[0:1]
	global_load_dwordx4 v[28:31], v[46:47], off
	global_load_dwordx4 v[24:27], v[60:61], off
	global_load_dwordx4 v[20:23], v[64:65], off
	global_load_dwordx4 v[32:35], v[48:49], off
	v_add_u32_e32 v123, s69, v166
	v_lshlrev_b32_e32 v40, 16, v114
	v_and_b32_e32 v41, 0xffff0000, v114
	v_lshlrev_b32_e32 v42, 16, v115
	v_and_b32_e32 v43, 0xffff0000, v115
	s_nop 1
	v_mov_b32_dpp v60, v40 row_ror:1 row_mask:0xf bank_mask:0xf
	v_mov_b32_dpp v61, v41 row_ror:1 row_mask:0xf bank_mask:0xf
	v_mov_b32_dpp v64, v42 row_ror:1 row_mask:0xf bank_mask:0xf
	v_mov_b32_dpp v65, v43 row_ror:1 row_mask:0xf bank_mask:0xf
	v_mov_b32_dpp v76, v40 row_ror:2 row_mask:0xf bank_mask:0xf
	v_mov_b32_dpp v77, v41 row_ror:2 row_mask:0xf bank_mask:0xf
	v_mov_b32_dpp v78, v42 row_ror:2 row_mask:0xf bank_mask:0xf
	v_mov_b32_dpp v79, v43 row_ror:2 row_mask:0xf bank_mask:0xf
	v_mul_lo_u32 v82, v123, s88
	s_and_saveexec_b64 s[0:1], s[10:11]
	s_xor_b64 s[76:77], exec, s[0:1]
	s_cbranch_execz .LBB0_575
	v_cndmask_b32_e64 v179, 0, v171, s[6:7]
	v_cndmask_b32_e64 v178, 0, v169, s[6:7]
	v_cndmask_b32_e64 v175, 0, v149, s[8:9]
	v_cndmask_b32_e64 v174, 0, v125, s[8:9]
	s_waitcnt vmcnt(4)
	v_pk_fma_f32 v[178:179], v[10:11], v[178:179], v[14:15]
	v_cndmask_b32_e64 v181, 0, v150, s[6:7]
	v_pk_fma_f32 v[174:175], v[6:7], v[174:175], v[178:179]
	v_cndmask_b32_e64 v180, 0, v127, s[6:7]
	v_pk_fma_f32 v[38:39], v[2:3], v[38:39], v[174:175]
	s_waitcnt vmcnt(0)
	v_pk_fma_f32 v[174:175], v[28:29], v[76:77], v[32:33]
	v_cndmask_b32_e64 v115, 0, v146, s[8:9]
	v_pk_fma_f32 v[174:175], v[24:25], v[60:61], v[174:175]
	v_cndmask_b32_e64 v114, 0, v124, s[8:9]
	v_pk_fma_f32 v[40:41], v[20:21], v[40:41], v[174:175]
	v_pk_fma_f32 v[180:181], v[8:9], v[180:181], v[12:13]
	v_and_b32_e32 v179, 0x7fffffff, v41
	v_and_b32_e32 v178, 0x7fffffff, v40
	v_pk_fma_f32 v[178:179], v[178:179], s[42:43], 1.0 op_sel_hi:[1,0,0]
	v_pk_fma_f32 v[114:115], v[4:5], v[114:115], v[180:181]
	v_rcp_f32_e32 v178, v178
	v_rcp_f32_e32 v179, v179
	v_pk_mul_f32 v[174:175], v[40:41], v[40:41]
	v_mov_b64_e32 v[180:181], s[54:55]
	v_pk_mul_f32 v[174:175], v[174:175], s[38:39] op_sel_hi:[1,0]
	v_pk_fma_f32 v[182:183], v[178:179], s[52:53], v[180:181] op_sel_hi:[1,0,0]
	v_exp_f32_e32 v174, v174
	v_exp_f32_e32 v175, v175
	v_pk_fma_f32 v[182:183], v[178:179], v[182:183], s[56:57] op_sel_hi:[1,1,0]
	v_pk_fma_f32 v[36:37], v[0:1], v[36:37], v[114:115]
	v_pk_fma_f32 v[182:183], v[178:179], v[182:183], s[62:63] op_sel_hi:[1,1,0]
	v_pk_fma_f32 v[114:115], v[30:31], v[78:79], v[34:35]
	v_pk_fma_f32 v[182:183], v[178:179], v[182:183], s[64:65] op_sel_hi:[1,1,0]
	v_pk_fma_f32 v[114:115], v[26:27], v[64:65], v[114:115]
	v_pk_mul_f32 v[178:179], v[178:179], v[182:183]
	s_nop 0
	v_pk_fma_f32 v[174:175], v[174:175], v[178:179], 0.5 op_sel_hi:[1,1,0] neg_lo:[1,0,0] neg_hi:[1,0,0]
	v_pk_fma_f32 v[42:43], v[22:23], v[42:43], v[114:115]
	v_mul_f32_e64 v178, |v40|, v174
	v_mul_f32_e64 v179, |v41|, v175
	v_pk_mul_f32 v[114:115], v[42:43], v[42:43]
	s_nop 0
	v_and_b32_e32 v174, 0x7fffffff, v42
	v_pk_mul_f32 v[114:115], v[114:115], s[38:39] op_sel_hi:[1,0]
	v_pk_fma_f32 v[40:41], v[40:41], 0.5, v[178:179] op_sel_hi:[1,0,1]
	v_and_b32_e32 v175, 0x7fffffff, v43
	v_pk_fma_f32 v[174:175], v[174:175], s[42:43], 1.0 op_sel_hi:[1,0,0]
	v_exp_f32_e32 v114, v114
	v_rcp_f32_e32 v174, v174
	v_rcp_f32_e32 v175, v175
	v_exp_f32_e32 v115, v115
	s_nop 0
	v_mul_lo_u32 v82, v123, s88
	v_pk_fma_f32 v[178:179], v[174:175], s[52:53], v[180:181] op_sel_hi:[1,0,0]
	v_pk_mul_f32 v[36:37], v[36:37], v[40:41]
	v_pk_fma_f32 v[178:179], v[174:175], v[178:179], s[56:57] op_sel_hi:[1,1,0]
	v_add_u32_e32 v136, v82, v44
	v_pk_fma_f32 v[178:179], v[174:175], v[178:179], s[62:63] op_sel_hi:[1,1,0]
	v_cvt_pk_bf16_f32 v36, v36, v37
	s_nop 0
	v_pk_fma_f32 v[178:179], v[174:175], v[178:179], s[64:65] op_sel_hi:[1,1,0]
	s_nop 0
	v_pk_mul_f32 v[174:175], v[174:175], v[178:179]
	s_nop 0
	v_pk_fma_f32 v[114:115], v[114:115], v[174:175], 0.5 op_sel_hi:[1,1,0] neg_lo:[1,0,0] neg_hi:[1,0,0]
	s_nop 0
	v_mul_f32_e64 v174, |v42|, v114
	v_mul_f32_e64 v175, |v43|, v115
	v_pk_fma_f32 v[42:43], v[42:43], 0.5, v[174:175] op_sel_hi:[1,0,1]
	v_pk_mul_f32 v[38:39], v[38:39], v[42:43]
	s_nop 0
	v_cvt_pk_bf16_f32 v37, v38, v39
	v_lshl_add_u64 v[38:39], v[136:137], 1, s[26:27]
	global_store_dwordx2 v[38:39], v[36:37], off

; __device__ __forceinline__ f32x2 gelu_pk(f32x2 v) {
;     const f32x2 av = __builtin_elementwise_abs(v), d = av * 0.2316418882f + 1.0f;
;     f32x2 t; t.x = __builtin_amdgcn_rcpf(d.x); t.y = __builtin_amdgcn_rcpf(d.y);
;     __device__ __forceinline__ void operator()(AccRef acc, const Unit& u, int wr, int wc, int fr, int fq) const {
;     ...
;                     const f32x4 wu0 = *(const f32x4*)(cw + (DFF + jn)), wu1 = *(const f32x4*)(cw + (UPN + DFF + jn)), wu2 = *(const f32x4*)(cw + (2 * UPN + DFF + jn)), bu = *(const f32x4*)(cb + (DFF + jn));
;                     f32x4 pu1 = (f32x4){0.f, 0.f, 0.f, 0.f}, pu2 = pu1;
; #pragma unroll
;                     for (int m = 0; m < 4; ++m) {
;                         const f32x4 au = unpack4(pa[ai][1][m][n]);
;                         const f32x4 ru1 = ror1v(au), ru2 = ror2v(au);
;                         const f32x4 u1 = fr >= 1 ? ru1 : pu1, u2 = fr >= 2 ? ru2 : pu2;
;                         if (m == 0 && fr < 2) *(f32x4*)(edge + (unsigned)((grp * 4 + fr) * UPN + DFF + jn)) = au;
;                         if (m == 3 && fr >= 14) *(f32x4*)(edge + (unsigned)((grp * 4 + (fr - 12)) * UPN + DFF + jn)) = au;
;                         cu[m] = bu + wu0 * u2 + wu1 * u1 + wu2 * au;
;                         pu1 = ru1; pu2 = ru2; }
;                 }
;                 {
;                     const f32x4 wg0 = *(const f32x4*)(cw + jn), wg1 = *(const f32x4*)(cw + (UPN + jn)), wg2 = *(const f32x4*)(cw + (2 * UPN + jn)), bg = *(const f32x4*)(cb + jn);
;                     f32x4 pg1 = (f32x4){0.f, 0.f, 0.f, 0.f}, pg2 = pg1;
; #pragma unroll
;                     for (int m = 0; m < 4; ++m) { const int row = rowg + m * 16 + fr;
;                         const f32x4 ag = unpack4(pa[ai][0][m][n]);
;                         const f32x4 rg1 = ror1v(ag), rg2 = ror2v(ag);
;                         const f32x4 g1 = fr >= 1 ? rg1 : pg1, g2 = fr >= 2 ? rg2 : pg2;
;                         if (m == 0 && fr < 2) *(f32x4*)(edge + (unsigned)((grp * 4 + fr) * UPN + jn)) = ag;
;                         if (m == 3 && fr >= 14) *(f32x4*)(edge + (unsigned)((grp * 4 + (fr - 12)) * UPN + jn)) = ag;
;                         const f32x4 o = gelu4(bg + wg0 * g2 + wg1 * g1 + wg2 * ag) * cu[m];
;                         if (!(m == 0 && fr < 2)) *(u32x2*)(act + (unsigned)(row * DFF + jn)) = pack4(o);
;                         pg1 = rg1; pg2 = rg2; }
.LBB0_577:
	s_or_b64 exec, exec, s[0:1]
	s_nop 0
	v_cndmask_b32_e64 v41, v171, v172, s[6:7]
	v_cndmask_b32_e64 v40, v169, v170, s[6:7]
	v_cndmask_b32_e64 v43, v150, v168, s[6:7]
	v_cndmask_b32_e64 v42, v127, v148, s[6:7]
	v_cndmask_b32_e64 v37, v146, v152, s[8:9]
	v_cndmask_b32_e64 v36, v124, v126, s[8:9]
	v_cndmask_b32_e64 v39, v149, v167, s[8:9]
	v_cndmask_b32_e64 v38, v125, v147, s[8:9]
	s_waitcnt vmcnt(4)
	v_pk_fma_f32 v[42:43], v[8:9], v[42:43], v[12:13]
	v_pk_fma_f32 v[40:41], v[10:11], v[40:41], v[14:15]
	v_pk_fma_f32 v[36:37], v[4:5], v[36:37], v[42:43]
	v_pk_fma_f32 v[38:39], v[6:7], v[38:39], v[40:41]
	v_pk_fma_f32 v[36:37], v[0:1], v[58:59], v[36:37]
	v_pk_fma_f32 v[38:39], v[2:3], v[56:57], v[38:39]
	v_cndmask_b32_e64 v57, v172, v90, s[6:7]
	v_cndmask_b32_e64 v56, v170, v89, s[6:7]
	v_cndmask_b32_e64 v59, v168, v88, s[6:7]
	v_cndmask_b32_e64 v58, v148, v85, s[6:7]
	v_cndmask_b32_e64 v41, v152, v86, s[8:9]
	v_cndmask_b32_e64 v40, v126, v83, s[8:9]
	v_cndmask_b32_e64 v43, v167, v87, s[8:9]
	v_cndmask_b32_e64 v42, v147, v84, s[8:9]
	v_pk_fma_f32 v[58:59], v[8:9], v[58:59], v[12:13]
	v_pk_fma_f32 v[56:57], v[10:11], v[56:57], v[14:15]
	v_pk_fma_f32 v[40:41], v[4:5], v[40:41], v[58:59]
	v_pk_fma_f32 v[42:43], v[6:7], v[42:43], v[56:57]
	v_pk_fma_f32 v[56:57], v[0:1], v[54:55], v[40:41]
	v_pk_fma_f32 v[58:59], v[2:3], v[52:53], v[42:43]
	v_lshlrev_b32_e32 v40, 16, v112
	v_and_b32_e32 v41, 0xffff0000, v112
	v_lshlrev_b32_e32 v42, 16, v113
	v_and_b32_e32 v43, 0xffff0000, v113
	s_nop 1
	v_mov_b32_dpp v112, v40 row_ror:1 row_mask:0xf bank_mask:0xf
	v_mov_b32_dpp v113, v41 row_ror:1 row_mask:0xf bank_mask:0xf
	v_mov_b32_dpp v123, v40 row_ror:2 row_mask:0xf bank_mask:0xf
	v_mov_b32_dpp v124, v41 row_ror:2 row_mask:0xf bank_mask:0xf
	v_cndmask_b32_e64 v55, v61, v113, s[8:9]
	v_cndmask_b32_e64 v54, v60, v112, s[8:9]
	v_cndmask_b32_e64 v61, v77, v124, s[6:7]
	v_cndmask_b32_e64 v60, v76, v123, s[6:7]
	s_waitcnt vmcnt(2)
	v_pk_fma_f32 v[60:61], v[28:29], v[60:61], v[32:33]
	s_nop 1
	v_pk_fma_f32 v[54:55], v[24:25], v[54:55], v[60:61]
	s_nop 1
	v_pk_fma_f32 v[40:41], v[20:21], v[40:41], v[54:55]
	s_nop 1
	v_and_b32_e32 v61, 0x7fffffff, v41
	v_and_b32_e32 v60, 0x7fffffff, v40
	v_pk_fma_f32 v[60:61], v[60:61], s[42:43], 1.0 op_sel_hi:[1,0,0]
	s_nop 1
	v_rcp_f32_e32 v60, v60
	v_rcp_f32_e32 v61, v61
	v_mov_b32_dpp v114, v42 row_ror:1 row_mask:0xf bank_mask:0xf
	v_mov_b32_dpp v115, v43 row_ror:1 row_mask:0xf bank_mask:0xf
	v_mov_b32_dpp v125, v42 row_ror:2 row_mask:0xf bank_mask:0xf
	v_mov_b32_dpp v126, v43 row_ror:2 row_mask:0xf bank_mask:0xf
	v_cndmask_b32_e64 v53, v65, v115, s[8:9]
	v_cndmask_b32_e64 v52, v64, v114, s[8:9]
	v_cndmask_b32_e64 v65, v79, v126, s[6:7]
	v_cndmask_b32_e64 v64, v78, v125, s[6:7]
	v_pk_fma_f32 v[64:65], v[30:31], v[64:65], v[34:35]
	v_pk_mul_f32 v[54:55], v[40:41], v[40:41]
	v_mov_b64_e32 v[76:77], s[54:55]
	v_pk_fma_f32 v[52:53], v[26:27], v[52:53], v[64:65]
	v_pk_mul_f32 v[54:55], v[54:55], s[38:39] op_sel_hi:[1,0]
	v_pk_fma_f32 v[64:65], v[60:61], s[52:53], v[76:77] op_sel_hi:[1,0,0]
	v_exp_f32_e32 v54, v54
	v_exp_f32_e32 v55, v55
	v_pk_fma_f32 v[64:65], v[60:61], v[64:65], s[56:57] op_sel_hi:[1,1,0]
	s_nop 0
	v_pk_fma_f32 v[64:65], v[60:61], v[64:65], s[62:63] op_sel_hi:[1,1,0]
	v_pk_fma_f32 v[42:43], v[22:23], v[42:43], v[52:53]
	v_pk_fma_f32 v[64:65], v[60:61], v[64:65], s[64:65] op_sel_hi:[1,1,0]
	v_pk_mul_f32 v[52:53], v[42:43], v[42:43]
	v_pk_mul_f32 v[60:61], v[60:61], v[64:65]
	v_pk_mul_f32 v[52:53], v[52:53], s[38:39] op_sel_hi:[1,0]
	v_pk_fma_f32 v[54:55], v[54:55], v[60:61], 0.5 op_sel_hi:[1,1,0] neg_lo:[1,0,0] neg_hi:[1,0,0]
	v_exp_f32_e32 v52, v52
	v_mul_f32_e64 v60, |v40|, v54
	v_mul_f32_e64 v61, |v41|, v55
	v_exp_f32_e32 v53, v53
	v_and_b32_e32 v54, 0x7fffffff, v42
	v_add_u32_e32 v64, 0xb000, v82
	v_pk_fma_f32 v[40:41], v[40:41], 0.5, v[60:61] op_sel_hi:[1,0,1]
	v_and_b32_e32 v55, 0x7fffffff, v43
	v_pk_fma_f32 v[54:55], v[54:55], s[42:43], 1.0 op_sel_hi:[1,0,0]
	s_nop 0
	v_rcp_f32_e32 v54, v54
	v_rcp_f32_e32 v55, v55
	v_pk_mul_f32 v[36:37], v[36:37], v[40:41]
	v_add_u32_e32 v136, v64, v44
	v_cvt_pk_bf16_f32 v36, v36, v37
	v_pk_fma_f32 v[60:61], v[54:55], s[52:53], v[76:77] op_sel_hi:[1,0,0]
	s_nop 1
	v_pk_fma_f32 v[60:61], v[54:55], v[60:61], s[56:57] op_sel_hi:[1,1,0]
	s_nop 1
	v_pk_fma_f32 v[60:61], v[54:55], v[60:61], s[62:63] op_sel_hi:[1,1,0]
	v_add_u32_e32 v65, 0x16000, v82
	v_pk_fma_f32 v[60:61], v[54:55], v[60:61], s[64:65] op_sel_hi:[1,1,0]
	s_nop 0
	v_pk_mul_f32 v[54:55], v[54:55], v[60:61]
	s_nop 0
	v_pk_fma_f32 v[52:53], v[52:53], v[54:55], 0.5 op_sel_hi:[1,1,0] neg_lo:[1,0,0] neg_hi:[1,0,0]
	s_nop 0
	v_mul_f32_e64 v54, |v42|, v52
	v_mul_f32_e64 v55, |v43|, v53
	v_pk_fma_f32 v[42:43], v[42:43], 0.5, v[54:55] op_sel_hi:[1,0,1]
	v_pk_mul_f32 v[38:39], v[38:39], v[42:43]
	s_nop 1
	v_cvt_pk_bf16_f32 v37, v38, v39
	v_lshl_add_u64 v[38:39], v[136:137], 1, s[26:27]
	global_store_dwordx2 v[38:39], v[36:37], off
	v_lshlrev_b32_e32 v36, 16, v110
	v_and_b32_e32 v37, 0xffff0000, v110
	v_lshlrev_b32_e32 v38, 16, v111
	v_mov_b32_dpp v43, v36 row_ror:2 row_mask:0xf bank_mask:0xf
	v_mov_b32_dpp v54, v37 row_ror:2 row_mask:0xf bank_mask:0xf
	v_and_b32_e32 v39, 0xffff0000, v111
	v_mov_b32_dpp v40, v36 row_ror:1 row_mask:0xf bank_mask:0xf
	v_mov_b32_dpp v41, v37 row_ror:1 row_mask:0xf bank_mask:0xf
	v_cndmask_b32_e64 v111, v124, v54, s[6:7]
	v_cndmask_b32_e64 v110, v123, v43, s[6:7]
	v_cndmask_b32_e64 v79, v113, v41, s[8:9]
	v_cndmask_b32_e64 v78, v112, v40, s[8:9]
	v_pk_fma_f32 v[110:111], v[28:29], v[110:111], v[32:33]
	s_nop 1
	v_pk_fma_f32 v[78:79], v[24:25], v[78:79], v[110:111]
	s_nop 1
; __device__ __forceinline__ f32x4 gelu4(f32x4 v) { const f32x2 a = gelu_pk((f32x2){v[0], v[1]}), b = gelu_pk((f32x2){v[2], v[3]}); return (f32x4){a.x, a.y, b.x, b.y}; }
; __device__ __forceinline__ f32x4 ror1v(f32x4 v) { return (f32x4){dpp_ror1(v[0]), dpp_ror1(v[1]), dpp_ror1(v[2]), dpp_ror1(v[3])}; }
; __device__ __forceinline__ f32x4 ror2v(f32x4 v) { return (f32x4){dpp_ror2(v[0]), dpp_ror2(v[1]), dpp_ror2(v[2]), dpp_ror2(v[3])}; }
; __device__ __forceinline__ u32x2 pack4(f32x4 v) { return (u32x2){pk2(v[0], v[1]), pk2(v[2], v[3])}; }
; __device__ __forceinline__ f32x2 gelu_pk(f32x2 v) {
;     const f32x2 av = __builtin_elementwise_abs(v), d = av * 0.2316418882f + 1.0f;
;     f32x2 t; t.x = __builtin_amdgcn_rcpf(d.x); t.y = __builtin_amdgcn_rcpf(d.y);
;     f32x2 q = t * 0.5307027145f + (-0.7265760135f); q = q * t + 0.7107068705f; q = q * t + (-0.142248368f); q = q * t + 0.127414796f; q = q * t;
;     const f32x2 s = (v * v) * (-0.72134752044f);
;     f32x2 e; e.x = __builtin_amdgcn_exp2f(s.x); e.y = __builtin_amdgcn_exp2f(s.y);
;     const f32x2 m = v * (q * e), r = v - m;
;     f32x2 o; o.x = v.x < 0.f ? m.x : r.x; o.y = v.y < 0.f ? m.y : r.y; return o;
;     __device__ __forceinline__ void operator()(AccRef acc, const Unit& u, int wr, int wc, int fr, int fq) const {
;     ...
;                     const f32x4 wg0 = *(const f32x4*)(cw + jn), wg1 = *(const f32x4*)(cw + (UPN + jn)), wg2 = *(const f32x4*)(cw + (2 * UPN + jn)), bg = *(const f32x4*)(cb + jn);
;                     f32x4 pg1 = (f32x4){0.f, 0.f, 0.f, 0.f}, pg2 = pg1;
; #pragma unroll
;                     for (int m = 0; m < 4; ++m) { const int row = rowg + m * 16 + fr;
;                         const f32x4 ag = unpack4(pa[ai][0][m][n]);
;                         const f32x4 rg1 = ror1v(ag), rg2 = ror2v(ag);
;                         const f32x4 g1 = fr >= 1 ? rg1 : pg1, g2 = fr >= 2 ? rg2 : pg2;
;                         if (m == 0 && fr < 2) *(f32x4*)(edge + (unsigned)((grp * 4 + fr) * UPN + jn)) = ag;
;                         if (m == 3 && fr >= 14) *(f32x4*)(edge + (unsigned)((grp * 4 + (fr - 12)) * UPN + jn)) = ag;
;                         const f32x4 o = gelu4(bg + wg0 * g2 + wg1 * g1 + wg2 * ag) * cu[m];
;                         if (!(m == 0 && fr < 2)) *(u32x2*)(act + (unsigned)(row * DFF + jn)) = pack4(o);
;                         pg1 = rg1; pg2 = rg2; }
	v_pk_fma_f32 v[36:37], v[20:21], v[36:37], v[78:79]
	s_nop 1
	v_and_b32_e32 v111, 0x7fffffff, v37
	v_and_b32_e32 v110, 0x7fffffff, v36
	v_pk_fma_f32 v[110:111], v[110:111], s[42:43], 1.0 op_sel_hi:[1,0,0]
	v_mov_b32_dpp v52, v38 row_ror:2 row_mask:0xf bank_mask:0xf
	v_rcp_f32_e32 v110, v110
	v_rcp_f32_e32 v111, v111
	v_mov_b32_dpp v55, v39 row_ror:2 row_mask:0xf bank_mask:0xf
	v_mov_b32_dpp v42, v38 row_ror:1 row_mask:0xf bank_mask:0xf
	v_mov_b32_dpp v53, v39 row_ror:1 row_mask:0xf bank_mask:0xf
	v_cndmask_b32_e64 v113, v126, v55, s[6:7]
	v_cndmask_b32_e64 v112, v125, v52, s[6:7]
	v_cndmask_b32_e64 v61, v115, v53, s[8:9]
	v_cndmask_b32_e64 v60, v114, v42, s[8:9]
	v_pk_fma_f32 v[112:113], v[30:31], v[112:113], v[34:35]
	v_pk_mul_f32 v[78:79], v[36:37], v[36:37]
	v_pk_fma_f32 v[60:61], v[26:27], v[60:61], v[112:113]
	v_pk_mul_f32 v[78:79], v[78:79], s[38:39] op_sel_hi:[1,0]
	v_pk_fma_f32 v[112:113], v[110:111], s[52:53], v[76:77] op_sel_hi:[1,0,0]
	v_exp_f32_e32 v78, v78
	v_exp_f32_e32 v79, v79
	v_pk_fma_f32 v[112:113], v[110:111], v[112:113], s[56:57] op_sel_hi:[1,1,0]
	s_nop 0
	v_pk_fma_f32 v[112:113], v[110:111], v[112:113], s[62:63] op_sel_hi:[1,1,0]
	v_pk_fma_f32 v[38:39], v[22:23], v[38:39], v[60:61]
	v_pk_fma_f32 v[112:113], v[110:111], v[112:113], s[64:65] op_sel_hi:[1,1,0]
	v_pk_mul_f32 v[60:61], v[38:39], v[38:39]
	v_pk_mul_f32 v[110:111], v[110:111], v[112:113]
	v_pk_mul_f32 v[60:61], v[60:61], s[38:39] op_sel_hi:[1,0]
	v_pk_fma_f32 v[78:79], v[78:79], v[110:111], 0.5 op_sel_hi:[1,1,0] neg_lo:[1,0,0] neg_hi:[1,0,0]
	v_exp_f32_e32 v60, v60
	v_mul_f32_e64 v110, |v36|, v78
	v_mul_f32_e64 v111, |v37|, v79
	v_exp_f32_e32 v61, v61
	v_and_b32_e32 v78, 0x7fffffff, v38
	v_add_u32_e32 v136, v65, v44
	v_pk_fma_f32 v[36:37], v[36:37], 0.5, v[110:111] op_sel_hi:[1,0,1]
	v_and_b32_e32 v79, 0x7fffffff, v39
	v_pk_fma_f32 v[78:79], v[78:79], s[42:43], 1.0 op_sel_hi:[1,0,0]
	s_nop 0
	v_rcp_f32_e32 v78, v78
	v_rcp_f32_e32 v79, v79
	v_pk_mul_f32 v[36:37], v[56:57], v[36:37]
	s_nop 1
	v_cvt_pk_bf16_f32 v36, v36, v37
	v_pk_fma_f32 v[76:77], v[78:79], s[52:53], v[76:77] op_sel_hi:[1,0,0]
	s_nop 1
	v_pk_fma_f32 v[76:77], v[78:79], v[76:77], s[56:57] op_sel_hi:[1,1,0]
	s_nop 0
	v_pk_fma_f32 v[76:77], v[78:79], v[76:77], s[62:63] op_sel_hi:[1,1,0]
	s_nop 0
	v_pk_fma_f32 v[76:77], v[78:79], v[76:77], s[64:65] op_sel_hi:[1,1,0]
	s_nop 0
	v_pk_mul_f32 v[76:77], v[78:79], v[76:77]
	s_nop 0
	v_pk_fma_f32 v[60:61], v[60:61], v[76:77], 0.5 op_sel_hi:[1,1,0] neg_lo:[1,0,0] neg_hi:[1,0,0]
	s_nop 0
	v_mul_f32_e64 v76, |v38|, v60
	v_mul_f32_e64 v77, |v39|, v61
	v_pk_fma_f32 v[38:39], v[38:39], 0.5, v[76:77] op_sel_hi:[1,0,1]
	v_pk_mul_f32 v[38:39], v[58:59], v[38:39]
	s_nop 1
	v_cvt_pk_bf16_f32 v37, v38, v39
	v_lshl_add_u64 v[38:39], v[136:137], 1, s[26:27]
	global_store_dwordx2 v[38:39], v[36:37], off
	v_lshlrev_b32_e32 v36, 16, v108
	v_and_b32_e32 v37, 0xffff0000, v108
	v_lshlrev_b32_e32 v38, 16, v109
	v_and_b32_e32 v39, 0xffff0000, v109
	s_nop 1
	v_mov_b32_dpp v56, v36 row_ror:1 row_mask:0xf bank_mask:0xf
	v_mov_b32_dpp v57, v37 row_ror:1 row_mask:0xf bank_mask:0xf
	v_mov_b32_dpp v58, v38 row_ror:1 row_mask:0xf bank_mask:0xf
	v_mov_b32_dpp v61, v39 row_ror:1 row_mask:0xf bank_mask:0xf
	v_mov_b32_dpp v59, v36 row_ror:2 row_mask:0xf bank_mask:0xf
	v_mov_b32_dpp v76, v37 row_ror:2 row_mask:0xf bank_mask:0xf
	v_mov_b32_dpp v60, v38 row_ror:2 row_mask:0xf bank_mask:0xf
	v_mov_b32_dpp v77, v39 row_ror:2 row_mask:0xf bank_mask:0xf
	s_and_saveexec_b64 s[0:1], vcc
	s_cbranch_execz .LBB0_579
	v_add_u32_e32 v136, v51, v44
	v_lshl_add_u64 v[78:79], v[136:137], 2, s[28:29]
	global_store_dwordx4 v[78:79], v[36:39], off
; __device__ __forceinline__ f32x2 gelu_pk(f32x2 v) {
;     const f32x2 av = __builtin_elementwise_abs(v), d = av * 0.2316418882f + 1.0f;
;     f32x2 t; t.x = __builtin_amdgcn_rcpf(d.x); t.y = __builtin_amdgcn_rcpf(d.y);
;     __device__ __forceinline__ void operator()(AccRef acc, const Unit& u, int wr, int wc, int fr, int fq) const {
;     ...
;                     const f32x4 wu0 = *(const f32x4*)(cw + (DFF + jn)), wu1 = *(const f32x4*)(cw + (UPN + DFF + jn)), wu2 = *(const f32x4*)(cw + (2 * UPN + DFF + jn)), bu = *(const f32x4*)(cb + (DFF + jn));
;                     f32x4 pu1 = (f32x4){0.f, 0.f, 0.f, 0.f}, pu2 = pu1;
; #pragma unroll
;                     for (int m = 0; m < 4; ++m) {
;                         const f32x4 au = unpack4(pa[ai][1][m][n]);
;                         const f32x4 ru1 = ror1v(au), ru2 = ror2v(au);
;                         const f32x4 u1 = fr >= 1 ? ru1 : pu1, u2 = fr >= 2 ? ru2 : pu2;
;                         if (m == 0 && fr < 2) *(f32x4*)(edge + (unsigned)((grp * 4 + fr) * UPN + DFF + jn)) = au;
;                         if (m == 3 && fr >= 14) *(f32x4*)(edge + (unsigned)((grp * 4 + (fr - 12)) * UPN + DFF + jn)) = au;
;                         cu[m] = bu + wu0 * u2 + wu1 * u1 + wu2 * au;
;                         pu1 = ru1; pu2 = ru2; }
;                 }
;                 {
;                     const f32x4 wg0 = *(const f32x4*)(cw + jn), wg1 = *(const f32x4*)(cw + (UPN + jn)), wg2 = *(const f32x4*)(cw + (2 * UPN + jn)), bg = *(const f32x4*)(cb + jn);
;                     f32x4 pg1 = (f32x4){0.f, 0.f, 0.f, 0.f}, pg2 = pg1;
; #pragma unroll
;                     for (int m = 0; m < 4; ++m) { const int row = rowg + m * 16 + fr;
;                         const f32x4 ag = unpack4(pa[ai][0][m][n]);
;                         const f32x4 rg1 = ror1v(ag), rg2 = ror2v(ag);
;                         const f32x4 g1 = fr >= 1 ? rg1 : pg1, g2 = fr >= 2 ? rg2 : pg2;
;                         if (m == 0 && fr < 2) *(f32x4*)(edge + (unsigned)((grp * 4 + fr) * UPN + jn)) = ag;
;                         if (m == 3 && fr >= 14) *(f32x4*)(edge + (unsigned)((grp * 4 + (fr - 12)) * UPN + jn)) = ag;
;                         const f32x4 o = gelu4(bg + wg0 * g2 + wg1 * g1 + wg2 * ag) * cu[m];
;                         if (!(m == 0 && fr < 2)) *(u32x2*)(act + (unsigned)(row * DFF + jn)) = pack4(o);
;                         pg1 = rg1; pg2 = rg2; }
.LBB0_579:
	s_or_b64 exec, exec, s[0:1]
	v_cndmask_b32_e64 v78, v42, v58, s[8:9]
	v_cndmask_b32_e64 v40, v40, v56, s[8:9]
	v_cndmask_b32_e64 v56, v43, v59, s[6:7]
	v_cndmask_b32_e64 v59, v90, v122, s[6:7]
	v_cndmask_b32_e64 v58, v89, v121, s[6:7]
	v_cndmask_b32_e64 v41, v41, v57, s[8:9]
	v_cndmask_b32_e64 v57, v54, v76, s[6:7]
	v_cndmask_b32_e64 v43, v55, v77, s[6:7]
	v_cndmask_b32_e64 v55, v87, v119, s[8:9]
	v_cndmask_b32_e64 v54, v84, v116, s[8:9]
	v_pk_fma_f32 v[10:11], v[10:11], v[58:59], v[14:15]
	v_cndmask_b32_e64 v79, v53, v61, s[8:9]
	v_pk_fma_f32 v[6:7], v[6:7], v[54:55], v[10:11]
	v_cndmask_b32_e64 v42, v52, v60, s[6:7]
	v_pk_fma_f32 v[2:3], v[2:3], v[18:19], v[6:7]
	v_pk_fma_f32 v[6:7], v[28:29], v[56:57], v[32:33]
	v_cndmask_b32_e64 v61, v88, v120, s[6:7]
	v_pk_fma_f32 v[6:7], v[24:25], v[40:41], v[6:7]
	v_cndmask_b32_e64 v60, v85, v117, s[6:7]
	v_pk_fma_f32 v[6:7], v[20:21], v[36:37], v[6:7]
	v_pk_fma_f32 v[8:9], v[8:9], v[60:61], v[12:13]
	v_and_b32_e32 v13, 0x7fffffff, v7
	v_and_b32_e32 v12, 0x7fffffff, v6
	v_pk_fma_f32 v[12:13], v[12:13], s[42:43], 1.0 op_sel_hi:[1,0,0]
	v_cndmask_b32_e64 v53, v86, v118, s[8:9]
	v_rcp_f32_e32 v12, v12
	v_rcp_f32_e32 v13, v13
	v_cndmask_b32_e64 v52, v83, v91, s[8:9]
	v_pk_fma_f32 v[4:5], v[4:5], v[52:53], v[8:9]
	v_pk_mul_f32 v[10:11], v[6:7], v[6:7]
	v_mov_b64_e32 v[14:15], s[54:55]
	v_pk_fma_f32 v[0:1], v[0:1], v[16:17], v[4:5]
	v_pk_mul_f32 v[10:11], v[10:11], s[38:39] op_sel_hi:[1,0]
	v_pk_fma_f32 v[16:17], v[12:13], s[52:53], v[14:15] op_sel_hi:[1,0,0]
	v_exp_f32_e32 v10, v10
	v_exp_f32_e32 v11, v11
	v_pk_fma_f32 v[16:17], v[12:13], v[16:17], s[56:57] op_sel_hi:[1,1,0]
	v_pk_fma_f32 v[4:5], v[30:31], v[42:43], v[34:35]
	v_pk_fma_f32 v[16:17], v[12:13], v[16:17], s[62:63] op_sel_hi:[1,1,0]
	v_pk_fma_f32 v[4:5], v[26:27], v[78:79], v[4:5]
	v_pk_fma_f32 v[16:17], v[12:13], v[16:17], s[64:65] op_sel_hi:[1,1,0]
	s_nop 0
	v_pk_mul_f32 v[12:13], v[12:13], v[16:17]
	v_pk_fma_f32 v[4:5], v[22:23], v[38:39], v[4:5]
	v_pk_fma_f32 v[10:11], v[10:11], v[12:13], 0.5 op_sel_hi:[1,1,0] neg_lo:[1,0,0] neg_hi:[1,0,0]
	v_pk_mul_f32 v[8:9], v[4:5], v[4:5]
	v_mul_f32_e64 v12, |v6|, v10
	v_mul_f32_e64 v13, |v7|, v11
	v_pk_mul_f32 v[8:9], v[8:9], s[38:39] op_sel_hi:[1,0]
	s_nop 0
	v_and_b32_e32 v10, 0x7fffffff, v4
	v_exp_f32_e32 v8, v8
	v_pk_fma_f32 v[6:7], v[6:7], 0.5, v[12:13] op_sel_hi:[1,0,1]
	v_and_b32_e32 v11, 0x7fffffff, v5
	v_pk_fma_f32 v[10:11], v[10:11], s[42:43], 1.0 op_sel_hi:[1,0,0]
	v_exp_f32_e32 v9, v9
	v_rcp_f32_e32 v10, v10
	v_rcp_f32_e32 v11, v11
	v_add_u32_e32 v76, 0x21000, v82
	v_pk_mul_f32 v[0:1], v[0:1], v[6:7]
	v_pk_fma_f32 v[12:13], v[10:11], s[52:53], v[14:15] op_sel_hi:[1,0,0]
	v_add_u32_e32 v136, v76, v44
	v_pk_fma_f32 v[12:13], v[10:11], v[12:13], s[56:57] op_sel_hi:[1,1,0]
	v_cvt_pk_bf16_f32 v0, v0, v1
	v_lshlrev_b32_e32 v36, 16, v100
	v_pk_fma_f32 v[12:13], v[10:11], v[12:13], s[62:63] op_sel_hi:[1,1,0]
	v_and_b32_e32 v37, 0xffff0000, v100
	v_pk_fma_f32 v[12:13], v[10:11], v[12:13], s[64:65] op_sel_hi:[1,1,0]
	v_lshlrev_b32_e32 v38, 16, v101
	v_pk_mul_f32 v[10:11], v[10:11], v[12:13]
	v_and_b32_e32 v39, 0xffff0000, v101
	v_pk_fma_f32 v[8:9], v[8:9], v[10:11], 0.5 op_sel_hi:[1,1,0] neg_lo:[1,0,0] neg_hi:[1,0,0]
	s_nop 1
	v_mul_f32_e64 v10, |v4|, v8
	v_mul_f32_e64 v11, |v5|, v9
	v_pk_fma_f32 v[4:5], v[4:5], 0.5, v[10:11] op_sel_hi:[1,0,1]
	v_pk_mul_f32 v[2:3], v[2:3], v[4:5]
	s_nop 1
	v_cvt_pk_bf16_f32 v1, v2, v3
	v_lshl_add_u64 v[2:3], v[136:137], 1, s[26:27]
	global_store_dwordx2 v[2:3], v[0:1], off
	global_load_dwordx4 v[8:11], v[62:63], off
	global_load_dwordx4 v[4:7], v[66:67], off
	s_nop 0
	global_load_dwordx4 v[0:3], v[68:69], off
	global_load_dwordx4 v[12:15], v[70:71], off
	s_nop 1
	v_mov_b32_dpp v89, v36 row_ror:1 row_mask:0xf bank_mask:0xf
	v_mov_b32_dpp v108, v37 row_ror:1 row_mask:0xf bank_mask:0xf
	v_mov_b32_dpp v100, v38 row_ror:1 row_mask:0xf bank_mask:0xf
	v_mov_b32_dpp v110, v39 row_ror:1 row_mask:0xf bank_mask:0xf
	v_mov_b32_dpp v101, v36 row_ror:2 row_mask:0xf bank_mask:0xf
	v_mov_b32_dpp v111, v37 row_ror:2 row_mask:0xf bank_mask:0xf
	v_mov_b32_dpp v113, v38 row_ror:2 row_mask:0xf bank_mask:0xf
	v_mov_b32_dpp v115, v39 row_ror:2 row_mask:0xf bank_mask:0xf
	s_and_saveexec_b64 s[0:1], s[12:13]
	s_cbranch_execz .LBB0_581
	v_add_u32_e32 v136, v50, v45
	v_lshl_add_u64 v[16:17], v[136:137], 2, s[28:29]
	global_store_dwordx4 v[16:17], v[36:39], off

; __device__ __forceinline__ f32x4 gelu4(f32x4 v) { const f32x2 a = gelu_pk((f32x2){v[0], v[1]}), b = gelu_pk((f32x2){v[2], v[3]}); return (f32x4){a.x, a.y, b.x, b.y}; }
; __device__ __forceinline__ f32x4 ror1v(f32x4 v) { return (f32x4){dpp_ror1(v[0]), dpp_ror1(v[1]), dpp_ror1(v[2]), dpp_ror1(v[3])}; }
; __device__ __forceinline__ f32x4 ror2v(f32x4 v) { return (f32x4){dpp_ror2(v[0]), dpp_ror2(v[1]), dpp_ror2(v[2]), dpp_ror2(v[3])}; }
; __device__ __forceinline__ u32x2 pack4(f32x4 v) { return (u32x2){pk2(v[0], v[1]), pk2(v[2], v[3])}; }
; __device__ __forceinline__ f32x2 gelu_pk(f32x2 v) {
;     const f32x2 av = __builtin_elementwise_abs(v), d = av * 0.2316418882f + 1.0f;
;     f32x2 t; t.x = __builtin_amdgcn_rcpf(d.x); t.y = __builtin_amdgcn_rcpf(d.y);
;     f32x2 q = t * 0.5307027145f + (-0.7265760135f); q = q * t + 0.7107068705f; q = q * t + (-0.142248368f); q = q * t + 0.127414796f; q = q * t;
;     const f32x2 s = (v * v) * (-0.72134752044f);
;     f32x2 e; e.x = __builtin_amdgcn_exp2f(s.x); e.y = __builtin_amdgcn_exp2f(s.y);
;     const f32x2 m = v * (q * e), r = v - m;
;     f32x2 o; o.x = v.x < 0.f ? m.x : r.x; o.y = v.y < 0.f ? m.y : r.y; return o;
;     __device__ __forceinline__ void operator()(AccRef acc, const Unit& u, int wr, int wc, int fr, int fq) const {
;     ...
;                     const f32x4 wg0 = *(const f32x4*)(cw + jn), wg1 = *(const f32x4*)(cw + (UPN + jn)), wg2 = *(const f32x4*)(cw + (2 * UPN + jn)), bg = *(const f32x4*)(cb + jn);
;                     f32x4 pg1 = (f32x4){0.f, 0.f, 0.f, 0.f}, pg2 = pg1;
; #pragma unroll
;                     for (int m = 0; m < 4; ++m) { const int row = rowg + m * 16 + fr;
;                         const f32x4 ag = unpack4(pa[ai][0][m][n]);
;                         const f32x4 rg1 = ror1v(ag), rg2 = ror2v(ag);
;                         const f32x4 g1 = fr >= 1 ? rg1 : pg1, g2 = fr >= 2 ? rg2 : pg2;
;                         if (m == 0 && fr < 2) *(f32x4*)(edge + (unsigned)((grp * 4 + fr) * UPN + jn)) = ag;
;                         if (m == 3 && fr >= 14) *(f32x4*)(edge + (unsigned)((grp * 4 + (fr - 12)) * UPN + jn)) = ag;
;                         const f32x4 o = gelu4(bg + wg0 * g2 + wg1 * g1 + wg2 * ag) * cu[m];
;                         if (!(m == 0 && fr < 2)) *(u32x2*)(act + (unsigned)(row * DFF + jn)) = pack4(o);
;                         pg1 = rg1; pg2 = rg2; }
.LBB0_583:
	s_or_b64 exec, exec, s[0:1]
	global_load_dwordx4 v[28:31], v[46:47], off offset:16
	global_load_dwordx4 v[24:27], v[72:73], off
	global_load_dwordx4 v[20:23], v[74:75], off
	global_load_dwordx4 v[32:35], v[48:49], off offset:16
	v_lshlrev_b32_e32 v40, 16, v98
	v_and_b32_e32 v41, 0xffff0000, v98
	v_lshlrev_b32_e32 v42, 16, v99
	v_and_b32_e32 v43, 0xffff0000, v99
	s_nop 1
	v_mov_b32_dpp v46, v40 row_ror:1 row_mask:0xf bank_mask:0xf
	v_mov_b32_dpp v47, v41 row_ror:1 row_mask:0xf bank_mask:0xf
	v_mov_b32_dpp v48, v42 row_ror:1 row_mask:0xf bank_mask:0xf
	v_mov_b32_dpp v49, v43 row_ror:1 row_mask:0xf bank_mask:0xf
	v_mov_b32_dpp v58, v40 row_ror:2 row_mask:0xf bank_mask:0xf
	v_mov_b32_dpp v59, v41 row_ror:2 row_mask:0xf bank_mask:0xf
	v_mov_b32_dpp v60, v42 row_ror:2 row_mask:0xf bank_mask:0xf
	v_mov_b32_dpp v61, v43 row_ror:2 row_mask:0xf bank_mask:0xf
	s_and_saveexec_b64 s[0:1], s[10:11]
	s_xor_b64 s[10:11], exec, s[0:1]
	s_cbranch_execz .LBB0_585
	v_cndmask_b32_e64 v81, 0, v115, s[6:7]
	v_cndmask_b32_e64 v80, 0, v113, s[6:7]
	v_cndmask_b32_e64 v75, 0, v110, s[8:9]
	v_cndmask_b32_e64 v74, 0, v100, s[8:9]
	s_waitcnt vmcnt(4)
	v_pk_fma_f32 v[80:81], v[10:11], v[80:81], v[14:15]
	v_cndmask_b32_e64 v99, 0, v111, s[6:7]
	v_pk_fma_f32 v[74:75], v[6:7], v[74:75], v[80:81]
	v_cndmask_b32_e64 v98, 0, v101, s[6:7]
	v_pk_fma_f32 v[38:39], v[2:3], v[38:39], v[74:75]
	s_waitcnt vmcnt(0)
	v_pk_fma_f32 v[74:75], v[28:29], v[58:59], v[32:33]
	v_cndmask_b32_e64 v73, 0, v108, s[8:9]
	v_pk_fma_f32 v[74:75], v[24:25], v[46:47], v[74:75]
	v_cndmask_b32_e64 v72, 0, v89, s[8:9]
	v_pk_fma_f32 v[40:41], v[20:21], v[40:41], v[74:75]
	v_pk_fma_f32 v[98:99], v[8:9], v[98:99], v[12:13]
	v_and_b32_e32 v81, 0x7fffffff, v41
	v_and_b32_e32 v80, 0x7fffffff, v40
	v_pk_fma_f32 v[80:81], v[80:81], s[42:43], 1.0 op_sel_hi:[1,0,0]
	v_pk_fma_f32 v[72:73], v[4:5], v[72:73], v[98:99]
	v_rcp_f32_e32 v80, v80
	v_rcp_f32_e32 v81, v81
	v_pk_mul_f32 v[74:75], v[40:41], v[40:41]
	v_mov_b64_e32 v[98:99], s[54:55]
	v_pk_mul_f32 v[74:75], v[74:75], s[38:39] op_sel_hi:[1,0]
	v_pk_fma_f32 v[104:105], v[80:81], s[52:53], v[98:99] op_sel_hi:[1,0,0]
	v_exp_f32_e32 v74, v74
	v_exp_f32_e32 v75, v75
	v_pk_fma_f32 v[104:105], v[80:81], v[104:105], s[56:57] op_sel_hi:[1,1,0]
	v_pk_fma_f32 v[36:37], v[0:1], v[36:37], v[72:73]
	v_pk_fma_f32 v[104:105], v[80:81], v[104:105], s[62:63] op_sel_hi:[1,1,0]
	v_pk_fma_f32 v[72:73], v[30:31], v[60:61], v[34:35]
	v_pk_fma_f32 v[104:105], v[80:81], v[104:105], s[64:65] op_sel_hi:[1,1,0]
	v_pk_fma_f32 v[72:73], v[26:27], v[48:49], v[72:73]
	v_pk_mul_f32 v[80:81], v[80:81], v[104:105]
	s_nop 0
	v_pk_fma_f32 v[74:75], v[74:75], v[80:81], 0.5 op_sel_hi:[1,1,0] neg_lo:[1,0,0] neg_hi:[1,0,0]
	v_pk_fma_f32 v[42:43], v[22:23], v[42:43], v[72:73]
	v_mul_f32_e64 v80, |v40|, v74
	v_mul_f32_e64 v81, |v41|, v75
	v_pk_mul_f32 v[72:73], v[42:43], v[42:43]
	s_nop 0
	v_and_b32_e32 v74, 0x7fffffff, v42
	v_pk_mul_f32 v[72:73], v[72:73], s[38:39] op_sel_hi:[1,0]
	v_pk_fma_f32 v[40:41], v[40:41], 0.5, v[80:81] op_sel_hi:[1,0,1]
	v_and_b32_e32 v75, 0x7fffffff, v43
	v_pk_fma_f32 v[74:75], v[74:75], s[42:43], 1.0 op_sel_hi:[1,0,0]
	v_exp_f32_e32 v72, v72
	v_rcp_f32_e32 v74, v74
	v_rcp_f32_e32 v75, v75
	v_exp_f32_e32 v73, v73
	s_nop 0
	v_pk_mul_f32 v[36:37], v[36:37], v[40:41]
	v_pk_fma_f32 v[80:81], v[74:75], s[52:53], v[98:99] op_sel_hi:[1,0,0]
	v_add_u32_e32 v136, v82, v50
	v_pk_fma_f32 v[80:81], v[74:75], v[80:81], s[56:57] op_sel_hi:[1,1,0]
	v_cvt_pk_bf16_f32 v36, v36, v37
	s_nop 0
	v_pk_fma_f32 v[80:81], v[74:75], v[80:81], s[62:63] op_sel_hi:[1,1,0]
	s_nop 0
	v_pk_fma_f32 v[80:81], v[74:75], v[80:81], s[64:65] op_sel_hi:[1,1,0]
	s_nop 0
	v_pk_mul_f32 v[74:75], v[74:75], v[80:81]
	s_nop 0
	v_pk_fma_f32 v[72:73], v[72:73], v[74:75], 0.5 op_sel_hi:[1,1,0] neg_lo:[1,0,0] neg_hi:[1,0,0]
	s_nop 0
	v_mul_f32_e64 v74, |v42|, v72
	v_mul_f32_e64 v75, |v43|, v73
	v_pk_fma_f32 v[42:43], v[42:43], 0.5, v[74:75] op_sel_hi:[1,0,1]
	v_pk_mul_f32 v[38:39], v[38:39], v[42:43]
	s_nop 0
	v_cvt_pk_bf16_f32 v37, v38, v39
	v_lshl_add_u64 v[38:39], v[136:137], 1, s[26:27]
	global_store_dwordx2 v[38:39], v[36:37], off

; __device__ __forceinline__ f32x2 gelu_pk(f32x2 v) {
;     const f32x2 av = __builtin_elementwise_abs(v), d = av * 0.2316418882f + 1.0f;
;     f32x2 t; t.x = __builtin_amdgcn_rcpf(d.x); t.y = __builtin_amdgcn_rcpf(d.y);
;     __device__ __forceinline__ void operator()(AccRef acc, const Unit& u, int wr, int wc, int fr, int fq) const {
;     ...
;                     const f32x4 wu0 = *(const f32x4*)(cw + (DFF + jn)), wu1 = *(const f32x4*)(cw + (UPN + DFF + jn)), wu2 = *(const f32x4*)(cw + (2 * UPN + DFF + jn)), bu = *(const f32x4*)(cb + (DFF + jn));
;                     f32x4 pu1 = (f32x4){0.f, 0.f, 0.f, 0.f}, pu2 = pu1;
; #pragma unroll
;                     for (int m = 0; m < 4; ++m) {
;                         const f32x4 au = unpack4(pa[ai][1][m][n]);
;                         const f32x4 ru1 = ror1v(au), ru2 = ror2v(au);
;                         const f32x4 u1 = fr >= 1 ? ru1 : pu1, u2 = fr >= 2 ? ru2 : pu2;
;                         if (m == 0 && fr < 2) *(f32x4*)(edge + (unsigned)((grp * 4 + fr) * UPN + DFF + jn)) = au;
;                         if (m == 3 && fr >= 14) *(f32x4*)(edge + (unsigned)((grp * 4 + (fr - 12)) * UPN + DFF + jn)) = au;
;                         cu[m] = bu + wu0 * u2 + wu1 * u1 + wu2 * au;
;                         pu1 = ru1; pu2 = ru2; }
;                 }
;                 {
;                     const f32x4 wg0 = *(const f32x4*)(cw + jn), wg1 = *(const f32x4*)(cw + (UPN + jn)), wg2 = *(const f32x4*)(cw + (2 * UPN + jn)), bg = *(const f32x4*)(cb + jn);
;                     f32x4 pg1 = (f32x4){0.f, 0.f, 0.f, 0.f}, pg2 = pg1;
; #pragma unroll
;                     for (int m = 0; m < 4; ++m) { const int row = rowg + m * 16 + fr;
;                         const f32x4 ag = unpack4(pa[ai][0][m][n]);
;                         const f32x4 rg1 = ror1v(ag), rg2 = ror2v(ag);
;                         const f32x4 g1 = fr >= 1 ? rg1 : pg1, g2 = fr >= 2 ? rg2 : pg2;
;                         if (m == 0 && fr < 2) *(f32x4*)(edge + (unsigned)((grp * 4 + fr) * UPN + jn)) = ag;
;                         if (m == 3 && fr >= 14) *(f32x4*)(edge + (unsigned)((grp * 4 + (fr - 12)) * UPN + jn)) = ag;
;                         const f32x4 o = gelu4(bg + wg0 * g2 + wg1 * g1 + wg2 * ag) * cu[m];
;                         if (!(m == 0 && fr < 2)) *(u32x2*)(act + (unsigned)(row * DFF + jn)) = pack4(o);
;                         pg1 = rg1; pg2 = rg2; }
.LBB0_587:
	s_or_b64 exec, exec, s[0:1]
	s_nop 0
	v_cndmask_b32_e64 v41, v115, v114, s[6:7]
	v_cndmask_b32_e64 v40, v113, v112, s[6:7]
	v_cndmask_b32_e64 v43, v111, v109, s[6:7]
	v_cndmask_b32_e64 v42, v101, v91, s[6:7]
	v_cndmask_b32_e64 v37, v108, v102, s[8:9]
	v_cndmask_b32_e64 v36, v89, v88, s[8:9]
	v_cndmask_b32_e64 v39, v110, v103, s[8:9]
	v_cndmask_b32_e64 v38, v100, v90, s[8:9]
	s_waitcnt vmcnt(4)
	v_pk_fma_f32 v[42:43], v[8:9], v[42:43], v[12:13]
	v_pk_fma_f32 v[40:41], v[10:11], v[40:41], v[14:15]
	v_pk_fma_f32 v[36:37], v[4:5], v[36:37], v[42:43]
	v_pk_fma_f32 v[38:39], v[6:7], v[38:39], v[40:41]
	v_pk_fma_f32 v[36:37], v[0:1], v[56:57], v[36:37]
	v_pk_fma_f32 v[38:39], v[2:3], v[54:55], v[38:39]
	v_cndmask_b32_e64 v55, v114, v71, s[6:7]
	v_cndmask_b32_e64 v54, v112, v70, s[6:7]
	v_cndmask_b32_e64 v57, v109, v69, s[6:7]
	v_cndmask_b32_e64 v56, v91, v66, s[6:7]
	v_cndmask_b32_e64 v41, v102, v67, s[8:9]
	v_cndmask_b32_e64 v40, v88, v62, s[8:9]
	v_cndmask_b32_e64 v43, v103, v68, s[8:9]
	v_cndmask_b32_e64 v42, v90, v63, s[8:9]
	v_pk_fma_f32 v[56:57], v[8:9], v[56:57], v[12:13]
	v_pk_fma_f32 v[54:55], v[10:11], v[54:55], v[14:15]
	v_pk_fma_f32 v[40:41], v[4:5], v[40:41], v[56:57]
	v_pk_fma_f32 v[42:43], v[6:7], v[42:43], v[54:55]
	v_pk_fma_f32 v[52:53], v[0:1], v[52:53], v[40:41]
	v_pk_fma_f32 v[54:55], v[2:3], v[44:45], v[42:43]
	v_lshlrev_b32_e32 v40, 16, v96
	v_and_b32_e32 v41, 0xffff0000, v96
	v_lshlrev_b32_e32 v42, 16, v97
	v_and_b32_e32 v43, 0xffff0000, v97
	s_nop 1
	v_mov_b32_dpp v74, v42 row_ror:1 row_mask:0xf bank_mask:0xf
	v_mov_b32_dpp v75, v43 row_ror:1 row_mask:0xf bank_mask:0xf
	v_mov_b32_dpp v80, v40 row_ror:2 row_mask:0xf bank_mask:0xf
	v_mov_b32_dpp v81, v41 row_ror:2 row_mask:0xf bank_mask:0xf
	v_mov_b32_dpp v72, v40 row_ror:1 row_mask:0xf bank_mask:0xf
	v_mov_b32_dpp v73, v41 row_ror:1 row_mask:0xf bank_mask:0xf
	v_cndmask_b32_e64 v45, v49, v75, s[8:9]
	v_cndmask_b32_e64 v44, v48, v74, s[8:9]
	v_cndmask_b32_e64 v49, v59, v81, s[6:7]
	v_cndmask_b32_e64 v48, v58, v80, s[6:7]
	v_cndmask_b32_e64 v47, v47, v73, s[8:9]
	v_cndmask_b32_e64 v46, v46, v72, s[8:9]
	s_waitcnt vmcnt(2)
	v_pk_fma_f32 v[48:49], v[28:29], v[48:49], v[32:33]
	s_nop 1
	v_pk_fma_f32 v[46:47], v[24:25], v[46:47], v[48:49]
	s_nop 1
	v_pk_fma_f32 v[40:41], v[20:21], v[40:41], v[46:47]
	v_mov_b32_dpp v82, v42 row_ror:2 row_mask:0xf bank_mask:0xf
	v_and_b32_e32 v49, 0x7fffffff, v41
	v_and_b32_e32 v48, 0x7fffffff, v40
	v_pk_fma_f32 v[48:49], v[48:49], s[42:43], 1.0 op_sel_hi:[1,0,0]
	v_mov_b32_dpp v88, v43 row_ror:2 row_mask:0xf bank_mask:0xf
	v_rcp_f32_e32 v48, v48
	v_rcp_f32_e32 v49, v49
	v_cndmask_b32_e64 v57, v61, v88, s[6:7]
	v_cndmask_b32_e64 v56, v60, v82, s[6:7]
	v_pk_fma_f32 v[56:57], v[30:31], v[56:57], v[34:35]
	v_pk_mul_f32 v[46:47], v[40:41], v[40:41]
	v_pk_fma_f32 v[44:45], v[26:27], v[44:45], v[56:57]
	v_mov_b64_e32 v[56:57], s[54:55]
	v_pk_mul_f32 v[46:47], v[46:47], s[38:39] op_sel_hi:[1,0]
	v_pk_fma_f32 v[58:59], v[48:49], s[52:53], v[56:57] op_sel_hi:[1,0,0]
	v_exp_f32_e32 v46, v46
	v_exp_f32_e32 v47, v47
	v_pk_fma_f32 v[58:59], v[48:49], v[58:59], s[56:57] op_sel_hi:[1,1,0]
	s_nop 0
	v_pk_fma_f32 v[58:59], v[48:49], v[58:59], s[62:63] op_sel_hi:[1,1,0]
	v_pk_fma_f32 v[42:43], v[22:23], v[42:43], v[44:45]
	v_pk_fma_f32 v[58:59], v[48:49], v[58:59], s[64:65] op_sel_hi:[1,1,0]
	v_pk_mul_f32 v[44:45], v[42:43], v[42:43]
	v_pk_mul_f32 v[48:49], v[48:49], v[58:59]
	v_pk_mul_f32 v[44:45], v[44:45], s[38:39] op_sel_hi:[1,0]
	v_pk_fma_f32 v[46:47], v[46:47], v[48:49], 0.5 op_sel_hi:[1,1,0] neg_lo:[1,0,0] neg_hi:[1,0,0]
	v_exp_f32_e32 v44, v44
	v_mul_f32_e64 v48, |v40|, v46
	v_mul_f32_e64 v49, |v41|, v47
	v_exp_f32_e32 v45, v45
	v_and_b32_e32 v46, 0x7fffffff, v42
	v_add_u32_e32 v136, v64, v50
	v_pk_fma_f32 v[40:41], v[40:41], 0.5, v[48:49] op_sel_hi:[1,0,1]
	v_and_b32_e32 v47, 0x7fffffff, v43
	v_pk_fma_f32 v[46:47], v[46:47], s[42:43], 1.0 op_sel_hi:[1,0,0]
	s_nop 0
	v_rcp_f32_e32 v46, v46
	v_rcp_f32_e32 v47, v47
	v_pk_mul_f32 v[36:37], v[36:37], v[40:41]
	s_nop 1
	v_cvt_pk_bf16_f32 v36, v36, v37
	v_pk_fma_f32 v[48:49], v[46:47], s[52:53], v[56:57] op_sel_hi:[1,0,0]
	s_nop 1
	v_pk_fma_f32 v[48:49], v[46:47], v[48:49], s[56:57] op_sel_hi:[1,1,0]
	s_nop 0
	v_pk_fma_f32 v[48:49], v[46:47], v[48:49], s[62:63] op_sel_hi:[1,1,0]
	s_nop 0
	v_pk_fma_f32 v[48:49], v[46:47], v[48:49], s[64:65] op_sel_hi:[1,1,0]
	s_nop 0
	v_pk_mul_f32 v[46:47], v[46:47], v[48:49]
	s_nop 0
	v_pk_fma_f32 v[44:45], v[44:45], v[46:47], 0.5 op_sel_hi:[1,1,0] neg_lo:[1,0,0] neg_hi:[1,0,0]
	s_nop 0
	v_mul_f32_e64 v46, |v42|, v44
	v_mul_f32_e64 v47, |v43|, v45
	v_pk_fma_f32 v[42:43], v[42:43], 0.5, v[46:47] op_sel_hi:[1,0,1]
	v_pk_mul_f32 v[38:39], v[38:39], v[42:43]
	s_nop 1
	v_cvt_pk_bf16_f32 v37, v38, v39
	v_lshl_add_u64 v[38:39], v[136:137], 1, s[26:27]
	global_store_dwordx2 v[38:39], v[36:37], off
	v_lshlrev_b32_e32 v36, 16, v94
	v_and_b32_e32 v37, 0xffff0000, v94
	v_lshlrev_b32_e32 v38, 16, v95
	v_mov_b32_dpp v44, v36 row_ror:2 row_mask:0xf bank_mask:0xf
	v_mov_b32_dpp v46, v37 row_ror:2 row_mask:0xf bank_mask:0xf
	v_mov_b32_dpp v40, v36 row_ror:1 row_mask:0xf bank_mask:0xf
	v_mov_b32_dpp v41, v37 row_ror:1 row_mask:0xf bank_mask:0xf
	v_cndmask_b32_e64 v61, v81, v46, s[6:7]
	v_cndmask_b32_e64 v60, v80, v44, s[6:7]
	v_cndmask_b32_e64 v59, v73, v41, s[8:9]
	v_cndmask_b32_e64 v58, v72, v40, s[8:9]
	v_pk_fma_f32 v[60:61], v[28:29], v[60:61], v[32:33]
	v_and_b32_e32 v39, 0xffff0000, v95
	v_pk_fma_f32 v[58:59], v[24:25], v[58:59], v[60:61]
	s_nop 1
	v_pk_fma_f32 v[36:37], v[20:21], v[36:37], v[58:59]
	s_nop 1
	v_and_b32_e32 v61, 0x7fffffff, v37
	v_and_b32_e32 v60, 0x7fffffff, v36
; __device__ __forceinline__ f32x4 gelu4(f32x4 v) { const f32x2 a = gelu_pk((f32x2){v[0], v[1]}), b = gelu_pk((f32x2){v[2], v[3]}); return (f32x4){a.x, a.y, b.x, b.y}; }
; __device__ __forceinline__ f32x4 ror1v(f32x4 v) { return (f32x4){dpp_ror1(v[0]), dpp_ror1(v[1]), dpp_ror1(v[2]), dpp_ror1(v[3])}; }
; __device__ __forceinline__ f32x2 gelu_pk(f32x2 v) {
;     const f32x2 av = __builtin_elementwise_abs(v), d = av * 0.2316418882f + 1.0f;
;     f32x2 t; t.x = __builtin_amdgcn_rcpf(d.x); t.y = __builtin_amdgcn_rcpf(d.y);
;     f32x2 q = t * 0.5307027145f + (-0.7265760135f); q = q * t + 0.7107068705f; q = q * t + (-0.142248368f); q = q * t + 0.127414796f; q = q * t;
;     const f32x2 s = (v * v) * (-0.72134752044f);
;     f32x2 e; e.x = __builtin_amdgcn_exp2f(s.x); e.y = __builtin_amdgcn_exp2f(s.y);
;     const f32x2 m = v * (q * e), r = v - m;
;     f32x2 o; o.x = v.x < 0.f ? m.x : r.x; o.y = v.y < 0.f ? m.y : r.y; return o;
; template <class Epi>
; __device__ __forceinline__ void gemm_phase(LAS unsigned char* lds, const Gemm g, const StaticOrder& S, const Epi& E) {
;     ...
;         if (wr == 0) PG8_BAR;
;         E(acc, cur, wr, wc, fr, fq);
;         if (!has_next) break;
;     __device__ __forceinline__ void operator()(AccRef acc, const Unit& u, int wr, int wc, int fr, int fq) const {
;     ...
;                     const f32x4 wg0 = *(const f32x4*)(cw + jn), wg1 = *(const f32x4*)(cw + (UPN + jn)), wg2 = *(const f32x4*)(cw + (2 * UPN + jn)), bg = *(const f32x4*)(cb + jn);
;                     f32x4 pg1 = (f32x4){0.f, 0.f, 0.f, 0.f}, pg2 = pg1;
; #pragma unroll
;                     for (int m = 0; m < 4; ++m) { const int row = rowg + m * 16 + fr;
;                         const f32x4 ag = unpack4(pa[ai][0][m][n]);
;                         const f32x4 rg1 = ror1v(ag), rg2 = ror2v(ag);
;                         const f32x4 g1 = fr >= 1 ? rg1 : pg1, g2 = fr >= 2 ? rg2 : pg2;
;                         if (m == 0 && fr < 2) *(f32x4*)(edge + (unsigned)((grp * 4 + fr) * UPN + jn)) = ag;
;                         if (m == 3 && fr >= 14) *(f32x4*)(edge + (unsigned)((grp * 4 + (fr - 12)) * UPN + jn)) = ag;
;                         const f32x4 o = gelu4(bg + wg0 * g2 + wg1 * g1 + wg2 * ag) * cu[m];
;                         if (!(m == 0 && fr < 2)) *(u32x2*)(act + (unsigned)(row * DFF + jn)) = pack4(o);
;                         pg1 = rg1; pg2 = rg2; }
	v_pk_fma_f32 v[60:61], v[60:61], s[42:43], 1.0 op_sel_hi:[1,0,0]
	s_nop 1
	v_rcp_f32_e32 v60, v60
	v_rcp_f32_e32 v61, v61
	v_mov_b32_dpp v45, v38 row_ror:2 row_mask:0xf bank_mask:0xf
	v_mov_b32_dpp v47, v39 row_ror:2 row_mask:0xf bank_mask:0xf
	v_mov_b32_dpp v42, v38 row_ror:1 row_mask:0xf bank_mask:0xf
	v_mov_b32_dpp v43, v39 row_ror:1 row_mask:0xf bank_mask:0xf
	v_cndmask_b32_e64 v73, v88, v47, s[6:7]
	v_cndmask_b32_e64 v72, v82, v45, s[6:7]
	v_cndmask_b32_e64 v49, v75, v43, s[8:9]
	v_cndmask_b32_e64 v48, v74, v42, s[8:9]
	v_pk_fma_f32 v[72:73], v[30:31], v[72:73], v[34:35]
	v_pk_mul_f32 v[58:59], v[36:37], v[36:37]
	v_pk_fma_f32 v[48:49], v[26:27], v[48:49], v[72:73]
	v_pk_mul_f32 v[58:59], v[58:59], s[38:39] op_sel_hi:[1,0]
	v_pk_fma_f32 v[72:73], v[60:61], s[52:53], v[56:57] op_sel_hi:[1,0,0]
	v_exp_f32_e32 v58, v58
	v_exp_f32_e32 v59, v59
	v_pk_fma_f32 v[72:73], v[60:61], v[72:73], s[56:57] op_sel_hi:[1,1,0]
	s_nop 0
	v_pk_fma_f32 v[72:73], v[60:61], v[72:73], s[62:63] op_sel_hi:[1,1,0]
	v_pk_fma_f32 v[38:39], v[22:23], v[38:39], v[48:49]
	v_pk_fma_f32 v[72:73], v[60:61], v[72:73], s[64:65] op_sel_hi:[1,1,0]
	v_pk_mul_f32 v[48:49], v[38:39], v[38:39]
	v_pk_mul_f32 v[60:61], v[60:61], v[72:73]
	v_pk_mul_f32 v[48:49], v[48:49], s[38:39] op_sel_hi:[1,0]
	v_pk_fma_f32 v[58:59], v[58:59], v[60:61], 0.5 op_sel_hi:[1,1,0] neg_lo:[1,0,0] neg_hi:[1,0,0]
	v_exp_f32_e32 v48, v48
	v_mul_f32_e64 v60, |v36|, v58
	v_mul_f32_e64 v61, |v37|, v59
	v_exp_f32_e32 v49, v49
	v_and_b32_e32 v58, 0x7fffffff, v38
	v_add_u32_e32 v136, v65, v50
	v_pk_fma_f32 v[36:37], v[36:37], 0.5, v[60:61] op_sel_hi:[1,0,1]
	v_and_b32_e32 v59, 0x7fffffff, v39
	v_pk_fma_f32 v[58:59], v[58:59], s[42:43], 1.0 op_sel_hi:[1,0,0]
	s_nop 0
	v_rcp_f32_e32 v58, v58
	v_rcp_f32_e32 v59, v59
	v_pk_mul_f32 v[36:37], v[52:53], v[36:37]
	s_nop 1
	v_cvt_pk_bf16_f32 v36, v36, v37
	v_pk_fma_f32 v[56:57], v[58:59], s[52:53], v[56:57] op_sel_hi:[1,0,0]
	s_nop 1
	v_pk_fma_f32 v[56:57], v[58:59], v[56:57], s[56:57] op_sel_hi:[1,1,0]
	s_nop 0
	v_pk_fma_f32 v[56:57], v[58:59], v[56:57], s[62:63] op_sel_hi:[1,1,0]
	s_nop 0
	v_pk_fma_f32 v[56:57], v[58:59], v[56:57], s[64:65] op_sel_hi:[1,1,0]
	s_nop 0
	v_pk_mul_f32 v[56:57], v[58:59], v[56:57]
	s_nop 0
	v_pk_fma_f32 v[48:49], v[48:49], v[56:57], 0.5 op_sel_hi:[1,1,0] neg_lo:[1,0,0] neg_hi:[1,0,0]
	s_nop 0
	v_mul_f32_e64 v56, |v38|, v48
	v_mul_f32_e64 v57, |v39|, v49
	v_pk_fma_f32 v[38:39], v[38:39], 0.5, v[56:57] op_sel_hi:[1,0,1]
	v_pk_mul_f32 v[38:39], v[54:55], v[38:39]
	s_nop 1
	v_cvt_pk_bf16_f32 v37, v38, v39
	v_lshl_add_u64 v[38:39], v[136:137], 1, s[26:27]
	global_store_dwordx2 v[38:39], v[36:37], off
	v_lshlrev_b32_e32 v36, 16, v92
	v_and_b32_e32 v37, 0xffff0000, v92
	v_lshlrev_b32_e32 v38, 16, v93
	v_and_b32_e32 v39, 0xffff0000, v93
	s_nop 1
	v_mov_b32_dpp v48, v36 row_ror:1 row_mask:0xf bank_mask:0xf
	v_mov_b32_dpp v49, v37 row_ror:1 row_mask:0xf bank_mask:0xf
	v_mov_b32_dpp v52, v38 row_ror:1 row_mask:0xf bank_mask:0xf
	v_mov_b32_dpp v53, v39 row_ror:1 row_mask:0xf bank_mask:0xf
	v_mov_b32_dpp v54, v36 row_ror:2 row_mask:0xf bank_mask:0xf
	v_mov_b32_dpp v56, v37 row_ror:2 row_mask:0xf bank_mask:0xf
	v_mov_b32_dpp v55, v38 row_ror:2 row_mask:0xf bank_mask:0xf
	v_mov_b32_dpp v57, v39 row_ror:2 row_mask:0xf bank_mask:0xf
	s_and_saveexec_b64 s[0:1], vcc
	s_cbranch_execz .LBB0_589
	v_add_u32_e32 v136, v50, v51
	v_lshl_add_u64 v[58:59], v[136:137], 2, s[28:29]
	global_store_dwordx4 v[58:59], v[36:39], off
.LBB0_589:
	s_or_b64 exec, exec, s[0:1]
	v_cndmask_b32_e64 v43, v43, v53, s[8:9]
	v_cndmask_b32_e64 v42, v42, v52, s[8:9]
	v_cndmask_b32_e64 v53, v71, v87, s[6:7]
	v_cndmask_b32_e64 v52, v70, v86, s[6:7]
	v_cndmask_b32_e64 v41, v41, v49, s[8:9]
	v_cndmask_b32_e64 v40, v40, v48, s[8:9]
	v_cndmask_b32_e64 v49, v68, v84, s[8:9]
	v_cndmask_b32_e64 v48, v63, v78, s[8:9]
	v_pk_fma_f32 v[10:11], v[10:11], v[52:53], v[14:15]
	v_cndmask_b32_e64 v59, v46, v56, s[6:7]
	v_cndmask_b32_e64 v58, v44, v54, s[6:7]
	v_pk_fma_f32 v[6:7], v[6:7], v[48:49], v[10:11]
	v_cndmask_b32_e64 v46, v45, v55, s[6:7]
	v_pk_fma_f32 v[2:3], v[2:3], v[18:19], v[6:7]
	v_pk_fma_f32 v[6:7], v[28:29], v[58:59], v[32:33]
	v_cndmask_b32_e64 v55, v69, v85, s[6:7]
	v_pk_fma_f32 v[6:7], v[24:25], v[40:41], v[6:7]
	v_cndmask_b32_e64 v54, v66, v79, s[6:7]
	v_pk_fma_f32 v[6:7], v[20:21], v[36:37], v[6:7]
	v_pk_fma_f32 v[8:9], v[8:9], v[54:55], v[12:13]
	v_and_b32_e32 v13, 0x7fffffff, v7
	v_and_b32_e32 v12, 0x7fffffff, v6
	v_pk_fma_f32 v[12:13], v[12:13], s[42:43], 1.0 op_sel_hi:[1,0,0]
	v_cndmask_b32_e64 v45, v67, v83, s[8:9]
	v_rcp_f32_e32 v12, v12
	v_rcp_f32_e32 v13, v13
	v_cndmask_b32_e64 v44, v62, v77, s[8:9]
	v_pk_fma_f32 v[4:5], v[4:5], v[44:45], v[8:9]
	v_pk_mul_f32 v[10:11], v[6:7], v[6:7]
	v_mov_b64_e32 v[14:15], s[54:55]
	v_pk_fma_f32 v[0:1], v[0:1], v[16:17], v[4:5]
	v_pk_mul_f32 v[10:11], v[10:11], s[38:39] op_sel_hi:[1,0]
	v_pk_fma_f32 v[16:17], v[12:13], s[52:53], v[14:15] op_sel_hi:[1,0,0]
	v_exp_f32_e32 v10, v10
	v_exp_f32_e32 v11, v11
	v_pk_fma_f32 v[16:17], v[12:13], v[16:17], s[56:57] op_sel_hi:[1,1,0]
	v_cndmask_b32_e64 v47, v47, v57, s[6:7]
	v_pk_fma_f32 v[16:17], v[12:13], v[16:17], s[62:63] op_sel_hi:[1,1,0]
	v_pk_fma_f32 v[4:5], v[30:31], v[46:47], v[34:35]
	v_pk_fma_f32 v[16:17], v[12:13], v[16:17], s[64:65] op_sel_hi:[1,1,0]
	v_pk_fma_f32 v[4:5], v[26:27], v[42:43], v[4:5]
	v_pk_mul_f32 v[12:13], v[12:13], v[16:17]
	s_nop 0
	v_pk_fma_f32 v[10:11], v[10:11], v[12:13], 0.5 op_sel_hi:[1,1,0] neg_lo:[1,0,0] neg_hi:[1,0,0]
	v_pk_fma_f32 v[4:5], v[22:23], v[38:39], v[4:5]
	v_mul_f32_e64 v12, |v6|, v10
	v_mul_f32_e64 v13, |v7|, v11
	v_pk_mul_f32 v[8:9], v[4:5], v[4:5]
	s_nop 0
	v_and_b32_e32 v10, 0x7fffffff, v4
	v_pk_mul_f32 v[8:9], v[8:9], s[38:39] op_sel_hi:[1,0]
	v_pk_fma_f32 v[6:7], v[6:7], 0.5, v[12:13] op_sel_hi:[1,0,1]
	v_and_b32_e32 v11, 0x7fffffff, v5
	v_pk_fma_f32 v[10:11], v[10:11], s[42:43], 1.0 op_sel_hi:[1,0,0]
	v_exp_f32_e32 v8, v8
	v_rcp_f32_e32 v10, v10
	v_rcp_f32_e32 v11, v11
	v_exp_f32_e32 v9, v9
	s_nop 0
	v_pk_mul_f32 v[0:1], v[0:1], v[6:7]
	v_pk_fma_f32 v[12:13], v[10:11], s[52:53], v[14:15] op_sel_hi:[1,0,0]
	v_add_u32_e32 v136, v76, v50
	v_pk_fma_f32 v[12:13], v[10:11], v[12:13], s[56:57] op_sel_hi:[1,1,0]
	v_cvt_pk_bf16_f32 v0, v0, v1
	s_mov_b64 s[0:1], -1
	v_pk_fma_f32 v[12:13], v[10:11], v[12:13], s[62:63] op_sel_hi:[1,1,0]
	s_nop 0
	v_pk_fma_f32 v[12:13], v[10:11], v[12:13], s[64:65] op_sel_hi:[1,1,0]
	s_nop 0
	v_pk_mul_f32 v[10:11], v[10:11], v[12:13]
	s_nop 0
	v_pk_fma_f32 v[8:9], v[8:9], v[10:11], 0.5 op_sel_hi:[1,1,0] neg_lo:[1,0,0] neg_hi:[1,0,0]
	s_nop 0
	v_mul_f32_e64 v10, |v4|, v8
	v_mul_f32_e64 v11, |v5|, v9
	v_pk_fma_f32 v[4:5], v[4:5], 0.5, v[10:11] op_sel_hi:[1,0,1]
	v_pk_mul_f32 v[2:3], v[2:3], v[4:5]
	s_andn2_b64 vcc, exec, s[4:5]
	v_cvt_pk_bf16_f32 v1, v2, v3
	v_lshl_add_u64 v[2:3], v[136:137], 1, s[26:27]
	global_store_dwordx2 v[2:3], v[0:1], off
	s_cbranch_vccnz .LBB0_542
	s_andn2_b64 vcc, exec, s[18:19]
	s_cbranch_vccnz .LBB0_541
	s_barrier
	s_branch .LBB0_541

; __device__ __forceinline__ f32x4 gelu4(f32x4 v) { const f32x2 a = gelu_pk((f32x2){v[0], v[1]}), b = gelu_pk((f32x2){v[2], v[3]}); return (f32x4){a.x, a.y, b.x, b.y}; }
; __device__ __forceinline__ f32x4 ror1v(f32x4 v) { return (f32x4){dpp_ror1(v[0]), dpp_ror1(v[1]), dpp_ror1(v[2]), dpp_ror1(v[3])}; }
; __device__ __forceinline__ f32x4 ror2v(f32x4 v) { return (f32x4){dpp_ror2(v[0]), dpp_ror2(v[1]), dpp_ror2(v[2]), dpp_ror2(v[3])}; }
; __device__ __forceinline__ u32x2 pack4(f32x4 v) { return (u32x2){pk2(v[0], v[1]), pk2(v[2], v[3])}; }
; __device__ __forceinline__ f32x2 gelu_pk(f32x2 v) {
;     const f32x2 av = __builtin_elementwise_abs(v), d = av * 0.2316418882f + 1.0f;
;     f32x2 t; t.x = __builtin_amdgcn_rcpf(d.x); t.y = __builtin_amdgcn_rcpf(d.y);
;     f32x2 q = t * 0.5307027145f + (-0.7265760135f); q = q * t + 0.7107068705f; q = q * t + (-0.142248368f); q = q * t + 0.127414796f; q = q * t;
;     const f32x2 s = (v * v) * (-0.72134752044f);
;     f32x2 e; e.x = __builtin_amdgcn_exp2f(s.x); e.y = __builtin_amdgcn_exp2f(s.y);
;     const f32x2 m = v * (q * e), r = v - m;
;     f32x2 o; o.x = v.x < 0.f ? m.x : r.x; o.y = v.y < 0.f ? m.y : r.y; return o;
;     __device__ __forceinline__ void operator()(AccRef acc, const Unit& u, int wr, int wc, int fr, int fq) const {
;     ...
;                     const f32x4 wg0 = *(const f32x4*)(cw + jn), wg1 = *(const f32x4*)(cw + (UPN + jn)), wg2 = *(const f32x4*)(cw + (2 * UPN + jn)), bg = *(const f32x4*)(cb + jn);
;                     f32x4 pg1 = (f32x4){0.f, 0.f, 0.f, 0.f}, pg2 = pg1;
; #pragma unroll
;                     for (int m = 0; m < 4; ++m) { const int row = rowg + m * 16 + fr;
;                         const f32x4 ag = unpack4(pa[ai][0][m][n]);
;                         const f32x4 rg1 = ror1v(ag), rg2 = ror2v(ag);
;                         const f32x4 g1 = fr >= 1 ? rg1 : pg1, g2 = fr >= 2 ? rg2 : pg2;
;                         if (m == 0 && fr < 2) *(f32x4*)(edge + (unsigned)((grp * 4 + fr) * UPN + jn)) = ag;
;                         if (m == 3 && fr >= 14) *(f32x4*)(edge + (unsigned)((grp * 4 + (fr - 12)) * UPN + jn)) = ag;
;                         const f32x4 o = gelu4(bg + wg0 * g2 + wg1 * g1 + wg2 * ag) * cu[m];
;                         if (!(m == 0 && fr < 2)) *(u32x2*)(act + (unsigned)(row * DFF + jn)) = pack4(o);
;                         pg1 = rg1; pg2 = rg2; }
.LBB0_1410:
	s_or_b64 exec, exec, s[0:1]
	v_mov_b32_e32 v45, v137
	v_add_u32_e32 v136, 0x1600, v44
	v_lshlrev_b64 v[32:33], 2, v[44:45]
	v_lshl_add_u64 v[58:59], v[136:137], 2, s[20:21]
	v_add_u32_e32 v136, 0x2c00, v44
	v_lshl_add_u64 v[56:57], s[20:21], 0, v[32:33]
	v_lshl_add_u64 v[62:63], v[136:137], 2, s[20:21]
	v_lshl_add_u64 v[64:65], s[22:23], 0, v[32:33]
	global_load_dwordx4 v[28:31], v[56:57], off
	global_load_dwordx4 v[20:23], v[58:59], off
	global_load_dwordx4 v[24:27], v[62:63], off
	global_load_dwordx4 v[32:35], v[64:65], off
	v_lshlrev_b32_e32 v40, 16, v190
	v_and_b32_e32 v41, 0xffff0000, v190
	v_lshlrev_b32_e32 v42, 16, v189
	v_and_b32_e32 v43, 0xffff0000, v189
	s_nop 1
	v_cmp_lt_i32_e64 s[8:9], 0, v166
	v_cmp_lt_i32_e64 s[6:7], 1, v166
	v_mov_b32_dpp v70, v40 row_ror:1 row_mask:0xf bank_mask:0xf
	v_mov_b32_dpp v71, v41 row_ror:1 row_mask:0xf bank_mask:0xf
	v_mov_b32_dpp v72, v42 row_ror:1 row_mask:0xf bank_mask:0xf
	v_mov_b32_dpp v73, v43 row_ror:1 row_mask:0xf bank_mask:0xf
	v_mov_b32_dpp v74, v40 row_ror:2 row_mask:0xf bank_mask:0xf
	v_mov_b32_dpp v75, v41 row_ror:2 row_mask:0xf bank_mask:0xf
	v_mov_b32_dpp v76, v42 row_ror:2 row_mask:0xf bank_mask:0xf
	v_mov_b32_dpp v77, v43 row_ror:2 row_mask:0xf bank_mask:0xf
	s_and_saveexec_b64 s[0:1], s[10:11]
	s_xor_b64 s[74:75], exec, s[0:1]
	s_cbranch_execz .LBB0_1412
	v_cndmask_b32_e64 v213, 0, v204, s[6:7]
	v_cndmask_b32_e64 v212, 0, v201, s[6:7]
	v_cndmask_b32_e64 v211, 0, v196, s[8:9]
	v_cndmask_b32_e64 v210, 0, v192, s[8:9]
	s_waitcnt vmcnt(4)
	v_pk_fma_f32 v[212:213], v[10:11], v[212:213], v[14:15]
	v_cndmask_b32_e64 v215, 0, v197, s[6:7]
	v_pk_fma_f32 v[210:211], v[2:3], v[210:211], v[212:213]
	v_cndmask_b32_e64 v214, 0, v193, s[6:7]
	v_pk_fma_f32 v[38:39], v[6:7], v[38:39], v[210:211]
	s_waitcnt vmcnt(0)
	v_pk_fma_f32 v[210:211], v[28:29], v[74:75], v[32:33]
	v_cndmask_b32_e64 v209, 0, v194, s[8:9]
	v_pk_fma_f32 v[210:211], v[20:21], v[70:71], v[210:211]
	v_cndmask_b32_e64 v208, 0, v191, s[8:9]
	v_pk_fma_f32 v[40:41], v[24:25], v[40:41], v[210:211]
	v_pk_fma_f32 v[214:215], v[8:9], v[214:215], v[12:13]
	v_and_b32_e32 v213, 0x7fffffff, v41
	v_and_b32_e32 v212, 0x7fffffff, v40
	v_pk_fma_f32 v[212:213], v[212:213], s[52:53], 1.0 op_sel_hi:[1,0,0]
	v_pk_fma_f32 v[208:209], v[0:1], v[208:209], v[214:215]
	v_rcp_f32_e32 v212, v212
	v_rcp_f32_e32 v213, v213
	v_pk_mul_f32 v[210:211], v[40:41], v[40:41]
	v_mov_b64_e32 v[214:215], s[56:57]
	v_pk_mul_f32 v[210:211], v[210:211], s[42:43] op_sel_hi:[1,0]
	v_pk_fma_f32 v[216:217], v[212:213], s[54:55], v[214:215] op_sel_hi:[1,0,0]
	v_exp_f32_e32 v210, v210
	v_exp_f32_e32 v211, v211
	v_pk_fma_f32 v[216:217], v[212:213], v[216:217], s[58:59] op_sel_hi:[1,1,0]
	v_pk_fma_f32 v[36:37], v[4:5], v[36:37], v[208:209]
	v_pk_fma_f32 v[216:217], v[212:213], v[216:217], s[60:61] op_sel_hi:[1,1,0]
	v_pk_fma_f32 v[208:209], v[30:31], v[76:77], v[34:35]
	v_pk_fma_f32 v[216:217], v[212:213], v[216:217], s[62:63] op_sel_hi:[1,1,0]
	v_pk_fma_f32 v[208:209], v[22:23], v[72:73], v[208:209]
	v_pk_mul_f32 v[212:213], v[212:213], v[216:217]
	s_nop 0
	v_pk_fma_f32 v[210:211], v[210:211], v[212:213], 0.5 op_sel_hi:[1,1,0] neg_lo:[1,0,0] neg_hi:[1,0,0]
	v_pk_fma_f32 v[42:43], v[26:27], v[42:43], v[208:209]
	v_mul_f32_e64 v212, |v40|, v210
	v_mul_f32_e64 v213, |v41|, v211
	v_pk_mul_f32 v[208:209], v[42:43], v[42:43]
	s_nop 0
	v_and_b32_e32 v210, 0x7fffffff, v42
	v_pk_mul_f32 v[208:209], v[208:209], s[42:43] op_sel_hi:[1,0]
	v_pk_fma_f32 v[40:41], v[40:41], 0.5, v[212:213] op_sel_hi:[1,0,1]
	v_and_b32_e32 v211, 0x7fffffff, v43
	v_pk_fma_f32 v[210:211], v[210:211], s[52:53], 1.0 op_sel_hi:[1,0,0]
	v_exp_f32_e32 v208, v208
	v_rcp_f32_e32 v210, v210
	v_rcp_f32_e32 v211, v211
	v_exp_f32_e32 v209, v209
	s_nop 0
	v_pk_mul_f32 v[36:37], v[36:37], v[40:41]
	v_pk_fma_f32 v[212:213], v[210:211], s[54:55], v[214:215] op_sel_hi:[1,0,0]
	v_cvt_pk_bf16_f32 v36, v36, v37
	s_nop 0
	v_pk_fma_f32 v[212:213], v[210:211], v[212:213], s[58:59] op_sel_hi:[1,1,0]
	s_nop 0
	v_pk_fma_f32 v[212:213], v[210:211], v[212:213], s[60:61] op_sel_hi:[1,1,0]
	s_nop 0
	v_pk_fma_f32 v[212:213], v[210:211], v[212:213], s[62:63] op_sel_hi:[1,1,0]
	s_nop 0
	v_pk_mul_f32 v[210:211], v[210:211], v[212:213]
	s_nop 0
	v_pk_fma_f32 v[208:209], v[208:209], v[210:211], 0.5 op_sel_hi:[1,1,0] neg_lo:[1,0,0] neg_hi:[1,0,0]
	s_nop 0
	v_mul_f32_e64 v210, |v42|, v208
	v_mul_f32_e64 v211, |v43|, v209
	v_pk_fma_f32 v[42:43], v[42:43], 0.5, v[210:211] op_sel_hi:[1,0,1]
	v_pk_mul_f32 v[38:39], v[38:39], v[42:43]
	s_nop 0
	v_cvt_pk_bf16_f32 v37, v38, v39
	v_mad_u64_u32 v[38:39], s[0:1], v146, s86, v[44:45]
	v_mov_b32_e32 v39, v137
	v_lshl_add_u64 v[38:39], v[38:39], 1, s[26:27]
	global_store_dwordx2 v[38:39], v[36:37], off

; __device__ __forceinline__ f32x2 gelu_pk(f32x2 v) {
;     const f32x2 av = __builtin_elementwise_abs(v), d = av * 0.2316418882f + 1.0f;
;     f32x2 t; t.x = __builtin_amdgcn_rcpf(d.x); t.y = __builtin_amdgcn_rcpf(d.y);
;     __device__ __forceinline__ void operator()(AccRef acc, const Unit& u, int wr, int wc, int fr, int fq) const {
;     ...
;                     const f32x4 wu0 = *(const f32x4*)(cw + (DFF + jn)), wu1 = *(const f32x4*)(cw + (UPN + DFF + jn)), wu2 = *(const f32x4*)(cw + (2 * UPN + DFF + jn)), bu = *(const f32x4*)(cb + (DFF + jn));
;                     f32x4 pu1 = (f32x4){0.f, 0.f, 0.f, 0.f}, pu2 = pu1;
; #pragma unroll
;                     for (int m = 0; m < 4; ++m) {
;                         const f32x4 au = unpack4(pa[ai][1][m][n]);
;                         const f32x4 ru1 = ror1v(au), ru2 = ror2v(au);
;                         const f32x4 u1 = fr >= 1 ? ru1 : pu1, u2 = fr >= 2 ? ru2 : pu2;
;                         if (m == 0 && fr < 2) *(f32x4*)(edge + (unsigned)((grp * 4 + fr) * UPN + DFF + jn)) = au;
;                         if (m == 3 && fr >= 14) *(f32x4*)(edge + (unsigned)((grp * 4 + (fr - 12)) * UPN + DFF + jn)) = au;
;                         cu[m] = bu + wu0 * u2 + wu1 * u1 + wu2 * au;
;                         pu1 = ru1; pu2 = ru2; }
;                 }
;                 {
;                     const f32x4 wg0 = *(const f32x4*)(cw + jn), wg1 = *(const f32x4*)(cw + (UPN + jn)), wg2 = *(const f32x4*)(cw + (2 * UPN + jn)), bg = *(const f32x4*)(cb + jn);
;                     f32x4 pg1 = (f32x4){0.f, 0.f, 0.f, 0.f}, pg2 = pg1;
; #pragma unroll
;                     for (int m = 0; m < 4; ++m) { const int row = rowg + m * 16 + fr;
;                         const f32x4 ag = unpack4(pa[ai][0][m][n]);
;                         const f32x4 rg1 = ror1v(ag), rg2 = ror2v(ag);
;                         const f32x4 g1 = fr >= 1 ? rg1 : pg1, g2 = fr >= 2 ? rg2 : pg2;
;                         if (m == 0 && fr < 2) *(f32x4*)(edge + (unsigned)((grp * 4 + fr) * UPN + jn)) = ag;
;                         if (m == 3 && fr >= 14) *(f32x4*)(edge + (unsigned)((grp * 4 + (fr - 12)) * UPN + jn)) = ag;
;                         const f32x4 o = gelu4(bg + wg0 * g2 + wg1 * g1 + wg2 * ag) * cu[m];
;                         if (!(m == 0 && fr < 2)) *(u32x2*)(act + (unsigned)(row * DFF + jn)) = pack4(o);
;                         pg1 = rg1; pg2 = rg2; }
.LBB0_1414:
	s_or_b64 exec, exec, s[0:1]
	s_nop 0
	v_cndmask_b32_e64 v41, v204, v206, s[6:7]
	v_cndmask_b32_e64 v40, v201, v205, s[6:7]
	v_cndmask_b32_e64 v43, v197, v203, s[6:7]
	v_cndmask_b32_e64 v42, v193, v199, s[6:7]
	v_cndmask_b32_e64 v37, v194, v200, s[8:9]
	v_cndmask_b32_e64 v36, v191, v195, s[8:9]
	v_cndmask_b32_e64 v39, v196, v202, s[8:9]
	v_cndmask_b32_e64 v38, v192, v198, s[8:9]
	s_waitcnt vmcnt(4)
	v_pk_fma_f32 v[42:43], v[8:9], v[42:43], v[12:13]
	v_pk_fma_f32 v[40:41], v[10:11], v[40:41], v[14:15]
	v_pk_fma_f32 v[36:37], v[0:1], v[36:37], v[42:43]
	v_pk_fma_f32 v[38:39], v[2:3], v[38:39], v[40:41]
	v_pk_fma_f32 v[36:37], v[4:5], v[68:69], v[36:37]
	v_pk_fma_f32 v[38:39], v[6:7], v[66:67], v[38:39]
	v_cndmask_b32_e64 v67, v206, v180, s[6:7]
	v_cndmask_b32_e64 v66, v205, v179, s[6:7]
	v_cndmask_b32_e64 v69, v203, v178, s[6:7]
	v_cndmask_b32_e64 v68, v199, v87, s[6:7]
	v_cndmask_b32_e64 v41, v200, v95, s[8:9]
	v_cndmask_b32_e64 v40, v195, v85, s[8:9]
	v_cndmask_b32_e64 v43, v202, v177, s[8:9]
	v_cndmask_b32_e64 v42, v198, v86, s[8:9]
	v_pk_fma_f32 v[68:69], v[8:9], v[68:69], v[12:13]
	v_pk_fma_f32 v[66:67], v[10:11], v[66:67], v[14:15]
	v_pk_fma_f32 v[40:41], v[0:1], v[40:41], v[68:69]
	v_pk_fma_f32 v[42:43], v[2:3], v[42:43], v[66:67]
	v_pk_fma_f32 v[66:67], v[4:5], v[60:61], v[40:41]
	v_pk_fma_f32 v[68:69], v[6:7], v[46:47], v[42:43]
	v_lshlrev_b32_e32 v40, 16, v94
	v_and_b32_e32 v41, 0xffff0000, v94
	v_lshlrev_b32_e32 v42, 16, v93
	v_and_b32_e32 v43, 0xffff0000, v93
	s_nop 1
	v_mov_b32_dpp v93, v40 row_ror:1 row_mask:0xf bank_mask:0xf
	v_mov_b32_dpp v94, v41 row_ror:1 row_mask:0xf bank_mask:0xf
	v_mov_b32_dpp v191, v40 row_ror:2 row_mask:0xf bank_mask:0xf
	v_mov_b32_dpp v192, v41 row_ror:2 row_mask:0xf bank_mask:0xf
	v_cndmask_b32_e64 v61, v71, v94, s[8:9]
	v_cndmask_b32_e64 v60, v70, v93, s[8:9]
	v_cndmask_b32_e64 v71, v75, v192, s[6:7]
	v_cndmask_b32_e64 v70, v74, v191, s[6:7]
	s_waitcnt vmcnt(2)
	v_pk_fma_f32 v[70:71], v[28:29], v[70:71], v[32:33]
	s_nop 1
	v_pk_fma_f32 v[60:61], v[20:21], v[60:61], v[70:71]
	s_nop 1
	v_pk_fma_f32 v[40:41], v[24:25], v[40:41], v[60:61]
	s_nop 1
	v_and_b32_e32 v71, 0x7fffffff, v41
	v_and_b32_e32 v70, 0x7fffffff, v40
	s_nop 1
	v_pk_fma_f32 v[70:71], v[70:71], s[52:53], 1.0 op_sel_hi:[1,0,0]
	v_mov_b32_dpp v189, v42 row_ror:1 row_mask:0xf bank_mask:0xf
	v_mov_b32_dpp v190, v43 row_ror:1 row_mask:0xf bank_mask:0xf
	v_mov_b32_dpp v193, v42 row_ror:2 row_mask:0xf bank_mask:0xf
	v_mov_b32_dpp v194, v43 row_ror:2 row_mask:0xf bank_mask:0xf
	v_rcp_f32_e32 v70, v70
	v_rcp_f32_e32 v71, v71
	v_cndmask_b32_e64 v47, v73, v190, s[8:9]
	v_cndmask_b32_e64 v46, v72, v189, s[8:9]
	v_cndmask_b32_e64 v73, v77, v194, s[6:7]
	v_cndmask_b32_e64 v72, v76, v193, s[6:7]
	v_pk_fma_f32 v[72:73], v[30:31], v[72:73], v[34:35]
	v_pk_mul_f32 v[60:61], v[40:41], v[40:41]
	v_pk_fma_f32 v[46:47], v[22:23], v[46:47], v[72:73]
	v_mov_b64_e32 v[72:73], s[56:57]
	v_pk_mul_f32 v[60:61], v[60:61], s[42:43] op_sel_hi:[1,0]
	v_pk_fma_f32 v[74:75], v[70:71], s[54:55], v[72:73] op_sel_hi:[1,0,0]
	v_exp_f32_e32 v60, v60
	v_exp_f32_e32 v61, v61
	v_pk_fma_f32 v[74:75], v[70:71], v[74:75], s[58:59] op_sel_hi:[1,1,0]
	s_nop 0
	v_pk_fma_f32 v[74:75], v[70:71], v[74:75], s[60:61] op_sel_hi:[1,1,0]
	v_pk_fma_f32 v[42:43], v[26:27], v[42:43], v[46:47]
	v_pk_fma_f32 v[74:75], v[70:71], v[74:75], s[62:63] op_sel_hi:[1,1,0]
	v_pk_mul_f32 v[46:47], v[42:43], v[42:43]
	v_pk_mul_f32 v[70:71], v[70:71], v[74:75]
	v_pk_mul_f32 v[46:47], v[46:47], s[42:43] op_sel_hi:[1,0]
	v_pk_fma_f32 v[60:61], v[60:61], v[70:71], 0.5 op_sel_hi:[1,1,0] neg_lo:[1,0,0] neg_hi:[1,0,0]
	v_exp_f32_e32 v46, v46
	v_mul_f32_e64 v70, |v40|, v60
	v_mul_f32_e64 v71, |v41|, v61
	v_exp_f32_e32 v47, v47
	v_and_b32_e32 v60, 0x7fffffff, v42
	v_mul_lo_u32 v45, v148, s86
	v_pk_fma_f32 v[40:41], v[40:41], 0.5, v[70:71] op_sel_hi:[1,0,1]
	v_and_b32_e32 v61, 0x7fffffff, v43
	v_pk_fma_f32 v[60:61], v[60:61], s[52:53], 1.0 op_sel_hi:[1,0,0]
	s_nop 0
	v_rcp_f32_e32 v60, v60
	v_rcp_f32_e32 v61, v61
	v_pk_mul_f32 v[36:37], v[36:37], v[40:41]
	v_add_u32_e32 v136, v45, v44
	v_cvt_pk_bf16_f32 v36, v36, v37
	v_pk_fma_f32 v[70:71], v[60:61], s[54:55], v[72:73] op_sel_hi:[1,0,0]
	s_nop 1
	v_pk_fma_f32 v[70:71], v[60:61], v[70:71], s[58:59] op_sel_hi:[1,1,0]
	s_nop 1
	v_pk_fma_f32 v[70:71], v[60:61], v[70:71], s[60:61] op_sel_hi:[1,1,0]
	v_add_u32_e32 v148, 0xb000, v45
	v_pk_fma_f32 v[70:71], v[60:61], v[70:71], s[62:63] op_sel_hi:[1,1,0]
	s_nop 0
	v_pk_mul_f32 v[60:61], v[60:61], v[70:71]
	s_nop 0
	v_pk_fma_f32 v[46:47], v[46:47], v[60:61], 0.5 op_sel_hi:[1,1,0] neg_lo:[1,0,0] neg_hi:[1,0,0]
	s_nop 0
	v_mul_f32_e64 v60, |v42|, v46
	v_mul_f32_e64 v61, |v43|, v47
	v_pk_fma_f32 v[42:43], v[42:43], 0.5, v[60:61] op_sel_hi:[1,0,1]
	v_pk_mul_f32 v[38:39], v[38:39], v[42:43]
	s_nop 1
	v_cvt_pk_bf16_f32 v37, v38, v39
	v_lshl_add_u64 v[38:39], v[136:137], 1, s[26:27]
	global_store_dwordx2 v[38:39], v[36:37], off
	v_lshlrev_b32_e32 v36, 16, v92
	v_and_b32_e32 v37, 0xffff0000, v92
	v_lshlrev_b32_e32 v38, 16, v91
	v_mov_b32_dpp v43, v36 row_ror:2 row_mask:0xf bank_mask:0xf
	v_mov_b32_dpp v60, v37 row_ror:2 row_mask:0xf bank_mask:0xf
	v_mov_b32_dpp v40, v36 row_ror:1 row_mask:0xf bank_mask:0xf
	v_mov_b32_dpp v41, v37 row_ror:1 row_mask:0xf bank_mask:0xf
	v_cndmask_b32_e64 v77, v192, v60, s[6:7]
	v_cndmask_b32_e64 v76, v191, v43, s[6:7]
	v_cndmask_b32_e64 v75, v94, v41, s[8:9]
	v_cndmask_b32_e64 v74, v93, v40, s[8:9]
	v_pk_fma_f32 v[76:77], v[28:29], v[76:77], v[32:33]
	v_and_b32_e32 v39, 0xffff0000, v91
	v_pk_fma_f32 v[74:75], v[20:21], v[74:75], v[76:77]
	s_nop 1
	v_pk_fma_f32 v[36:37], v[24:25], v[36:37], v[74:75]
; __device__ __forceinline__ f32x4 gelu4(f32x4 v) { const f32x2 a = gelu_pk((f32x2){v[0], v[1]}), b = gelu_pk((f32x2){v[2], v[3]}); return (f32x4){a.x, a.y, b.x, b.y}; }
; __device__ __forceinline__ f32x4 ror1v(f32x4 v) { return (f32x4){dpp_ror1(v[0]), dpp_ror1(v[1]), dpp_ror1(v[2]), dpp_ror1(v[3])}; }
; __device__ __forceinline__ f32x4 ror2v(f32x4 v) { return (f32x4){dpp_ror2(v[0]), dpp_ror2(v[1]), dpp_ror2(v[2]), dpp_ror2(v[3])}; }
; __device__ __forceinline__ u32x2 pack4(f32x4 v) { return (u32x2){pk2(v[0], v[1]), pk2(v[2], v[3])}; }
; __device__ __forceinline__ f32x2 gelu_pk(f32x2 v) {
;     const f32x2 av = __builtin_elementwise_abs(v), d = av * 0.2316418882f + 1.0f;
;     f32x2 t; t.x = __builtin_amdgcn_rcpf(d.x); t.y = __builtin_amdgcn_rcpf(d.y);
;     f32x2 q = t * 0.5307027145f + (-0.7265760135f); q = q * t + 0.7107068705f; q = q * t + (-0.142248368f); q = q * t + 0.127414796f; q = q * t;
;     const f32x2 s = (v * v) * (-0.72134752044f);
;     f32x2 e; e.x = __builtin_amdgcn_exp2f(s.x); e.y = __builtin_amdgcn_exp2f(s.y);
;     const f32x2 m = v * (q * e), r = v - m;
;     f32x2 o; o.x = v.x < 0.f ? m.x : r.x; o.y = v.y < 0.f ? m.y : r.y; return o;
;     __device__ __forceinline__ void operator()(AccRef acc, const Unit& u, int wr, int wc, int fr, int fq) const {
;     ...
;                     const f32x4 wg0 = *(const f32x4*)(cw + jn), wg1 = *(const f32x4*)(cw + (UPN + jn)), wg2 = *(const f32x4*)(cw + (2 * UPN + jn)), bg = *(const f32x4*)(cb + jn);
;                     f32x4 pg1 = (f32x4){0.f, 0.f, 0.f, 0.f}, pg2 = pg1;
; #pragma unroll
;                     for (int m = 0; m < 4; ++m) { const int row = rowg + m * 16 + fr;
;                         const f32x4 ag = unpack4(pa[ai][0][m][n]);
;                         const f32x4 rg1 = ror1v(ag), rg2 = ror2v(ag);
;                         const f32x4 g1 = fr >= 1 ? rg1 : pg1, g2 = fr >= 2 ? rg2 : pg2;
;                         if (m == 0 && fr < 2) *(f32x4*)(edge + (unsigned)((grp * 4 + fr) * UPN + jn)) = ag;
;                         if (m == 3 && fr >= 14) *(f32x4*)(edge + (unsigned)((grp * 4 + (fr - 12)) * UPN + jn)) = ag;
;                         const f32x4 o = gelu4(bg + wg0 * g2 + wg1 * g1 + wg2 * ag) * cu[m];
;                         if (!(m == 0 && fr < 2)) *(u32x2*)(act + (unsigned)(row * DFF + jn)) = pack4(o);
;                         pg1 = rg1; pg2 = rg2; }
	s_nop 1
	v_and_b32_e32 v77, 0x7fffffff, v37
	v_and_b32_e32 v76, 0x7fffffff, v36
	v_pk_fma_f32 v[76:77], v[76:77], s[52:53], 1.0 op_sel_hi:[1,0,0]
	s_nop 1
	v_rcp_f32_e32 v76, v76
	v_rcp_f32_e32 v77, v77
	v_mov_b32_dpp v46, v38 row_ror:2 row_mask:0xf bank_mask:0xf
	v_mov_b32_dpp v61, v39 row_ror:2 row_mask:0xf bank_mask:0xf
	v_mov_b32_dpp v42, v38 row_ror:1 row_mask:0xf bank_mask:0xf
	v_mov_b32_dpp v47, v39 row_ror:1 row_mask:0xf bank_mask:0xf
	v_cndmask_b32_e64 v93, v194, v61, s[6:7]
	v_cndmask_b32_e64 v92, v193, v46, s[6:7]
	v_cndmask_b32_e64 v71, v190, v47, s[8:9]
	v_cndmask_b32_e64 v70, v189, v42, s[8:9]
	v_pk_fma_f32 v[92:93], v[30:31], v[92:93], v[34:35]
	v_pk_mul_f32 v[74:75], v[36:37], v[36:37]
	v_pk_fma_f32 v[70:71], v[22:23], v[70:71], v[92:93]
	v_pk_mul_f32 v[74:75], v[74:75], s[42:43] op_sel_hi:[1,0]
	v_pk_fma_f32 v[92:93], v[76:77], s[54:55], v[72:73] op_sel_hi:[1,0,0]
	v_exp_f32_e32 v74, v74
	v_exp_f32_e32 v75, v75
	v_pk_fma_f32 v[92:93], v[76:77], v[92:93], s[58:59] op_sel_hi:[1,1,0]
	s_nop 0
	v_pk_fma_f32 v[92:93], v[76:77], v[92:93], s[60:61] op_sel_hi:[1,1,0]
	v_pk_fma_f32 v[38:39], v[26:27], v[38:39], v[70:71]
	v_pk_fma_f32 v[92:93], v[76:77], v[92:93], s[62:63] op_sel_hi:[1,1,0]
	v_pk_mul_f32 v[70:71], v[38:39], v[38:39]
	v_pk_mul_f32 v[76:77], v[76:77], v[92:93]
	v_pk_mul_f32 v[70:71], v[70:71], s[42:43] op_sel_hi:[1,0]
	v_pk_fma_f32 v[74:75], v[74:75], v[76:77], 0.5 op_sel_hi:[1,1,0] neg_lo:[1,0,0] neg_hi:[1,0,0]
	v_exp_f32_e32 v70, v70
	v_mul_f32_e64 v76, |v36|, v74
	v_mul_f32_e64 v77, |v37|, v75
	v_exp_f32_e32 v71, v71
	v_and_b32_e32 v74, 0x7fffffff, v38
	v_add_u32_e32 v136, v148, v44
	v_pk_fma_f32 v[36:37], v[36:37], 0.5, v[76:77] op_sel_hi:[1,0,1]
	v_and_b32_e32 v75, 0x7fffffff, v39
	v_pk_fma_f32 v[74:75], v[74:75], s[52:53], 1.0 op_sel_hi:[1,0,0]
	s_nop 0
	v_rcp_f32_e32 v74, v74
	v_rcp_f32_e32 v75, v75
	v_pk_mul_f32 v[36:37], v[66:67], v[36:37]
	s_nop 1
	v_cvt_pk_bf16_f32 v36, v36, v37
	v_pk_fma_f32 v[72:73], v[74:75], s[54:55], v[72:73] op_sel_hi:[1,0,0]
	s_nop 1
	v_pk_fma_f32 v[72:73], v[74:75], v[72:73], s[58:59] op_sel_hi:[1,1,0]
	s_nop 0
	v_pk_fma_f32 v[72:73], v[74:75], v[72:73], s[60:61] op_sel_hi:[1,1,0]
	s_nop 0
	v_pk_fma_f32 v[72:73], v[74:75], v[72:73], s[62:63] op_sel_hi:[1,1,0]
	s_nop 0
	v_pk_mul_f32 v[72:73], v[74:75], v[72:73]
	s_nop 0
	v_pk_fma_f32 v[70:71], v[70:71], v[72:73], 0.5 op_sel_hi:[1,1,0] neg_lo:[1,0,0] neg_hi:[1,0,0]
	s_nop 0
	v_mul_f32_e64 v72, |v38|, v70
	v_mul_f32_e64 v73, |v39|, v71
	v_pk_fma_f32 v[38:39], v[38:39], 0.5, v[72:73] op_sel_hi:[1,0,1]
	v_pk_mul_f32 v[38:39], v[68:69], v[38:39]
	s_nop 1
	v_cvt_pk_bf16_f32 v37, v38, v39
	v_lshl_add_u64 v[38:39], v[136:137], 1, s[26:27]
	global_store_dwordx2 v[38:39], v[36:37], off
	v_lshlrev_b32_e32 v36, 16, v82
	v_and_b32_e32 v37, 0xffff0000, v82
	v_lshlrev_b32_e32 v38, 16, v83
	v_and_b32_e32 v39, 0xffff0000, v83
	s_nop 1
	v_mov_b32_dpp v66, v36 row_ror:1 row_mask:0xf bank_mask:0xf
	v_mov_b32_dpp v67, v37 row_ror:1 row_mask:0xf bank_mask:0xf
	v_mov_b32_dpp v68, v38 row_ror:1 row_mask:0xf bank_mask:0xf
	v_mov_b32_dpp v71, v39 row_ror:1 row_mask:0xf bank_mask:0xf
	v_mov_b32_dpp v69, v36 row_ror:2 row_mask:0xf bank_mask:0xf
	v_mov_b32_dpp v72, v37 row_ror:2 row_mask:0xf bank_mask:0xf
	v_mov_b32_dpp v70, v38 row_ror:2 row_mask:0xf bank_mask:0xf
	v_mov_b32_dpp v73, v39 row_ror:2 row_mask:0xf bank_mask:0xf
	s_and_saveexec_b64 s[0:1], vcc
	s_cbranch_execz .LBB0_1416
	v_add_u32_e32 v136, v152, v44
	v_lshl_add_u64 v[74:75], v[136:137], 2, s[28:29]
	global_store_dwordx4 v[74:75], v[36:39], off
; __device__ __forceinline__ f32x2 gelu_pk(f32x2 v) {
;     __device__ __forceinline__ void operator()(AccRef acc, const Unit& u, int wr, int wc, int fr, int fq) const {
;     ...
;             for (int n = 0; n < 2; ++n) { const unsigned jn = (unsigned)(j0 + 4 * n);
;                 f32x4 cu[4];
;                 {
;                     const f32x4 wu0 = *(const f32x4*)(cw + (DFF + jn)), wu1 = *(const f32x4*)(cw + (UPN + DFF + jn)), wu2 = *(const f32x4*)(cw + (2 * UPN + DFF + jn)), bu = *(const f32x4*)(cb + (DFF + jn));
;                     f32x4 pu1 = (f32x4){0.f, 0.f, 0.f, 0.f}, pu2 = pu1;
; #pragma unroll
;                     for (int m = 0; m < 4; ++m) {
;                         const f32x4 au = unpack4(pa[ai][1][m][n]);
;                         const f32x4 ru1 = ror1v(au), ru2 = ror2v(au);
;                         const f32x4 u1 = fr >= 1 ? ru1 : pu1, u2 = fr >= 2 ? ru2 : pu2;
;                         if (m == 0 && fr < 2) *(f32x4*)(edge + (unsigned)((grp * 4 + fr) * UPN + DFF + jn)) = au;
;                         if (m == 3 && fr >= 14) *(f32x4*)(edge + (unsigned)((grp * 4 + (fr - 12)) * UPN + DFF + jn)) = au;
;                         cu[m] = bu + wu0 * u2 + wu1 * u1 + wu2 * au;
;                         pu1 = ru1; pu2 = ru2; }
;                 }
;                 {
;                     const f32x4 wg0 = *(const f32x4*)(cw + jn), wg1 = *(const f32x4*)(cw + (UPN + jn)), wg2 = *(const f32x4*)(cw + (2 * UPN + jn)), bg = *(const f32x4*)(cb + jn);
;                     f32x4 pg1 = (f32x4){0.f, 0.f, 0.f, 0.f}, pg2 = pg1;
; #pragma unroll
;                     for (int m = 0; m < 4; ++m) { const int row = rowg + m * 16 + fr;
;                         const f32x4 ag = unpack4(pa[ai][0][m][n]);
;                         const f32x4 rg1 = ror1v(ag), rg2 = ror2v(ag);
;                         const f32x4 g1 = fr >= 1 ? rg1 : pg1, g2 = fr >= 2 ? rg2 : pg2;
;                         if (m == 0 && fr < 2) *(f32x4*)(edge + (unsigned)((grp * 4 + fr) * UPN + jn)) = ag;
;                         if (m == 3 && fr >= 14) *(f32x4*)(edge + (unsigned)((grp * 4 + (fr - 12)) * UPN + jn)) = ag;
;                         const f32x4 o = gelu4(bg + wg0 * g2 + wg1 * g1 + wg2 * ag) * cu[m];
;                         if (!(m == 0 && fr < 2)) *(u32x2*)(act + (unsigned)(row * DFF + jn)) = pack4(o);
;                         pg1 = rg1; pg2 = rg2; }
.LBB0_1416:
	s_or_b64 exec, exec, s[0:1]
	v_cndmask_b32_e64 v74, v42, v68, s[8:9]
	v_cndmask_b32_e64 v40, v40, v66, s[8:9]
	v_cndmask_b32_e64 v66, v43, v69, s[6:7]
	v_cndmask_b32_e64 v69, v180, v188, s[6:7]
	v_cndmask_b32_e64 v68, v179, v187, s[6:7]
	v_cndmask_b32_e64 v41, v41, v67, s[8:9]
	v_cndmask_b32_e64 v67, v60, v72, s[6:7]
	v_cndmask_b32_e64 v43, v61, v73, s[6:7]
	v_cndmask_b32_e64 v61, v177, v185, s[8:9]
	v_cndmask_b32_e64 v60, v86, v182, s[8:9]
	v_pk_fma_f32 v[10:11], v[10:11], v[68:69], v[14:15]
	v_cndmask_b32_e64 v75, v47, v71, s[8:9]
	v_pk_fma_f32 v[2:3], v[2:3], v[60:61], v[10:11]
	v_cndmask_b32_e64 v42, v46, v70, s[6:7]
	v_pk_fma_f32 v[2:3], v[6:7], v[18:19], v[2:3]
	v_pk_fma_f32 v[6:7], v[28:29], v[66:67], v[32:33]
	v_cndmask_b32_e64 v71, v178, v186, s[6:7]
	v_pk_fma_f32 v[6:7], v[20:21], v[40:41], v[6:7]
	v_cndmask_b32_e64 v70, v87, v183, s[6:7]
	v_pk_fma_f32 v[6:7], v[24:25], v[36:37], v[6:7]
	v_pk_fma_f32 v[8:9], v[8:9], v[70:71], v[12:13]
	v_and_b32_e32 v13, 0x7fffffff, v7
	v_and_b32_e32 v12, 0x7fffffff, v6
	v_pk_fma_f32 v[12:13], v[12:13], s[52:53], 1.0 op_sel_hi:[1,0,0]
	v_cndmask_b32_e64 v47, v95, v184, s[8:9]
	v_rcp_f32_e32 v12, v12
	v_rcp_f32_e32 v13, v13
	v_cndmask_b32_e64 v46, v85, v181, s[8:9]
	v_pk_fma_f32 v[0:1], v[0:1], v[46:47], v[8:9]
	v_pk_mul_f32 v[10:11], v[6:7], v[6:7]
	v_mov_b64_e32 v[14:15], s[56:57]
	v_pk_fma_f32 v[0:1], v[4:5], v[16:17], v[0:1]
	v_pk_mul_f32 v[10:11], v[10:11], s[42:43] op_sel_hi:[1,0]
	v_pk_fma_f32 v[16:17], v[12:13], s[54:55], v[14:15] op_sel_hi:[1,0,0]
	v_exp_f32_e32 v10, v10
	v_exp_f32_e32 v11, v11
	v_pk_fma_f32 v[16:17], v[12:13], v[16:17], s[58:59] op_sel_hi:[1,1,0]
	v_pk_fma_f32 v[4:5], v[30:31], v[42:43], v[34:35]
	v_pk_fma_f32 v[16:17], v[12:13], v[16:17], s[60:61] op_sel_hi:[1,1,0]
	v_pk_fma_f32 v[4:5], v[22:23], v[74:75], v[4:5]
	v_pk_fma_f32 v[16:17], v[12:13], v[16:17], s[62:63] op_sel_hi:[1,1,0]
	s_nop 0
	v_pk_mul_f32 v[12:13], v[12:13], v[16:17]
	v_pk_fma_f32 v[4:5], v[26:27], v[38:39], v[4:5]
	v_pk_fma_f32 v[10:11], v[10:11], v[12:13], 0.5 op_sel_hi:[1,1,0] neg_lo:[1,0,0] neg_hi:[1,0,0]
	v_pk_mul_f32 v[8:9], v[4:5], v[4:5]
	v_mul_f32_e64 v12, |v6|, v10
	v_mul_f32_e64 v13, |v7|, v11
	v_pk_mul_f32 v[8:9], v[8:9], s[42:43] op_sel_hi:[1,0]
	s_nop 0
	v_and_b32_e32 v10, 0x7fffffff, v4
	v_exp_f32_e32 v8, v8
	v_pk_fma_f32 v[6:7], v[6:7], 0.5, v[12:13] op_sel_hi:[1,0,1]
	v_and_b32_e32 v11, 0x7fffffff, v5
	v_pk_fma_f32 v[10:11], v[10:11], s[52:53], 1.0 op_sel_hi:[1,0,0]
	v_exp_f32_e32 v9, v9
	v_rcp_f32_e32 v10, v10
	v_rcp_f32_e32 v11, v11
	v_add_u32_e32 v177, 0xb000, v148
	v_pk_mul_f32 v[0:1], v[0:1], v[6:7]
	v_pk_fma_f32 v[12:13], v[10:11], s[54:55], v[14:15] op_sel_hi:[1,0,0]
	v_add_u32_e32 v136, v177, v44
	v_pk_fma_f32 v[12:13], v[10:11], v[12:13], s[58:59] op_sel_hi:[1,1,0]
	v_cvt_pk_bf16_f32 v0, v0, v1
	v_lshlrev_b32_e32 v36, 16, v173
	v_pk_fma_f32 v[12:13], v[10:11], v[12:13], s[60:61] op_sel_hi:[1,1,0]
	v_and_b32_e32 v37, 0xffff0000, v173
	v_pk_fma_f32 v[12:13], v[10:11], v[12:13], s[62:63] op_sel_hi:[1,1,0]
	v_lshlrev_b32_e32 v38, 16, v174
	v_pk_mul_f32 v[10:11], v[10:11], v[12:13]
	v_and_b32_e32 v39, 0xffff0000, v174
	v_pk_fma_f32 v[8:9], v[8:9], v[10:11], 0.5 op_sel_hi:[1,1,0] neg_lo:[1,0,0] neg_hi:[1,0,0]
	s_nop 1
	v_mul_f32_e64 v10, |v4|, v8
	v_mul_f32_e64 v11, |v5|, v9
	v_pk_fma_f32 v[4:5], v[4:5], 0.5, v[10:11] op_sel_hi:[1,0,1]
	v_pk_mul_f32 v[2:3], v[2:3], v[4:5]
	s_nop 1
	v_cvt_pk_bf16_f32 v1, v2, v3
	v_lshl_add_u64 v[2:3], v[136:137], 1, s[26:27]
	v_add_u32_e32 v136, 0xb04, v44
	v_lshlrev_b64 v[12:13], 2, v[136:137]
	v_add_u32_e32 v136, 0x2104, v44
	v_lshl_add_u64 v[66:67], v[136:137], 2, s[20:21]
	v_add_u32_e32 v136, 0x3704, v44
	global_store_dwordx2 v[2:3], v[0:1], off
	v_lshl_add_u64 v[60:61], s[20:21], 0, v[12:13]
	v_lshl_add_u64 v[68:69], v[136:137], 2, s[20:21]
	v_lshl_add_u64 v[70:71], s[22:23], 0, v[12:13]
	global_load_dwordx4 v[8:11], v[60:61], off
	global_load_dwordx4 v[0:3], v[66:67], off
	global_load_dwordx4 v[4:7], v[68:69], off
	global_load_dwordx4 v[12:15], v[70:71], off
	s_nop 1
	v_or_b32_e32 v46, 4, v44
	v_mov_b32_dpp v193, v36 row_ror:1 row_mask:0xf bank_mask:0xf
	v_mov_b32_dpp v199, v37 row_ror:1 row_mask:0xf bank_mask:0xf
	v_mov_b32_dpp v196, v38 row_ror:1 row_mask:0xf bank_mask:0xf
	v_mov_b32_dpp v202, v39 row_ror:1 row_mask:0xf bank_mask:0xf
	v_mov_b32_dpp v197, v36 row_ror:2 row_mask:0xf bank_mask:0xf
	v_mov_b32_dpp v203, v37 row_ror:2 row_mask:0xf bank_mask:0xf
	v_mov_b32_dpp v205, v38 row_ror:2 row_mask:0xf bank_mask:0xf
	v_mov_b32_dpp v207, v39 row_ror:2 row_mask:0xf bank_mask:0xf
	s_and_saveexec_b64 s[0:1], s[12:13]
	s_cbranch_execz .LBB0_1418
	v_add_u32_e32 v136, v46, v84
	v_lshl_add_u64 v[16:17], v[136:137], 2, s[28:29]
	global_store_dwordx4 v[16:17], v[36:39], off

; __device__ __forceinline__ f32x4 gelu4(f32x4 v) { const f32x2 a = gelu_pk((f32x2){v[0], v[1]}), b = gelu_pk((f32x2){v[2], v[3]}); return (f32x4){a.x, a.y, b.x, b.y}; }
; __device__ __forceinline__ f32x4 ror1v(f32x4 v) { return (f32x4){dpp_ror1(v[0]), dpp_ror1(v[1]), dpp_ror1(v[2]), dpp_ror1(v[3])}; }
; __device__ __forceinline__ f32x4 ror2v(f32x4 v) { return (f32x4){dpp_ror2(v[0]), dpp_ror2(v[1]), dpp_ror2(v[2]), dpp_ror2(v[3])}; }
; __device__ __forceinline__ u32x2 pack4(f32x4 v) { return (u32x2){pk2(v[0], v[1]), pk2(v[2], v[3])}; }
; __device__ __forceinline__ f32x2 gelu_pk(f32x2 v) {
;     const f32x2 av = __builtin_elementwise_abs(v), d = av * 0.2316418882f + 1.0f;
;     f32x2 t; t.x = __builtin_amdgcn_rcpf(d.x); t.y = __builtin_amdgcn_rcpf(d.y);
;     f32x2 q = t * 0.5307027145f + (-0.7265760135f); q = q * t + 0.7107068705f; q = q * t + (-0.142248368f); q = q * t + 0.127414796f; q = q * t;
;     const f32x2 s = (v * v) * (-0.72134752044f);
;     f32x2 e; e.x = __builtin_amdgcn_exp2f(s.x); e.y = __builtin_amdgcn_exp2f(s.y);
;     const f32x2 m = v * (q * e), r = v - m;
;     f32x2 o; o.x = v.x < 0.f ? m.x : r.x; o.y = v.y < 0.f ? m.y : r.y; return o;
;     __device__ __forceinline__ void operator()(AccRef acc, const Unit& u, int wr, int wc, int fr, int fq) const {
;     ...
;                     const f32x4 wg0 = *(const f32x4*)(cw + jn), wg1 = *(const f32x4*)(cw + (UPN + jn)), wg2 = *(const f32x4*)(cw + (2 * UPN + jn)), bg = *(const f32x4*)(cb + jn);
;                     f32x4 pg1 = (f32x4){0.f, 0.f, 0.f, 0.f}, pg2 = pg1;
; #pragma unroll
;                     for (int m = 0; m < 4; ++m) { const int row = rowg + m * 16 + fr;
;                         const f32x4 ag = unpack4(pa[ai][0][m][n]);
;                         const f32x4 rg1 = ror1v(ag), rg2 = ror2v(ag);
;                         const f32x4 g1 = fr >= 1 ? rg1 : pg1, g2 = fr >= 2 ? rg2 : pg2;
;                         if (m == 0 && fr < 2) *(f32x4*)(edge + (unsigned)((grp * 4 + fr) * UPN + jn)) = ag;
;                         if (m == 3 && fr >= 14) *(f32x4*)(edge + (unsigned)((grp * 4 + (fr - 12)) * UPN + jn)) = ag;
;                         const f32x4 o = gelu4(bg + wg0 * g2 + wg1 * g1 + wg2 * ag) * cu[m];
;                         if (!(m == 0 && fr < 2)) *(u32x2*)(act + (unsigned)(row * DFF + jn)) = pack4(o);
;                         pg1 = rg1; pg2 = rg2; }
.LBB0_1420:
	s_or_b64 exec, exec, s[0:1]
	v_mov_b32_e32 v47, v137
	v_add_u32_e32 v136, 0x1604, v44
	v_lshlrev_b64 v[32:33], 2, v[46:47]
	v_lshl_add_u64 v[74:75], v[136:137], 2, s[20:21]
	v_add_u32_e32 v136, 0x2c04, v44
	v_lshl_add_u64 v[72:73], s[20:21], 0, v[32:33]
	v_lshl_add_u64 v[76:77], v[136:137], 2, s[20:21]
	v_lshl_add_u64 v[78:79], s[22:23], 0, v[32:33]
	global_load_dwordx4 v[28:31], v[72:73], off
	global_load_dwordx4 v[20:23], v[74:75], off
	global_load_dwordx4 v[24:27], v[76:77], off
	global_load_dwordx4 v[32:35], v[78:79], off
	v_lshlrev_b32_e32 v40, 16, v172
	v_and_b32_e32 v41, 0xffff0000, v172
	v_lshlrev_b32_e32 v42, 16, v171
	v_and_b32_e32 v43, 0xffff0000, v171
	s_nop 1
	v_mov_b32_dpp v88, v40 row_ror:1 row_mask:0xf bank_mask:0xf
	v_mov_b32_dpp v89, v41 row_ror:1 row_mask:0xf bank_mask:0xf
	v_mov_b32_dpp v90, v42 row_ror:1 row_mask:0xf bank_mask:0xf
	v_mov_b32_dpp v91, v43 row_ror:1 row_mask:0xf bank_mask:0xf
	v_mov_b32_dpp v92, v40 row_ror:2 row_mask:0xf bank_mask:0xf
	v_mov_b32_dpp v93, v41 row_ror:2 row_mask:0xf bank_mask:0xf
	v_mov_b32_dpp v94, v42 row_ror:2 row_mask:0xf bank_mask:0xf
	v_mov_b32_dpp v95, v43 row_ror:2 row_mask:0xf bank_mask:0xf
	s_and_saveexec_b64 s[0:1], s[10:11]
	s_xor_b64 s[74:75], exec, s[0:1]
	s_cbranch_execz .LBB0_1422
	v_cndmask_b32_e64 v213, 0, v207, s[6:7]
	v_cndmask_b32_e64 v212, 0, v205, s[6:7]
	v_cndmask_b32_e64 v211, 0, v202, s[8:9]
	v_cndmask_b32_e64 v210, 0, v196, s[8:9]
	s_waitcnt vmcnt(4)
	v_pk_fma_f32 v[212:213], v[10:11], v[212:213], v[14:15]
	v_cndmask_b32_e64 v215, 0, v203, s[6:7]
	v_pk_fma_f32 v[210:211], v[2:3], v[210:211], v[212:213]
	v_cndmask_b32_e64 v214, 0, v197, s[6:7]
	v_pk_fma_f32 v[38:39], v[6:7], v[38:39], v[210:211]
	s_waitcnt vmcnt(0)
	v_pk_fma_f32 v[210:211], v[28:29], v[92:93], v[32:33]
	v_cndmask_b32_e64 v209, 0, v199, s[8:9]
	v_pk_fma_f32 v[210:211], v[20:21], v[88:89], v[210:211]
	v_cndmask_b32_e64 v208, 0, v193, s[8:9]
	v_pk_fma_f32 v[40:41], v[24:25], v[40:41], v[210:211]
	v_pk_fma_f32 v[214:215], v[8:9], v[214:215], v[12:13]
	v_and_b32_e32 v213, 0x7fffffff, v41
	v_and_b32_e32 v212, 0x7fffffff, v40
	v_pk_fma_f32 v[212:213], v[212:213], s[52:53], 1.0 op_sel_hi:[1,0,0]
	v_pk_fma_f32 v[208:209], v[0:1], v[208:209], v[214:215]
	v_rcp_f32_e32 v212, v212
	v_rcp_f32_e32 v213, v213
	v_pk_mul_f32 v[210:211], v[40:41], v[40:41]
	v_mov_b64_e32 v[214:215], s[56:57]
	v_pk_mul_f32 v[210:211], v[210:211], s[42:43] op_sel_hi:[1,0]
	v_pk_fma_f32 v[216:217], v[212:213], s[54:55], v[214:215] op_sel_hi:[1,0,0]
	v_exp_f32_e32 v210, v210
	v_exp_f32_e32 v211, v211
	v_pk_fma_f32 v[216:217], v[212:213], v[216:217], s[58:59] op_sel_hi:[1,1,0]
	v_pk_fma_f32 v[36:37], v[4:5], v[36:37], v[208:209]
	v_pk_fma_f32 v[216:217], v[212:213], v[216:217], s[60:61] op_sel_hi:[1,1,0]
	v_pk_fma_f32 v[208:209], v[30:31], v[94:95], v[34:35]
	v_pk_fma_f32 v[216:217], v[212:213], v[216:217], s[62:63] op_sel_hi:[1,1,0]
	v_pk_fma_f32 v[208:209], v[22:23], v[90:91], v[208:209]
	v_pk_mul_f32 v[212:213], v[212:213], v[216:217]
	s_nop 0
	v_pk_fma_f32 v[210:211], v[210:211], v[212:213], 0.5 op_sel_hi:[1,1,0] neg_lo:[1,0,0] neg_hi:[1,0,0]
	v_pk_fma_f32 v[42:43], v[26:27], v[42:43], v[208:209]
	v_mul_f32_e64 v212, |v40|, v210
	v_mul_f32_e64 v213, |v41|, v211
	v_pk_mul_f32 v[208:209], v[42:43], v[42:43]
	s_nop 0
	v_and_b32_e32 v210, 0x7fffffff, v42
	v_pk_mul_f32 v[208:209], v[208:209], s[42:43] op_sel_hi:[1,0]
	v_pk_fma_f32 v[40:41], v[40:41], 0.5, v[212:213] op_sel_hi:[1,0,1]
	v_and_b32_e32 v211, 0x7fffffff, v43
	v_pk_fma_f32 v[210:211], v[210:211], s[52:53], 1.0 op_sel_hi:[1,0,0]
	v_exp_f32_e32 v208, v208
	v_rcp_f32_e32 v210, v210
	v_rcp_f32_e32 v211, v211
	v_exp_f32_e32 v209, v209
	s_nop 0
	v_pk_mul_f32 v[36:37], v[36:37], v[40:41]
	v_pk_fma_f32 v[212:213], v[210:211], s[54:55], v[214:215] op_sel_hi:[1,0,0]
	v_cvt_pk_bf16_f32 v36, v36, v37
	s_nop 0
	v_pk_fma_f32 v[212:213], v[210:211], v[212:213], s[58:59] op_sel_hi:[1,1,0]
	s_nop 0
	v_pk_fma_f32 v[212:213], v[210:211], v[212:213], s[60:61] op_sel_hi:[1,1,0]
	s_nop 0
	v_pk_fma_f32 v[212:213], v[210:211], v[212:213], s[62:63] op_sel_hi:[1,1,0]
	s_nop 0
	v_pk_mul_f32 v[210:211], v[210:211], v[212:213]
	s_nop 0
	v_pk_fma_f32 v[208:209], v[208:209], v[210:211], 0.5 op_sel_hi:[1,1,0] neg_lo:[1,0,0] neg_hi:[1,0,0]
	s_nop 0
	v_mul_f32_e64 v210, |v42|, v208
	v_mul_f32_e64 v211, |v43|, v209
	v_pk_fma_f32 v[42:43], v[42:43], 0.5, v[210:211] op_sel_hi:[1,0,1]
	v_pk_mul_f32 v[38:39], v[38:39], v[42:43]
	s_nop 0
	v_cvt_pk_bf16_f32 v37, v38, v39
	v_mad_u64_u32 v[38:39], s[0:1], v146, s86, v[46:47]
	v_mov_b32_e32 v39, v137
	v_lshl_add_u64 v[38:39], v[38:39], 1, s[26:27]
	global_store_dwordx2 v[38:39], v[36:37], off

; __device__ __forceinline__ f32x2 gelu_pk(f32x2 v) {
;     const f32x2 av = __builtin_elementwise_abs(v), d = av * 0.2316418882f + 1.0f;
;     f32x2 t; t.x = __builtin_amdgcn_rcpf(d.x); t.y = __builtin_amdgcn_rcpf(d.y);
;     __device__ __forceinline__ void operator()(AccRef acc, const Unit& u, int wr, int wc, int fr, int fq) const {
;     ...
;                     const f32x4 wu0 = *(const f32x4*)(cw + (DFF + jn)), wu1 = *(const f32x4*)(cw + (UPN + DFF + jn)), wu2 = *(const f32x4*)(cw + (2 * UPN + DFF + jn)), bu = *(const f32x4*)(cb + (DFF + jn));
;                     f32x4 pu1 = (f32x4){0.f, 0.f, 0.f, 0.f}, pu2 = pu1;
; #pragma unroll
;                     for (int m = 0; m < 4; ++m) {
;                         const f32x4 au = unpack4(pa[ai][1][m][n]);
;                         const f32x4 ru1 = ror1v(au), ru2 = ror2v(au);
;                         const f32x4 u1 = fr >= 1 ? ru1 : pu1, u2 = fr >= 2 ? ru2 : pu2;
;                         if (m == 0 && fr < 2) *(f32x4*)(edge + (unsigned)((grp * 4 + fr) * UPN + DFF + jn)) = au;
;                         if (m == 3 && fr >= 14) *(f32x4*)(edge + (unsigned)((grp * 4 + (fr - 12)) * UPN + DFF + jn)) = au;
;                         cu[m] = bu + wu0 * u2 + wu1 * u1 + wu2 * au;
;                         pu1 = ru1; pu2 = ru2; }
;                 }
;                 {
;                     const f32x4 wg0 = *(const f32x4*)(cw + jn), wg1 = *(const f32x4*)(cw + (UPN + jn)), wg2 = *(const f32x4*)(cw + (2 * UPN + jn)), bg = *(const f32x4*)(cb + jn);
;                     f32x4 pg1 = (f32x4){0.f, 0.f, 0.f, 0.f}, pg2 = pg1;
; #pragma unroll
;                     for (int m = 0; m < 4; ++m) { const int row = rowg + m * 16 + fr;
;                         const f32x4 ag = unpack4(pa[ai][0][m][n]);
;                         const f32x4 rg1 = ror1v(ag), rg2 = ror2v(ag);
;                         const f32x4 g1 = fr >= 1 ? rg1 : pg1, g2 = fr >= 2 ? rg2 : pg2;
;                         if (m == 0 && fr < 2) *(f32x4*)(edge + (unsigned)((grp * 4 + fr) * UPN + jn)) = ag;
;                         if (m == 3 && fr >= 14) *(f32x4*)(edge + (unsigned)((grp * 4 + (fr - 12)) * UPN + jn)) = ag;
;                         const f32x4 o = gelu4(bg + wg0 * g2 + wg1 * g1 + wg2 * ag) * cu[m];
;                         if (!(m == 0 && fr < 2)) *(u32x2*)(act + (unsigned)(row * DFF + jn)) = pack4(o);
;                         pg1 = rg1; pg2 = rg2; }
.LBB0_1424:
	s_or_b64 exec, exec, s[0:1]
	s_nop 0
	v_cndmask_b32_e64 v41, v207, v206, s[6:7]
	v_cndmask_b32_e64 v40, v205, v204, s[6:7]
	v_cndmask_b32_e64 v43, v203, v201, s[6:7]
	v_cndmask_b32_e64 v42, v197, v195, s[6:7]
	v_cndmask_b32_e64 v37, v199, v198, s[8:9]
	v_cndmask_b32_e64 v36, v193, v192, s[8:9]
	v_cndmask_b32_e64 v39, v202, v200, s[8:9]
	v_cndmask_b32_e64 v38, v196, v194, s[8:9]
	s_waitcnt vmcnt(4)
	v_pk_fma_f32 v[42:43], v[8:9], v[42:43], v[12:13]
	v_pk_fma_f32 v[40:41], v[10:11], v[40:41], v[14:15]
	v_pk_fma_f32 v[36:37], v[0:1], v[36:37], v[42:43]
	v_pk_fma_f32 v[38:39], v[2:3], v[38:39], v[40:41]
	v_pk_fma_f32 v[36:37], v[4:5], v[86:87], v[36:37]
	v_pk_fma_f32 v[38:39], v[6:7], v[84:85], v[38:39]
	v_cndmask_b32_e64 v85, v206, v183, s[6:7]
	v_cndmask_b32_e64 v84, v204, v182, s[6:7]
	v_cndmask_b32_e64 v87, v201, v181, s[6:7]
	v_cndmask_b32_e64 v86, v195, v178, s[6:7]
	v_cndmask_b32_e64 v41, v198, v179, s[8:9]
	v_cndmask_b32_e64 v40, v192, v173, s[8:9]
	v_cndmask_b32_e64 v43, v200, v180, s[8:9]
	v_cndmask_b32_e64 v42, v194, v174, s[8:9]
	v_pk_fma_f32 v[86:87], v[8:9], v[86:87], v[12:13]
	v_pk_fma_f32 v[84:85], v[10:11], v[84:85], v[14:15]
	v_pk_fma_f32 v[40:41], v[0:1], v[40:41], v[86:87]
	v_pk_fma_f32 v[42:43], v[2:3], v[42:43], v[84:85]
	v_pk_fma_f32 v[82:83], v[4:5], v[82:83], v[40:41]
	v_pk_fma_f32 v[84:85], v[6:7], v[80:81], v[42:43]
	v_lshlrev_b32_e32 v40, 16, v170
	v_and_b32_e32 v41, 0xffff0000, v170
	v_lshlrev_b32_e32 v42, 16, v169
	v_and_b32_e32 v43, 0xffff0000, v169
	s_nop 1
	v_mov_b32_dpp v146, v40 row_ror:1 row_mask:0xf bank_mask:0xf
	v_mov_b32_dpp v169, v41 row_ror:1 row_mask:0xf bank_mask:0xf
	v_mov_b32_dpp v172, v40 row_ror:2 row_mask:0xf bank_mask:0xf
	v_mov_b32_dpp v175, v41 row_ror:2 row_mask:0xf bank_mask:0xf
	v_cndmask_b32_e64 v87, v89, v169, s[8:9]
	v_cndmask_b32_e64 v86, v88, v146, s[8:9]
	v_cndmask_b32_e64 v89, v93, v175, s[6:7]
	v_cndmask_b32_e64 v88, v92, v172, s[6:7]
	s_waitcnt vmcnt(2)
	v_pk_fma_f32 v[88:89], v[28:29], v[88:89], v[32:33]
	s_nop 1
	v_pk_fma_f32 v[86:87], v[20:21], v[86:87], v[88:89]
	s_nop 1
	v_pk_fma_f32 v[40:41], v[24:25], v[40:41], v[86:87]
	s_nop 1
	v_and_b32_e32 v89, 0x7fffffff, v41
	v_and_b32_e32 v88, 0x7fffffff, v40
	s_nop 1
	v_pk_fma_f32 v[88:89], v[88:89], s[52:53], 1.0 op_sel_hi:[1,0,0]
	v_mov_b32_dpp v170, v42 row_ror:1 row_mask:0xf bank_mask:0xf
	v_mov_b32_dpp v171, v43 row_ror:1 row_mask:0xf bank_mask:0xf
	v_mov_b32_dpp v192, v42 row_ror:2 row_mask:0xf bank_mask:0xf
	v_mov_b32_dpp v193, v43 row_ror:2 row_mask:0xf bank_mask:0xf
	v_rcp_f32_e32 v88, v88
	v_rcp_f32_e32 v89, v89
	v_cndmask_b32_e64 v81, v91, v171, s[8:9]
	v_cndmask_b32_e64 v80, v90, v170, s[8:9]
	v_cndmask_b32_e64 v91, v95, v193, s[6:7]
	v_cndmask_b32_e64 v90, v94, v192, s[6:7]
	v_pk_fma_f32 v[90:91], v[30:31], v[90:91], v[34:35]
	v_pk_mul_f32 v[86:87], v[40:41], v[40:41]
	v_pk_fma_f32 v[80:81], v[22:23], v[80:81], v[90:91]
	v_mov_b64_e32 v[90:91], s[56:57]
	v_pk_mul_f32 v[86:87], v[86:87], s[42:43] op_sel_hi:[1,0]
	v_pk_fma_f32 v[92:93], v[88:89], s[54:55], v[90:91] op_sel_hi:[1,0,0]
	v_exp_f32_e32 v86, v86
	v_exp_f32_e32 v87, v87
	v_pk_fma_f32 v[92:93], v[88:89], v[92:93], s[58:59] op_sel_hi:[1,1,0]
	s_nop 0
	v_pk_fma_f32 v[92:93], v[88:89], v[92:93], s[60:61] op_sel_hi:[1,1,0]
	v_pk_fma_f32 v[42:43], v[26:27], v[42:43], v[80:81]
	v_pk_fma_f32 v[92:93], v[88:89], v[92:93], s[62:63] op_sel_hi:[1,1,0]
	v_pk_mul_f32 v[80:81], v[42:43], v[42:43]
	v_pk_mul_f32 v[88:89], v[88:89], v[92:93]
	v_pk_mul_f32 v[80:81], v[80:81], s[42:43] op_sel_hi:[1,0]
	v_pk_fma_f32 v[86:87], v[86:87], v[88:89], 0.5 op_sel_hi:[1,1,0] neg_lo:[1,0,0] neg_hi:[1,0,0]
	v_exp_f32_e32 v80, v80
	v_mul_f32_e64 v88, |v40|, v86
	v_mul_f32_e64 v89, |v41|, v87
	v_exp_f32_e32 v81, v81
	v_and_b32_e32 v86, 0x7fffffff, v42
	v_add_u32_e32 v136, v45, v46
	v_pk_fma_f32 v[40:41], v[40:41], 0.5, v[88:89] op_sel_hi:[1,0,1]
	v_and_b32_e32 v87, 0x7fffffff, v43
	v_pk_fma_f32 v[86:87], v[86:87], s[52:53], 1.0 op_sel_hi:[1,0,0]
	s_nop 0
	v_rcp_f32_e32 v86, v86
	v_rcp_f32_e32 v87, v87
	v_pk_mul_f32 v[36:37], v[36:37], v[40:41]
	s_nop 1
	v_cvt_pk_bf16_f32 v36, v36, v37
	v_pk_fma_f32 v[88:89], v[86:87], s[54:55], v[90:91] op_sel_hi:[1,0,0]
	s_nop 1
	v_pk_fma_f32 v[88:89], v[86:87], v[88:89], s[58:59] op_sel_hi:[1,1,0]
	s_nop 1
	v_pk_fma_f32 v[88:89], v[86:87], v[88:89], s[60:61] op_sel_hi:[1,1,0]
	s_nop 1
	v_pk_fma_f32 v[88:89], v[86:87], v[88:89], s[62:63] op_sel_hi:[1,1,0]
	s_nop 0
	v_pk_mul_f32 v[86:87], v[86:87], v[88:89]
	s_nop 0
	v_pk_fma_f32 v[80:81], v[80:81], v[86:87], 0.5 op_sel_hi:[1,1,0] neg_lo:[1,0,0] neg_hi:[1,0,0]
	s_nop 0
	v_mul_f32_e64 v86, |v42|, v80
	v_mul_f32_e64 v87, |v43|, v81
	v_pk_fma_f32 v[42:43], v[42:43], 0.5, v[86:87] op_sel_hi:[1,0,1]
	v_pk_mul_f32 v[38:39], v[38:39], v[42:43]
	s_nop 1
	v_cvt_pk_bf16_f32 v37, v38, v39
	v_lshl_add_u64 v[38:39], v[136:137], 1, s[26:27]
	global_store_dwordx2 v[38:39], v[36:37], off
	v_lshlrev_b32_e32 v36, 16, v167
	v_and_b32_e32 v37, 0xffff0000, v167
	v_lshlrev_b32_e32 v38, 16, v168
	v_mov_b32_dpp v43, v36 row_ror:2 row_mask:0xf bank_mask:0xf
	v_mov_b32_dpp v80, v37 row_ror:2 row_mask:0xf bank_mask:0xf
	v_mov_b32_dpp v40, v36 row_ror:1 row_mask:0xf bank_mask:0xf
	v_mov_b32_dpp v41, v37 row_ror:1 row_mask:0xf bank_mask:0xf
	v_cndmask_b32_e64 v93, v175, v80, s[6:7]
	v_cndmask_b32_e64 v92, v172, v43, s[6:7]
	v_cndmask_b32_e64 v89, v169, v41, s[8:9]
	v_cndmask_b32_e64 v88, v146, v40, s[8:9]
	v_pk_fma_f32 v[92:93], v[28:29], v[92:93], v[32:33]
	v_and_b32_e32 v39, 0xffff0000, v168
	v_pk_fma_f32 v[88:89], v[20:21], v[88:89], v[92:93]
	s_nop 1
	v_pk_fma_f32 v[36:37], v[24:25], v[36:37], v[88:89]
	s_nop 1
; __device__ __forceinline__ f32x4 gelu4(f32x4 v) { const f32x2 a = gelu_pk((f32x2){v[0], v[1]}), b = gelu_pk((f32x2){v[2], v[3]}); return (f32x4){a.x, a.y, b.x, b.y}; }
; __device__ __forceinline__ f32x4 ror1v(f32x4 v) { return (f32x4){dpp_ror1(v[0]), dpp_ror1(v[1]), dpp_ror1(v[2]), dpp_ror1(v[3])}; }
; __device__ __forceinline__ f32x4 ror2v(f32x4 v) { return (f32x4){dpp_ror2(v[0]), dpp_ror2(v[1]), dpp_ror2(v[2]), dpp_ror2(v[3])}; }
; __device__ __forceinline__ u32x2 pack4(f32x4 v) { return (u32x2){pk2(v[0], v[1]), pk2(v[2], v[3])}; }
; __device__ __forceinline__ f32x2 gelu_pk(f32x2 v) {
;     const f32x2 av = __builtin_elementwise_abs(v), d = av * 0.2316418882f + 1.0f;
;     f32x2 t; t.x = __builtin_amdgcn_rcpf(d.x); t.y = __builtin_amdgcn_rcpf(d.y);
;     f32x2 q = t * 0.5307027145f + (-0.7265760135f); q = q * t + 0.7107068705f; q = q * t + (-0.142248368f); q = q * t + 0.127414796f; q = q * t;
;     const f32x2 s = (v * v) * (-0.72134752044f);
;     f32x2 e; e.x = __builtin_amdgcn_exp2f(s.x); e.y = __builtin_amdgcn_exp2f(s.y);
;     const f32x2 m = v * (q * e), r = v - m;
;     f32x2 o; o.x = v.x < 0.f ? m.x : r.x; o.y = v.y < 0.f ? m.y : r.y; return o;
;     __device__ __forceinline__ void operator()(AccRef acc, const Unit& u, int wr, int wc, int fr, int fq) const {
;     ...
;                     const f32x4 wg0 = *(const f32x4*)(cw + jn), wg1 = *(const f32x4*)(cw + (UPN + jn)), wg2 = *(const f32x4*)(cw + (2 * UPN + jn)), bg = *(const f32x4*)(cb + jn);
;                     f32x4 pg1 = (f32x4){0.f, 0.f, 0.f, 0.f}, pg2 = pg1;
; #pragma unroll
;                     for (int m = 0; m < 4; ++m) { const int row = rowg + m * 16 + fr;
;                         const f32x4 ag = unpack4(pa[ai][0][m][n]);
;                         const f32x4 rg1 = ror1v(ag), rg2 = ror2v(ag);
;                         const f32x4 g1 = fr >= 1 ? rg1 : pg1, g2 = fr >= 2 ? rg2 : pg2;
;                         if (m == 0 && fr < 2) *(f32x4*)(edge + (unsigned)((grp * 4 + fr) * UPN + jn)) = ag;
;                         if (m == 3 && fr >= 14) *(f32x4*)(edge + (unsigned)((grp * 4 + (fr - 12)) * UPN + jn)) = ag;
;                         const f32x4 o = gelu4(bg + wg0 * g2 + wg1 * g1 + wg2 * ag) * cu[m];
;                         if (!(m == 0 && fr < 2)) *(u32x2*)(act + (unsigned)(row * DFF + jn)) = pack4(o);
;                         pg1 = rg1; pg2 = rg2; }
	v_and_b32_e32 v93, 0x7fffffff, v37
	v_and_b32_e32 v92, 0x7fffffff, v36
	v_pk_fma_f32 v[92:93], v[92:93], s[52:53], 1.0 op_sel_hi:[1,0,0]
	v_mov_b32_dpp v45, v38 row_ror:2 row_mask:0xf bank_mask:0xf
	v_rcp_f32_e32 v92, v92
	v_rcp_f32_e32 v93, v93
	v_mov_b32_dpp v81, v39 row_ror:2 row_mask:0xf bank_mask:0xf
	v_mov_b32_dpp v42, v38 row_ror:1 row_mask:0xf bank_mask:0xf
	v_mov_b32_dpp v47, v39 row_ror:1 row_mask:0xf bank_mask:0xf
	v_cndmask_b32_e64 v95, v193, v81, s[6:7]
	v_cndmask_b32_e64 v94, v192, v45, s[6:7]
	v_cndmask_b32_e64 v87, v171, v47, s[8:9]
	v_cndmask_b32_e64 v86, v170, v42, s[8:9]
	v_pk_fma_f32 v[94:95], v[30:31], v[94:95], v[34:35]
	v_pk_mul_f32 v[88:89], v[36:37], v[36:37]
	v_pk_fma_f32 v[86:87], v[22:23], v[86:87], v[94:95]
	v_pk_mul_f32 v[88:89], v[88:89], s[42:43] op_sel_hi:[1,0]
	v_pk_fma_f32 v[94:95], v[92:93], s[54:55], v[90:91] op_sel_hi:[1,0,0]
	v_exp_f32_e32 v88, v88
	v_exp_f32_e32 v89, v89
	v_pk_fma_f32 v[94:95], v[92:93], v[94:95], s[58:59] op_sel_hi:[1,1,0]
	s_nop 0
	v_pk_fma_f32 v[94:95], v[92:93], v[94:95], s[60:61] op_sel_hi:[1,1,0]
	v_pk_fma_f32 v[38:39], v[26:27], v[38:39], v[86:87]
	v_pk_fma_f32 v[94:95], v[92:93], v[94:95], s[62:63] op_sel_hi:[1,1,0]
	v_pk_mul_f32 v[86:87], v[38:39], v[38:39]
	v_pk_mul_f32 v[92:93], v[92:93], v[94:95]
	v_pk_mul_f32 v[86:87], v[86:87], s[42:43] op_sel_hi:[1,0]
	v_pk_fma_f32 v[88:89], v[88:89], v[92:93], 0.5 op_sel_hi:[1,1,0] neg_lo:[1,0,0] neg_hi:[1,0,0]
	v_exp_f32_e32 v86, v86
	v_mul_f32_e64 v92, |v36|, v88
	v_mul_f32_e64 v93, |v37|, v89
	v_exp_f32_e32 v87, v87
	v_and_b32_e32 v88, 0x7fffffff, v38
	v_add_u32_e32 v136, v148, v46
	v_pk_fma_f32 v[36:37], v[36:37], 0.5, v[92:93] op_sel_hi:[1,0,1]
	v_and_b32_e32 v89, 0x7fffffff, v39
	v_pk_fma_f32 v[88:89], v[88:89], s[52:53], 1.0 op_sel_hi:[1,0,0]
	s_nop 0
	v_rcp_f32_e32 v88, v88
	v_rcp_f32_e32 v89, v89
	v_pk_mul_f32 v[36:37], v[82:83], v[36:37]
	s_nop 1
	v_cvt_pk_bf16_f32 v36, v36, v37
	v_pk_fma_f32 v[90:91], v[88:89], s[54:55], v[90:91] op_sel_hi:[1,0,0]
	s_nop 1
	v_pk_fma_f32 v[90:91], v[88:89], v[90:91], s[58:59] op_sel_hi:[1,1,0]
	s_nop 0
	v_pk_fma_f32 v[90:91], v[88:89], v[90:91], s[60:61] op_sel_hi:[1,1,0]
	s_nop 0
	v_pk_fma_f32 v[90:91], v[88:89], v[90:91], s[62:63] op_sel_hi:[1,1,0]
	s_nop 0
	v_pk_mul_f32 v[88:89], v[88:89], v[90:91]
	s_nop 0
	v_pk_fma_f32 v[86:87], v[86:87], v[88:89], 0.5 op_sel_hi:[1,1,0] neg_lo:[1,0,0] neg_hi:[1,0,0]
	s_nop 0
	v_mul_f32_e64 v88, |v38|, v86
	v_mul_f32_e64 v89, |v39|, v87
	v_pk_fma_f32 v[38:39], v[38:39], 0.5, v[88:89] op_sel_hi:[1,0,1]
	v_pk_mul_f32 v[38:39], v[84:85], v[38:39]
	s_nop 1
	v_cvt_pk_bf16_f32 v37, v38, v39
	v_lshl_add_u64 v[38:39], v[136:137], 1, s[26:27]
	global_store_dwordx2 v[38:39], v[36:37], off
	v_lshlrev_b32_e32 v36, 16, v147
	v_and_b32_e32 v37, 0xffff0000, v147
	v_lshlrev_b32_e32 v38, 16, v149
	v_and_b32_e32 v39, 0xffff0000, v149
	s_nop 1
	v_mov_b32_dpp v82, v36 row_ror:1 row_mask:0xf bank_mask:0xf
	v_mov_b32_dpp v83, v37 row_ror:1 row_mask:0xf bank_mask:0xf
	v_mov_b32_dpp v84, v38 row_ror:1 row_mask:0xf bank_mask:0xf
	v_mov_b32_dpp v87, v39 row_ror:1 row_mask:0xf bank_mask:0xf
	v_mov_b32_dpp v85, v36 row_ror:2 row_mask:0xf bank_mask:0xf
	v_mov_b32_dpp v88, v37 row_ror:2 row_mask:0xf bank_mask:0xf
	v_mov_b32_dpp v86, v38 row_ror:2 row_mask:0xf bank_mask:0xf
	v_mov_b32_dpp v89, v39 row_ror:2 row_mask:0xf bank_mask:0xf
	s_and_saveexec_b64 s[0:1], vcc
	s_cbranch_execz .LBB0_1426
	v_add_u32_e32 v136, v46, v152
	v_lshl_add_u64 v[90:91], v[136:137], 2, s[28:29]
	global_store_dwordx4 v[90:91], v[36:39], off
; __device__ __forceinline__ f32x2 gelu_pk(f32x2 v) {
;     __device__ __forceinline__ void operator()(AccRef acc, const Unit& u, int wr, int wc, int fr, int fq) const {
;     ...
;             for (int n = 0; n < 2; ++n) { const unsigned jn = (unsigned)(j0 + 4 * n);
;                 f32x4 cu[4];
;                 {
;                     const f32x4 wu0 = *(const f32x4*)(cw + (DFF + jn)), wu1 = *(const f32x4*)(cw + (UPN + DFF + jn)), wu2 = *(const f32x4*)(cw + (2 * UPN + DFF + jn)), bu = *(const f32x4*)(cb + (DFF + jn));
;                     f32x4 pu1 = (f32x4){0.f, 0.f, 0.f, 0.f}, pu2 = pu1;
; #pragma unroll
;                     for (int m = 0; m < 4; ++m) {
;                         const f32x4 au = unpack4(pa[ai][1][m][n]);
;                         const f32x4 ru1 = ror1v(au), ru2 = ror2v(au);
;                         const f32x4 u1 = fr >= 1 ? ru1 : pu1, u2 = fr >= 2 ? ru2 : pu2;
;                         if (m == 0 && fr < 2) *(f32x4*)(edge + (unsigned)((grp * 4 + fr) * UPN + DFF + jn)) = au;
;                         if (m == 3 && fr >= 14) *(f32x4*)(edge + (unsigned)((grp * 4 + (fr - 12)) * UPN + DFF + jn)) = au;
;                         cu[m] = bu + wu0 * u2 + wu1 * u1 + wu2 * au;
;                         pu1 = ru1; pu2 = ru2; }
;                 }
;                 {
;                     const f32x4 wg0 = *(const f32x4*)(cw + jn), wg1 = *(const f32x4*)(cw + (UPN + jn)), wg2 = *(const f32x4*)(cw + (2 * UPN + jn)), bg = *(const f32x4*)(cb + jn);
;                     f32x4 pg1 = (f32x4){0.f, 0.f, 0.f, 0.f}, pg2 = pg1;
; #pragma unroll
;                     for (int m = 0; m < 4; ++m) { const int row = rowg + m * 16 + fr;
;                         const f32x4 ag = unpack4(pa[ai][0][m][n]);
;                         const f32x4 rg1 = ror1v(ag), rg2 = ror2v(ag);
;                         const f32x4 g1 = fr >= 1 ? rg1 : pg1, g2 = fr >= 2 ? rg2 : pg2;
;                         if (m == 0 && fr < 2) *(f32x4*)(edge + (unsigned)((grp * 4 + fr) * UPN + jn)) = ag;
;                         if (m == 3 && fr >= 14) *(f32x4*)(edge + (unsigned)((grp * 4 + (fr - 12)) * UPN + jn)) = ag;
;                         const f32x4 o = gelu4(bg + wg0 * g2 + wg1 * g1 + wg2 * ag) * cu[m];
;                         if (!(m == 0 && fr < 2)) *(u32x2*)(act + (unsigned)(row * DFF + jn)) = pack4(o);
;                         pg1 = rg1; pg2 = rg2; }
.LBB0_1426:
	s_or_b64 exec, exec, s[0:1]
	v_cndmask_b32_e64 v91, v47, v87, s[8:9]
	v_cndmask_b32_e64 v90, v42, v84, s[8:9]
	v_cndmask_b32_e64 v42, v45, v86, s[6:7]
	v_cndmask_b32_e64 v87, v183, v191, s[6:7]
	v_cndmask_b32_e64 v86, v182, v190, s[6:7]
	v_cndmask_b32_e64 v40, v40, v82, s[8:9]
	v_cndmask_b32_e64 v82, v43, v85, s[6:7]
	v_cndmask_b32_e64 v85, v180, v188, s[8:9]
	v_cndmask_b32_e64 v84, v174, v185, s[8:9]
	v_pk_fma_f32 v[10:11], v[10:11], v[86:87], v[14:15]
	v_cndmask_b32_e64 v41, v41, v83, s[8:9]
	v_cndmask_b32_e64 v83, v80, v88, s[6:7]
	v_pk_fma_f32 v[2:3], v[2:3], v[84:85], v[10:11]
	v_cndmask_b32_e64 v43, v81, v89, s[6:7]
	v_pk_fma_f32 v[2:3], v[6:7], v[18:19], v[2:3]
	v_pk_fma_f32 v[6:7], v[28:29], v[82:83], v[32:33]
	v_cndmask_b32_e64 v89, v181, v189, s[6:7]
	v_pk_fma_f32 v[6:7], v[20:21], v[40:41], v[6:7]
	v_cndmask_b32_e64 v88, v178, v186, s[6:7]
	v_pk_fma_f32 v[6:7], v[24:25], v[36:37], v[6:7]
	v_pk_fma_f32 v[8:9], v[8:9], v[88:89], v[12:13]
	v_and_b32_e32 v13, 0x7fffffff, v7
	v_and_b32_e32 v12, 0x7fffffff, v6
	v_pk_fma_f32 v[12:13], v[12:13], s[52:53], 1.0 op_sel_hi:[1,0,0]
	v_cndmask_b32_e64 v81, v179, v187, s[8:9]
	v_rcp_f32_e32 v12, v12
	v_rcp_f32_e32 v13, v13
	v_cndmask_b32_e64 v80, v173, v184, s[8:9]
	v_pk_fma_f32 v[0:1], v[0:1], v[80:81], v[8:9]
	v_pk_mul_f32 v[10:11], v[6:7], v[6:7]
	v_mov_b64_e32 v[14:15], s[56:57]
	v_pk_fma_f32 v[0:1], v[4:5], v[16:17], v[0:1]
	v_pk_mul_f32 v[10:11], v[10:11], s[42:43] op_sel_hi:[1,0]
	v_pk_fma_f32 v[16:17], v[12:13], s[54:55], v[14:15] op_sel_hi:[1,0,0]
	v_exp_f32_e32 v10, v10
	v_exp_f32_e32 v11, v11
	v_pk_fma_f32 v[16:17], v[12:13], v[16:17], s[58:59] op_sel_hi:[1,1,0]
	v_pk_fma_f32 v[4:5], v[30:31], v[42:43], v[34:35]
	v_pk_fma_f32 v[16:17], v[12:13], v[16:17], s[60:61] op_sel_hi:[1,1,0]
	v_pk_fma_f32 v[4:5], v[22:23], v[90:91], v[4:5]
	v_pk_fma_f32 v[16:17], v[12:13], v[16:17], s[62:63] op_sel_hi:[1,1,0]
	s_nop 0
	v_pk_mul_f32 v[12:13], v[12:13], v[16:17]
	v_pk_fma_f32 v[4:5], v[26:27], v[38:39], v[4:5]
	v_pk_fma_f32 v[10:11], v[10:11], v[12:13], 0.5 op_sel_hi:[1,1,0] neg_lo:[1,0,0] neg_hi:[1,0,0]
	v_pk_mul_f32 v[8:9], v[4:5], v[4:5]
	v_mul_f32_e64 v12, |v6|, v10
	v_mul_f32_e64 v13, |v7|, v11
	v_pk_mul_f32 v[8:9], v[8:9], s[42:43] op_sel_hi:[1,0]
	s_nop 0
	v_and_b32_e32 v10, 0x7fffffff, v4
	v_exp_f32_e32 v8, v8
	v_pk_fma_f32 v[6:7], v[6:7], 0.5, v[12:13] op_sel_hi:[1,0,1]
	v_and_b32_e32 v11, 0x7fffffff, v5
	v_pk_fma_f32 v[10:11], v[10:11], s[52:53], 1.0 op_sel_hi:[1,0,0]
	v_exp_f32_e32 v9, v9
	v_rcp_f32_e32 v10, v10
	v_rcp_f32_e32 v11, v11
	v_pk_mul_f32 v[0:1], v[0:1], v[6:7]
	v_add_u32_e32 v136, v177, v46
	v_pk_fma_f32 v[12:13], v[10:11], s[54:55], v[14:15] op_sel_hi:[1,0,0]
	v_cvt_pk_bf16_f32 v0, v0, v1
	s_addk_i32 s65, 0x80
	v_pk_fma_f32 v[12:13], v[10:11], v[12:13], s[58:59] op_sel_hi:[1,1,0]
	s_ashr_i32 s69, s65, 4
	v_pk_fma_f32 v[12:13], v[10:11], v[12:13], s[60:61] op_sel_hi:[1,1,0]
	v_add_u32_e32 v16, s69, v166
	v_pk_fma_f32 v[12:13], v[10:11], v[12:13], s[62:63] op_sel_hi:[1,1,0]
	v_mul_lo_u32 v80, v16, s85
	v_pk_mul_f32 v[10:11], v[10:11], v[12:13]
	v_lshlrev_b32_e32 v36, 16, v120
	v_pk_fma_f32 v[8:9], v[8:9], v[10:11], 0.5 op_sel_hi:[1,1,0] neg_lo:[1,0,0] neg_hi:[1,0,0]
	v_and_b32_e32 v37, 0xffff0000, v120
	v_mul_f32_e64 v10, |v4|, v8
	v_mul_f32_e64 v11, |v5|, v9
	v_lshlrev_b32_e32 v38, 16, v121
	v_and_b32_e32 v39, 0xffff0000, v121
	s_nop 1
	v_pk_fma_f32 v[4:5], v[4:5], 0.5, v[10:11] op_sel_hi:[1,0,1]
	v_pk_mul_f32 v[2:3], v[2:3], v[4:5]
	s_nop 1
	v_cvt_pk_bf16_f32 v1, v2, v3
	v_lshl_add_u64 v[2:3], v[136:137], 1, s[26:27]
	global_store_dwordx2 v[2:3], v[0:1], off
	global_load_dwordx4 v[8:11], v[48:49], off
	global_load_dwordx4 v[4:7], v[50:51], off
	s_nop 0
	global_load_dwordx4 v[0:3], v[52:53], off
	global_load_dwordx4 v[12:15], v[54:55], off
	s_nop 1
	v_add_u32_e32 v45, 0xb00, v80
	v_mov_b32_dpp v146, v36 row_ror:1 row_mask:0xf bank_mask:0xf
	v_mov_b32_dpp v149, v37 row_ror:1 row_mask:0xf bank_mask:0xf
	v_mov_b32_dpp v147, v38 row_ror:1 row_mask:0xf bank_mask:0xf
	v_mov_b32_dpp v167, v39 row_ror:1 row_mask:0xf bank_mask:0xf
	v_mov_b32_dpp v148, v36 row_ror:2 row_mask:0xf bank_mask:0xf
	v_mov_b32_dpp v168, v37 row_ror:2 row_mask:0xf bank_mask:0xf
	v_mov_b32_dpp v172, v38 row_ror:2 row_mask:0xf bank_mask:0xf
	v_mov_b32_dpp v174, v39 row_ror:2 row_mask:0xf bank_mask:0xf
	s_and_saveexec_b64 s[0:1], s[12:13]
	s_cbranch_execz .LBB0_1428
	v_add_u32_e32 v136, v45, v44
	v_lshl_add_u64 v[16:17], v[136:137], 2, s[28:29]
	global_store_dwordx4 v[16:17], v[36:39], off

; __device__ __forceinline__ f32x4 gelu4(f32x4 v) { const f32x2 a = gelu_pk((f32x2){v[0], v[1]}), b = gelu_pk((f32x2){v[2], v[3]}); return (f32x4){a.x, a.y, b.x, b.y}; }
; __device__ __forceinline__ f32x4 ror1v(f32x4 v) { return (f32x4){dpp_ror1(v[0]), dpp_ror1(v[1]), dpp_ror1(v[2]), dpp_ror1(v[3])}; }
; __device__ __forceinline__ f32x4 ror2v(f32x4 v) { return (f32x4){dpp_ror2(v[0]), dpp_ror2(v[1]), dpp_ror2(v[2]), dpp_ror2(v[3])}; }
; __device__ __forceinline__ u32x2 pack4(f32x4 v) { return (u32x2){pk2(v[0], v[1]), pk2(v[2], v[3])}; }
; __device__ __forceinline__ f32x2 gelu_pk(f32x2 v) {
;     const f32x2 av = __builtin_elementwise_abs(v), d = av * 0.2316418882f + 1.0f;
;     f32x2 t; t.x = __builtin_amdgcn_rcpf(d.x); t.y = __builtin_amdgcn_rcpf(d.y);
;     f32x2 q = t * 0.5307027145f + (-0.7265760135f); q = q * t + 0.7107068705f; q = q * t + (-0.142248368f); q = q * t + 0.127414796f; q = q * t;
;     const f32x2 s = (v * v) * (-0.72134752044f);
;     f32x2 e; e.x = __builtin_amdgcn_exp2f(s.x); e.y = __builtin_amdgcn_exp2f(s.y);
;     const f32x2 m = v * (q * e), r = v - m;
;     f32x2 o; o.x = v.x < 0.f ? m.x : r.x; o.y = v.y < 0.f ? m.y : r.y; return o;
;     __device__ __forceinline__ void operator()(AccRef acc, const Unit& u, int wr, int wc, int fr, int fq) const {
;     ...
;                     const f32x4 wg0 = *(const f32x4*)(cw + jn), wg1 = *(const f32x4*)(cw + (UPN + jn)), wg2 = *(const f32x4*)(cw + (2 * UPN + jn)), bg = *(const f32x4*)(cb + jn);
;                     f32x4 pg1 = (f32x4){0.f, 0.f, 0.f, 0.f}, pg2 = pg1;
; #pragma unroll
;                     for (int m = 0; m < 4; ++m) { const int row = rowg + m * 16 + fr;
;                         const f32x4 ag = unpack4(pa[ai][0][m][n]);
;                         const f32x4 rg1 = ror1v(ag), rg2 = ror2v(ag);
;                         const f32x4 g1 = fr >= 1 ? rg1 : pg1, g2 = fr >= 2 ? rg2 : pg2;
;                         if (m == 0 && fr < 2) *(f32x4*)(edge + (unsigned)((grp * 4 + fr) * UPN + jn)) = ag;
;                         if (m == 3 && fr >= 14) *(f32x4*)(edge + (unsigned)((grp * 4 + (fr - 12)) * UPN + jn)) = ag;
;                         const f32x4 o = gelu4(bg + wg0 * g2 + wg1 * g1 + wg2 * ag) * cu[m];
;                         if (!(m == 0 && fr < 2)) *(u32x2*)(act + (unsigned)(row * DFF + jn)) = pack4(o);
;                         pg1 = rg1; pg2 = rg2; }
.LBB0_1430:
	s_or_b64 exec, exec, s[0:1]
	global_load_dwordx4 v[28:31], v[56:57], off
	global_load_dwordx4 v[24:27], v[58:59], off
	global_load_dwordx4 v[20:23], v[62:63], off
	global_load_dwordx4 v[32:35], v[64:65], off
	v_add_u32_e32 v124, s65, v166
	v_lshlrev_b32_e32 v40, 16, v118
	v_and_b32_e32 v41, 0xffff0000, v118
	v_lshlrev_b32_e32 v42, 16, v119
	v_and_b32_e32 v43, 0xffff0000, v119
	s_nop 1
	v_mov_b32_dpp v56, v40 row_ror:1 row_mask:0xf bank_mask:0xf
	v_mov_b32_dpp v57, v41 row_ror:1 row_mask:0xf bank_mask:0xf
	v_mov_b32_dpp v58, v42 row_ror:1 row_mask:0xf bank_mask:0xf
	v_mov_b32_dpp v59, v43 row_ror:1 row_mask:0xf bank_mask:0xf
	v_mov_b32_dpp v62, v40 row_ror:2 row_mask:0xf bank_mask:0xf
	v_mov_b32_dpp v63, v41 row_ror:2 row_mask:0xf bank_mask:0xf
	v_mov_b32_dpp v64, v42 row_ror:2 row_mask:0xf bank_mask:0xf
	v_mov_b32_dpp v65, v43 row_ror:2 row_mask:0xf bank_mask:0xf
	v_mul_lo_u32 v82, v124, s86
	s_and_saveexec_b64 s[0:1], s[10:11]
	s_xor_b64 s[74:75], exec, s[0:1]
	s_cbranch_execz .LBB0_1432
	v_cndmask_b32_e64 v179, 0, v174, s[6:7]
	v_cndmask_b32_e64 v178, 0, v172, s[6:7]
	v_cndmask_b32_e64 v127, 0, v167, s[8:9]
	v_cndmask_b32_e64 v126, 0, v147, s[8:9]
	s_waitcnt vmcnt(4)
	v_pk_fma_f32 v[178:179], v[10:11], v[178:179], v[14:15]
	v_cndmask_b32_e64 v181, 0, v168, s[6:7]
	v_pk_fma_f32 v[126:127], v[6:7], v[126:127], v[178:179]
	v_cndmask_b32_e64 v180, 0, v148, s[6:7]
	v_pk_fma_f32 v[38:39], v[2:3], v[38:39], v[126:127]
	s_waitcnt vmcnt(0)
	v_pk_fma_f32 v[126:127], v[28:29], v[62:63], v[32:33]
	v_cndmask_b32_e64 v119, 0, v149, s[8:9]
	v_pk_fma_f32 v[126:127], v[24:25], v[56:57], v[126:127]
	v_cndmask_b32_e64 v118, 0, v146, s[8:9]
	v_pk_fma_f32 v[40:41], v[20:21], v[40:41], v[126:127]
	v_pk_fma_f32 v[180:181], v[8:9], v[180:181], v[12:13]
	v_and_b32_e32 v179, 0x7fffffff, v41
	v_and_b32_e32 v178, 0x7fffffff, v40
	v_pk_fma_f32 v[178:179], v[178:179], s[52:53], 1.0 op_sel_hi:[1,0,0]
	v_pk_fma_f32 v[118:119], v[4:5], v[118:119], v[180:181]
	v_rcp_f32_e32 v178, v178
	v_rcp_f32_e32 v179, v179
	v_pk_mul_f32 v[126:127], v[40:41], v[40:41]
	v_mov_b64_e32 v[180:181], s[56:57]
	v_pk_mul_f32 v[126:127], v[126:127], s[42:43] op_sel_hi:[1,0]
	v_pk_fma_f32 v[182:183], v[178:179], s[54:55], v[180:181] op_sel_hi:[1,0,0]
	v_exp_f32_e32 v126, v126
	v_exp_f32_e32 v127, v127
	v_pk_fma_f32 v[182:183], v[178:179], v[182:183], s[58:59] op_sel_hi:[1,1,0]
	v_pk_fma_f32 v[36:37], v[0:1], v[36:37], v[118:119]
	v_pk_fma_f32 v[182:183], v[178:179], v[182:183], s[60:61] op_sel_hi:[1,1,0]
	v_pk_fma_f32 v[118:119], v[30:31], v[64:65], v[34:35]
	v_pk_fma_f32 v[182:183], v[178:179], v[182:183], s[62:63] op_sel_hi:[1,1,0]
	v_pk_fma_f32 v[118:119], v[26:27], v[58:59], v[118:119]
	v_pk_mul_f32 v[178:179], v[178:179], v[182:183]
	s_nop 0
	v_pk_fma_f32 v[126:127], v[126:127], v[178:179], 0.5 op_sel_hi:[1,1,0] neg_lo:[1,0,0] neg_hi:[1,0,0]
	v_pk_fma_f32 v[42:43], v[22:23], v[42:43], v[118:119]
	v_mul_f32_e64 v178, |v40|, v126
	v_mul_f32_e64 v179, |v41|, v127
	v_pk_mul_f32 v[118:119], v[42:43], v[42:43]
	s_nop 0
	v_and_b32_e32 v126, 0x7fffffff, v42
	v_pk_mul_f32 v[118:119], v[118:119], s[42:43] op_sel_hi:[1,0]
	v_pk_fma_f32 v[40:41], v[40:41], 0.5, v[178:179] op_sel_hi:[1,0,1]
	v_and_b32_e32 v127, 0x7fffffff, v43
	v_pk_fma_f32 v[126:127], v[126:127], s[52:53], 1.0 op_sel_hi:[1,0,0]
	v_exp_f32_e32 v118, v118
	v_rcp_f32_e32 v126, v126
	v_rcp_f32_e32 v127, v127
	v_exp_f32_e32 v119, v119
	s_nop 0
	v_mul_lo_u32 v82, v124, s86
	v_pk_fma_f32 v[178:179], v[126:127], s[54:55], v[180:181] op_sel_hi:[1,0,0]
	v_pk_mul_f32 v[36:37], v[36:37], v[40:41]
	v_pk_fma_f32 v[178:179], v[126:127], v[178:179], s[58:59] op_sel_hi:[1,1,0]
	v_add_u32_e32 v136, v82, v44
	v_pk_fma_f32 v[178:179], v[126:127], v[178:179], s[60:61] op_sel_hi:[1,1,0]
	v_cvt_pk_bf16_f32 v36, v36, v37
	s_nop 0
	v_pk_fma_f32 v[178:179], v[126:127], v[178:179], s[62:63] op_sel_hi:[1,1,0]
	s_nop 0
	v_pk_mul_f32 v[126:127], v[126:127], v[178:179]
	s_nop 0
	v_pk_fma_f32 v[118:119], v[118:119], v[126:127], 0.5 op_sel_hi:[1,1,0] neg_lo:[1,0,0] neg_hi:[1,0,0]
	s_nop 0
	v_mul_f32_e64 v126, |v42|, v118
	v_mul_f32_e64 v127, |v43|, v119
	v_pk_fma_f32 v[42:43], v[42:43], 0.5, v[126:127] op_sel_hi:[1,0,1]
	v_pk_mul_f32 v[38:39], v[38:39], v[42:43]
	s_nop 0
	v_cvt_pk_bf16_f32 v37, v38, v39
	v_lshl_add_u64 v[38:39], v[136:137], 1, s[26:27]
	global_store_dwordx2 v[38:39], v[36:37], off

; __device__ __forceinline__ f32x2 gelu_pk(f32x2 v) {
;     const f32x2 av = __builtin_elementwise_abs(v), d = av * 0.2316418882f + 1.0f;
;     f32x2 t; t.x = __builtin_amdgcn_rcpf(d.x); t.y = __builtin_amdgcn_rcpf(d.y);
;     __device__ __forceinline__ void operator()(AccRef acc, const Unit& u, int wr, int wc, int fr, int fq) const {
;     ...
;                     const f32x4 wu0 = *(const f32x4*)(cw + (DFF + jn)), wu1 = *(const f32x4*)(cw + (UPN + DFF + jn)), wu2 = *(const f32x4*)(cw + (2 * UPN + DFF + jn)), bu = *(const f32x4*)(cb + (DFF + jn));
;                     f32x4 pu1 = (f32x4){0.f, 0.f, 0.f, 0.f}, pu2 = pu1;
; #pragma unroll
;                     for (int m = 0; m < 4; ++m) {
;                         const f32x4 au = unpack4(pa[ai][1][m][n]);
;                         const f32x4 ru1 = ror1v(au), ru2 = ror2v(au);
;                         const f32x4 u1 = fr >= 1 ? ru1 : pu1, u2 = fr >= 2 ? ru2 : pu2;
;                         if (m == 0 && fr < 2) *(f32x4*)(edge + (unsigned)((grp * 4 + fr) * UPN + DFF + jn)) = au;
;                         if (m == 3 && fr >= 14) *(f32x4*)(edge + (unsigned)((grp * 4 + (fr - 12)) * UPN + DFF + jn)) = au;
;                         cu[m] = bu + wu0 * u2 + wu1 * u1 + wu2 * au;
;                         pu1 = ru1; pu2 = ru2; }
;                 }
;                 {
;                     const f32x4 wg0 = *(const f32x4*)(cw + jn), wg1 = *(const f32x4*)(cw + (UPN + jn)), wg2 = *(const f32x4*)(cw + (2 * UPN + jn)), bg = *(const f32x4*)(cb + jn);
;                     f32x4 pg1 = (f32x4){0.f, 0.f, 0.f, 0.f}, pg2 = pg1;
; #pragma unroll
;                     for (int m = 0; m < 4; ++m) { const int row = rowg + m * 16 + fr;
;                         const f32x4 ag = unpack4(pa[ai][0][m][n]);
;                         const f32x4 rg1 = ror1v(ag), rg2 = ror2v(ag);
;                         const f32x4 g1 = fr >= 1 ? rg1 : pg1, g2 = fr >= 2 ? rg2 : pg2;
;                         if (m == 0 && fr < 2) *(f32x4*)(edge + (unsigned)((grp * 4 + fr) * UPN + jn)) = ag;
;                         if (m == 3 && fr >= 14) *(f32x4*)(edge + (unsigned)((grp * 4 + (fr - 12)) * UPN + jn)) = ag;
;                         const f32x4 o = gelu4(bg + wg0 * g2 + wg1 * g1 + wg2 * ag) * cu[m];
;                         if (!(m == 0 && fr < 2)) *(u32x2*)(act + (unsigned)(row * DFF + jn)) = pack4(o);
;                         pg1 = rg1; pg2 = rg2; }
.LBB0_1434:
	s_or_b64 exec, exec, s[0:1]
	s_nop 0
	v_cndmask_b32_e64 v41, v174, v175, s[6:7]
	v_cndmask_b32_e64 v40, v172, v173, s[6:7]
	v_cndmask_b32_e64 v43, v168, v171, s[6:7]
	v_cndmask_b32_e64 v42, v148, v152, s[6:7]
	v_cndmask_b32_e64 v37, v149, v169, s[8:9]
	v_cndmask_b32_e64 v36, v146, v123, s[8:9]
	v_cndmask_b32_e64 v39, v167, v170, s[8:9]
	v_cndmask_b32_e64 v38, v147, v150, s[8:9]
	s_waitcnt vmcnt(4)
	v_pk_fma_f32 v[42:43], v[8:9], v[42:43], v[12:13]
	v_pk_fma_f32 v[40:41], v[10:11], v[40:41], v[14:15]
	v_pk_fma_f32 v[36:37], v[4:5], v[36:37], v[42:43]
	v_pk_fma_f32 v[38:39], v[6:7], v[38:39], v[40:41]
	v_pk_fma_f32 v[36:37], v[0:1], v[54:55], v[36:37]
	v_pk_fma_f32 v[38:39], v[2:3], v[52:53], v[38:39]
	v_cndmask_b32_e64 v53, v175, v90, s[6:7]
	v_cndmask_b32_e64 v52, v173, v89, s[6:7]
	v_cndmask_b32_e64 v55, v171, v88, s[6:7]
	v_cndmask_b32_e64 v54, v152, v85, s[6:7]
	v_cndmask_b32_e64 v41, v169, v86, s[8:9]
	v_cndmask_b32_e64 v40, v123, v83, s[8:9]
	v_cndmask_b32_e64 v43, v170, v87, s[8:9]
	v_cndmask_b32_e64 v42, v150, v84, s[8:9]
	v_pk_fma_f32 v[54:55], v[8:9], v[54:55], v[12:13]
	v_pk_fma_f32 v[52:53], v[10:11], v[52:53], v[14:15]
	v_pk_fma_f32 v[40:41], v[4:5], v[40:41], v[54:55]
	v_pk_fma_f32 v[42:43], v[6:7], v[42:43], v[52:53]
	v_pk_fma_f32 v[52:53], v[0:1], v[50:51], v[40:41]
	v_pk_fma_f32 v[54:55], v[2:3], v[48:49], v[42:43]
	v_lshlrev_b32_e32 v40, 16, v116
	v_and_b32_e32 v41, 0xffff0000, v116
	v_lshlrev_b32_e32 v42, 16, v117
	v_and_b32_e32 v43, 0xffff0000, v117
	s_nop 1
	v_mov_b32_dpp v116, v40 row_ror:1 row_mask:0xf bank_mask:0xf
	v_mov_b32_dpp v117, v41 row_ror:1 row_mask:0xf bank_mask:0xf
	v_mov_b32_dpp v123, v40 row_ror:2 row_mask:0xf bank_mask:0xf
	v_mov_b32_dpp v124, v41 row_ror:2 row_mask:0xf bank_mask:0xf
	v_cndmask_b32_e64 v51, v57, v117, s[8:9]
	v_cndmask_b32_e64 v50, v56, v116, s[8:9]
	v_cndmask_b32_e64 v57, v63, v124, s[6:7]
	v_cndmask_b32_e64 v56, v62, v123, s[6:7]
	s_waitcnt vmcnt(2)
	v_pk_fma_f32 v[56:57], v[28:29], v[56:57], v[32:33]
	s_nop 1
	v_pk_fma_f32 v[50:51], v[24:25], v[50:51], v[56:57]
	s_nop 1
	v_pk_fma_f32 v[40:41], v[20:21], v[40:41], v[50:51]
	s_nop 1
	v_and_b32_e32 v57, 0x7fffffff, v41
	v_and_b32_e32 v56, 0x7fffffff, v40
	s_nop 1
	v_pk_fma_f32 v[56:57], v[56:57], s[52:53], 1.0 op_sel_hi:[1,0,0]
	v_mov_b32_dpp v118, v42 row_ror:1 row_mask:0xf bank_mask:0xf
	v_mov_b32_dpp v119, v43 row_ror:1 row_mask:0xf bank_mask:0xf
	v_mov_b32_dpp v125, v42 row_ror:2 row_mask:0xf bank_mask:0xf
	v_mov_b32_dpp v126, v43 row_ror:2 row_mask:0xf bank_mask:0xf
	v_rcp_f32_e32 v56, v56
	v_rcp_f32_e32 v57, v57
	v_cndmask_b32_e64 v49, v59, v119, s[8:9]
	v_cndmask_b32_e64 v48, v58, v118, s[8:9]
	v_cndmask_b32_e64 v59, v65, v126, s[6:7]
	v_cndmask_b32_e64 v58, v64, v125, s[6:7]
	v_pk_fma_f32 v[58:59], v[30:31], v[58:59], v[34:35]
	v_pk_mul_f32 v[50:51], v[40:41], v[40:41]
	v_pk_fma_f32 v[48:49], v[26:27], v[48:49], v[58:59]
	v_mov_b64_e32 v[58:59], s[56:57]
	v_pk_mul_f32 v[50:51], v[50:51], s[42:43] op_sel_hi:[1,0]
	v_pk_fma_f32 v[62:63], v[56:57], s[54:55], v[58:59] op_sel_hi:[1,0,0]
	v_exp_f32_e32 v50, v50
	v_exp_f32_e32 v51, v51
	v_pk_fma_f32 v[62:63], v[56:57], v[62:63], s[58:59] op_sel_hi:[1,1,0]
	s_nop 0
	v_pk_fma_f32 v[62:63], v[56:57], v[62:63], s[60:61] op_sel_hi:[1,1,0]
	v_pk_fma_f32 v[42:43], v[22:23], v[42:43], v[48:49]
	v_pk_fma_f32 v[62:63], v[56:57], v[62:63], s[62:63] op_sel_hi:[1,1,0]
	v_pk_mul_f32 v[48:49], v[42:43], v[42:43]
	v_pk_mul_f32 v[56:57], v[56:57], v[62:63]
	v_pk_mul_f32 v[48:49], v[48:49], s[42:43] op_sel_hi:[1,0]
	v_pk_fma_f32 v[50:51], v[50:51], v[56:57], 0.5 op_sel_hi:[1,1,0] neg_lo:[1,0,0] neg_hi:[1,0,0]
	v_exp_f32_e32 v48, v48
	v_mul_f32_e64 v56, |v40|, v50
	v_mul_f32_e64 v57, |v41|, v51
	v_exp_f32_e32 v49, v49
	v_and_b32_e32 v50, 0x7fffffff, v42
	v_add_u32_e32 v62, 0xb000, v82
	v_pk_fma_f32 v[40:41], v[40:41], 0.5, v[56:57] op_sel_hi:[1,0,1]
	v_and_b32_e32 v51, 0x7fffffff, v43
	v_pk_fma_f32 v[50:51], v[50:51], s[52:53], 1.0 op_sel_hi:[1,0,0]
	s_nop 0
	v_rcp_f32_e32 v50, v50
	v_rcp_f32_e32 v51, v51
	v_pk_mul_f32 v[36:37], v[36:37], v[40:41]
	v_add_u32_e32 v136, v62, v44
	v_cvt_pk_bf16_f32 v36, v36, v37
	v_pk_fma_f32 v[56:57], v[50:51], s[54:55], v[58:59] op_sel_hi:[1,0,0]
	s_nop 1
	v_pk_fma_f32 v[56:57], v[50:51], v[56:57], s[58:59] op_sel_hi:[1,1,0]
	s_nop 1
	v_pk_fma_f32 v[56:57], v[50:51], v[56:57], s[60:61] op_sel_hi:[1,1,0]
	v_add_u32_e32 v63, 0x16000, v82
	v_pk_fma_f32 v[56:57], v[50:51], v[56:57], s[62:63] op_sel_hi:[1,1,0]
	s_nop 0
	v_pk_mul_f32 v[50:51], v[50:51], v[56:57]
	s_nop 0
	v_pk_fma_f32 v[48:49], v[48:49], v[50:51], 0.5 op_sel_hi:[1,1,0] neg_lo:[1,0,0] neg_hi:[1,0,0]
	s_nop 0
	v_mul_f32_e64 v50, |v42|, v48
	v_mul_f32_e64 v51, |v43|, v49
	v_pk_fma_f32 v[42:43], v[42:43], 0.5, v[50:51] op_sel_hi:[1,0,1]
	v_pk_mul_f32 v[38:39], v[38:39], v[42:43]
	s_nop 1
	v_cvt_pk_bf16_f32 v37, v38, v39
	v_lshl_add_u64 v[38:39], v[136:137], 1, s[26:27]
	global_store_dwordx2 v[38:39], v[36:37], off
	v_lshlrev_b32_e32 v36, 16, v114
	v_and_b32_e32 v37, 0xffff0000, v114
	v_lshlrev_b32_e32 v38, 16, v115
	v_mov_b32_dpp v43, v36 row_ror:2 row_mask:0xf bank_mask:0xf
	v_mov_b32_dpp v50, v37 row_ror:2 row_mask:0xf bank_mask:0xf
	v_and_b32_e32 v39, 0xffff0000, v115
	v_mov_b32_dpp v40, v36 row_ror:1 row_mask:0xf bank_mask:0xf
	v_mov_b32_dpp v41, v37 row_ror:1 row_mask:0xf bank_mask:0xf
	v_cndmask_b32_e64 v115, v124, v50, s[6:7]
	v_cndmask_b32_e64 v114, v123, v43, s[6:7]
	v_cndmask_b32_e64 v65, v117, v41, s[8:9]
	v_cndmask_b32_e64 v64, v116, v40, s[8:9]
	v_pk_fma_f32 v[114:115], v[28:29], v[114:115], v[32:33]
	s_nop 1
	v_pk_fma_f32 v[64:65], v[24:25], v[64:65], v[114:115]
	s_nop 1
; __device__ __forceinline__ f32x4 gelu4(f32x4 v) { const f32x2 a = gelu_pk((f32x2){v[0], v[1]}), b = gelu_pk((f32x2){v[2], v[3]}); return (f32x4){a.x, a.y, b.x, b.y}; }
; __device__ __forceinline__ f32x4 ror1v(f32x4 v) { return (f32x4){dpp_ror1(v[0]), dpp_ror1(v[1]), dpp_ror1(v[2]), dpp_ror1(v[3])}; }
; __device__ __forceinline__ f32x4 ror2v(f32x4 v) { return (f32x4){dpp_ror2(v[0]), dpp_ror2(v[1]), dpp_ror2(v[2]), dpp_ror2(v[3])}; }
; __device__ __forceinline__ u32x2 pack4(f32x4 v) { return (u32x2){pk2(v[0], v[1]), pk2(v[2], v[3])}; }
; __device__ __forceinline__ f32x2 gelu_pk(f32x2 v) {
;     const f32x2 av = __builtin_elementwise_abs(v), d = av * 0.2316418882f + 1.0f;
;     f32x2 t; t.x = __builtin_amdgcn_rcpf(d.x); t.y = __builtin_amdgcn_rcpf(d.y);
;     f32x2 q = t * 0.5307027145f + (-0.7265760135f); q = q * t + 0.7107068705f; q = q * t + (-0.142248368f); q = q * t + 0.127414796f; q = q * t;
;     const f32x2 s = (v * v) * (-0.72134752044f);
;     f32x2 e; e.x = __builtin_amdgcn_exp2f(s.x); e.y = __builtin_amdgcn_exp2f(s.y);
;     const f32x2 m = v * (q * e), r = v - m;
;     f32x2 o; o.x = v.x < 0.f ? m.x : r.x; o.y = v.y < 0.f ? m.y : r.y; return o;
;     __device__ __forceinline__ void operator()(AccRef acc, const Unit& u, int wr, int wc, int fr, int fq) const {
;     ...
;                     const f32x4 wg0 = *(const f32x4*)(cw + jn), wg1 = *(const f32x4*)(cw + (UPN + jn)), wg2 = *(const f32x4*)(cw + (2 * UPN + jn)), bg = *(const f32x4*)(cb + jn);
;                     f32x4 pg1 = (f32x4){0.f, 0.f, 0.f, 0.f}, pg2 = pg1;
; #pragma unroll
;                     for (int m = 0; m < 4; ++m) { const int row = rowg + m * 16 + fr;
;                         const f32x4 ag = unpack4(pa[ai][0][m][n]);
;                         const f32x4 rg1 = ror1v(ag), rg2 = ror2v(ag);
;                         const f32x4 g1 = fr >= 1 ? rg1 : pg1, g2 = fr >= 2 ? rg2 : pg2;
;                         if (m == 0 && fr < 2) *(f32x4*)(edge + (unsigned)((grp * 4 + fr) * UPN + jn)) = ag;
;                         if (m == 3 && fr >= 14) *(f32x4*)(edge + (unsigned)((grp * 4 + (fr - 12)) * UPN + jn)) = ag;
;                         const f32x4 o = gelu4(bg + wg0 * g2 + wg1 * g1 + wg2 * ag) * cu[m];
;                         if (!(m == 0 && fr < 2)) *(u32x2*)(act + (unsigned)(row * DFF + jn)) = pack4(o);
;                         pg1 = rg1; pg2 = rg2; }
	v_pk_fma_f32 v[36:37], v[20:21], v[36:37], v[64:65]
	s_nop 1
	v_and_b32_e32 v115, 0x7fffffff, v37
	v_and_b32_e32 v114, 0x7fffffff, v36
	v_pk_fma_f32 v[114:115], v[114:115], s[52:53], 1.0 op_sel_hi:[1,0,0]
	v_mov_b32_dpp v48, v38 row_ror:2 row_mask:0xf bank_mask:0xf
	v_rcp_f32_e32 v114, v114
	v_rcp_f32_e32 v115, v115
	v_mov_b32_dpp v51, v39 row_ror:2 row_mask:0xf bank_mask:0xf
	v_mov_b32_dpp v42, v38 row_ror:1 row_mask:0xf bank_mask:0xf
	v_mov_b32_dpp v49, v39 row_ror:1 row_mask:0xf bank_mask:0xf
	v_cndmask_b32_e64 v117, v126, v51, s[6:7]
	v_cndmask_b32_e64 v116, v125, v48, s[6:7]
	v_cndmask_b32_e64 v57, v119, v49, s[8:9]
	v_cndmask_b32_e64 v56, v118, v42, s[8:9]
	v_pk_fma_f32 v[116:117], v[30:31], v[116:117], v[34:35]
	v_pk_mul_f32 v[64:65], v[36:37], v[36:37]
	v_pk_fma_f32 v[56:57], v[26:27], v[56:57], v[116:117]
	v_pk_mul_f32 v[64:65], v[64:65], s[42:43] op_sel_hi:[1,0]
	v_pk_fma_f32 v[116:117], v[114:115], s[54:55], v[58:59] op_sel_hi:[1,0,0]
	v_exp_f32_e32 v64, v64
	v_exp_f32_e32 v65, v65
	v_pk_fma_f32 v[116:117], v[114:115], v[116:117], s[58:59] op_sel_hi:[1,1,0]
	s_nop 0
	v_pk_fma_f32 v[116:117], v[114:115], v[116:117], s[60:61] op_sel_hi:[1,1,0]
	v_pk_fma_f32 v[38:39], v[22:23], v[38:39], v[56:57]
	v_pk_fma_f32 v[116:117], v[114:115], v[116:117], s[62:63] op_sel_hi:[1,1,0]
	v_pk_mul_f32 v[56:57], v[38:39], v[38:39]
	v_pk_mul_f32 v[114:115], v[114:115], v[116:117]
	v_pk_mul_f32 v[56:57], v[56:57], s[42:43] op_sel_hi:[1,0]
	v_pk_fma_f32 v[64:65], v[64:65], v[114:115], 0.5 op_sel_hi:[1,1,0] neg_lo:[1,0,0] neg_hi:[1,0,0]
	v_exp_f32_e32 v56, v56
	v_mul_f32_e64 v114, |v36|, v64
	v_mul_f32_e64 v115, |v37|, v65
	v_exp_f32_e32 v57, v57
	v_and_b32_e32 v64, 0x7fffffff, v38
	v_add_u32_e32 v136, v63, v44
	v_pk_fma_f32 v[36:37], v[36:37], 0.5, v[114:115] op_sel_hi:[1,0,1]
	v_and_b32_e32 v65, 0x7fffffff, v39
	v_pk_fma_f32 v[64:65], v[64:65], s[52:53], 1.0 op_sel_hi:[1,0,0]
	s_nop 0
	v_rcp_f32_e32 v64, v64
	v_rcp_f32_e32 v65, v65
	v_pk_mul_f32 v[36:37], v[52:53], v[36:37]
	s_nop 1
	v_cvt_pk_bf16_f32 v36, v36, v37
	v_pk_fma_f32 v[58:59], v[64:65], s[54:55], v[58:59] op_sel_hi:[1,0,0]
	s_nop 1
	v_pk_fma_f32 v[58:59], v[64:65], v[58:59], s[58:59] op_sel_hi:[1,1,0]
	s_nop 0
	v_pk_fma_f32 v[58:59], v[64:65], v[58:59], s[60:61] op_sel_hi:[1,1,0]
	s_nop 0
	v_pk_fma_f32 v[58:59], v[64:65], v[58:59], s[62:63] op_sel_hi:[1,1,0]
	s_nop 0
	v_pk_mul_f32 v[58:59], v[64:65], v[58:59]
	s_nop 0
	v_pk_fma_f32 v[56:57], v[56:57], v[58:59], 0.5 op_sel_hi:[1,1,0] neg_lo:[1,0,0] neg_hi:[1,0,0]
	s_nop 0
	v_mul_f32_e64 v58, |v38|, v56
	v_mul_f32_e64 v59, |v39|, v57
	v_pk_fma_f32 v[38:39], v[38:39], 0.5, v[58:59] op_sel_hi:[1,0,1]
	v_pk_mul_f32 v[38:39], v[54:55], v[38:39]
	s_nop 1
	v_cvt_pk_bf16_f32 v37, v38, v39
	v_lshl_add_u64 v[38:39], v[136:137], 1, s[26:27]
	global_store_dwordx2 v[38:39], v[36:37], off
	v_lshlrev_b32_e32 v36, 16, v112
	v_and_b32_e32 v37, 0xffff0000, v112
	v_lshlrev_b32_e32 v38, 16, v113
	v_and_b32_e32 v39, 0xffff0000, v113
	s_nop 1
	v_mov_b32_dpp v52, v36 row_ror:1 row_mask:0xf bank_mask:0xf
	v_mov_b32_dpp v53, v37 row_ror:1 row_mask:0xf bank_mask:0xf
	v_mov_b32_dpp v54, v38 row_ror:1 row_mask:0xf bank_mask:0xf
	v_mov_b32_dpp v57, v39 row_ror:1 row_mask:0xf bank_mask:0xf
	v_mov_b32_dpp v55, v36 row_ror:2 row_mask:0xf bank_mask:0xf
	v_mov_b32_dpp v58, v37 row_ror:2 row_mask:0xf bank_mask:0xf
	v_mov_b32_dpp v56, v38 row_ror:2 row_mask:0xf bank_mask:0xf
	v_mov_b32_dpp v59, v39 row_ror:2 row_mask:0xf bank_mask:0xf
	s_and_saveexec_b64 s[0:1], vcc
	s_cbranch_execz .LBB0_1436
	v_add_u32_e32 v136, v47, v44
	v_lshl_add_u64 v[64:65], v[136:137], 2, s[28:29]
	global_store_dwordx4 v[64:65], v[36:39], off
; __device__ __forceinline__ f32x2 gelu_pk(f32x2 v) {
;     const f32x2 av = __builtin_elementwise_abs(v), d = av * 0.2316418882f + 1.0f;
;     f32x2 t; t.x = __builtin_amdgcn_rcpf(d.x); t.y = __builtin_amdgcn_rcpf(d.y);
;     __device__ __forceinline__ void operator()(AccRef acc, const Unit& u, int wr, int wc, int fr, int fq) const {
;     ...
;                     const f32x4 wu0 = *(const f32x4*)(cw + (DFF + jn)), wu1 = *(const f32x4*)(cw + (UPN + DFF + jn)), wu2 = *(const f32x4*)(cw + (2 * UPN + DFF + jn)), bu = *(const f32x4*)(cb + (DFF + jn));
;                     f32x4 pu1 = (f32x4){0.f, 0.f, 0.f, 0.f}, pu2 = pu1;
; #pragma unroll
;                     for (int m = 0; m < 4; ++m) {
;                         const f32x4 au = unpack4(pa[ai][1][m][n]);
;                         const f32x4 ru1 = ror1v(au), ru2 = ror2v(au);
;                         const f32x4 u1 = fr >= 1 ? ru1 : pu1, u2 = fr >= 2 ? ru2 : pu2;
;                         if (m == 0 && fr < 2) *(f32x4*)(edge + (unsigned)((grp * 4 + fr) * UPN + DFF + jn)) = au;
;                         if (m == 3 && fr >= 14) *(f32x4*)(edge + (unsigned)((grp * 4 + (fr - 12)) * UPN + DFF + jn)) = au;
;                         cu[m] = bu + wu0 * u2 + wu1 * u1 + wu2 * au;
;                         pu1 = ru1; pu2 = ru2; }
;                 }
;                 {
;                     const f32x4 wg0 = *(const f32x4*)(cw + jn), wg1 = *(const f32x4*)(cw + (UPN + jn)), wg2 = *(const f32x4*)(cw + (2 * UPN + jn)), bg = *(const f32x4*)(cb + jn);
;                     f32x4 pg1 = (f32x4){0.f, 0.f, 0.f, 0.f}, pg2 = pg1;
; #pragma unroll
;                     for (int m = 0; m < 4; ++m) { const int row = rowg + m * 16 + fr;
;                         const f32x4 ag = unpack4(pa[ai][0][m][n]);
;                         const f32x4 rg1 = ror1v(ag), rg2 = ror2v(ag);
;                         const f32x4 g1 = fr >= 1 ? rg1 : pg1, g2 = fr >= 2 ? rg2 : pg2;
;                         if (m == 0 && fr < 2) *(f32x4*)(edge + (unsigned)((grp * 4 + fr) * UPN + jn)) = ag;
;                         if (m == 3 && fr >= 14) *(f32x4*)(edge + (unsigned)((grp * 4 + (fr - 12)) * UPN + jn)) = ag;
;                         const f32x4 o = gelu4(bg + wg0 * g2 + wg1 * g1 + wg2 * ag) * cu[m];
;                         if (!(m == 0 && fr < 2)) *(u32x2*)(act + (unsigned)(row * DFF + jn)) = pack4(o);
;                         pg1 = rg1; pg2 = rg2; }
.LBB0_1436:
	s_or_b64 exec, exec, s[0:1]
	v_cndmask_b32_e64 v64, v42, v54, s[8:9]
	v_cndmask_b32_e64 v40, v40, v52, s[8:9]
	v_cndmask_b32_e64 v52, v43, v55, s[6:7]
	v_cndmask_b32_e64 v55, v90, v122, s[6:7]
	v_cndmask_b32_e64 v54, v89, v121, s[6:7]
	v_cndmask_b32_e64 v41, v41, v53, s[8:9]
	v_cndmask_b32_e64 v53, v50, v58, s[6:7]
	v_cndmask_b32_e64 v43, v51, v59, s[6:7]
	v_cndmask_b32_e64 v51, v87, v95, s[8:9]
	v_cndmask_b32_e64 v50, v84, v92, s[8:9]
	v_pk_fma_f32 v[10:11], v[10:11], v[54:55], v[14:15]
	v_cndmask_b32_e64 v65, v49, v57, s[8:9]
	v_pk_fma_f32 v[6:7], v[6:7], v[50:51], v[10:11]
	v_cndmask_b32_e64 v42, v48, v56, s[6:7]
	v_pk_fma_f32 v[2:3], v[2:3], v[18:19], v[6:7]
	v_pk_fma_f32 v[6:7], v[28:29], v[52:53], v[32:33]
	v_cndmask_b32_e64 v57, v88, v120, s[6:7]
	v_pk_fma_f32 v[6:7], v[24:25], v[40:41], v[6:7]
	v_cndmask_b32_e64 v56, v85, v93, s[6:7]
	v_pk_fma_f32 v[6:7], v[20:21], v[36:37], v[6:7]
	v_pk_fma_f32 v[8:9], v[8:9], v[56:57], v[12:13]
	v_and_b32_e32 v13, 0x7fffffff, v7
	v_and_b32_e32 v12, 0x7fffffff, v6
	v_pk_fma_f32 v[12:13], v[12:13], s[52:53], 1.0 op_sel_hi:[1,0,0]
	v_cndmask_b32_e64 v49, v86, v94, s[8:9]
	v_rcp_f32_e32 v12, v12
	v_rcp_f32_e32 v13, v13
	v_cndmask_b32_e64 v48, v83, v91, s[8:9]
	v_pk_fma_f32 v[4:5], v[4:5], v[48:49], v[8:9]
	v_pk_mul_f32 v[10:11], v[6:7], v[6:7]
	v_mov_b64_e32 v[14:15], s[56:57]
	v_pk_fma_f32 v[0:1], v[0:1], v[16:17], v[4:5]
	v_pk_mul_f32 v[10:11], v[10:11], s[42:43] op_sel_hi:[1,0]
	v_pk_fma_f32 v[16:17], v[12:13], s[54:55], v[14:15] op_sel_hi:[1,0,0]
	v_exp_f32_e32 v10, v10
	v_exp_f32_e32 v11, v11
	v_pk_fma_f32 v[16:17], v[12:13], v[16:17], s[58:59] op_sel_hi:[1,1,0]
	v_pk_fma_f32 v[4:5], v[30:31], v[42:43], v[34:35]
	v_pk_fma_f32 v[16:17], v[12:13], v[16:17], s[60:61] op_sel_hi:[1,1,0]
	v_pk_fma_f32 v[4:5], v[26:27], v[64:65], v[4:5]
	v_pk_fma_f32 v[16:17], v[12:13], v[16:17], s[62:63] op_sel_hi:[1,1,0]
	s_nop 0
	v_pk_mul_f32 v[12:13], v[12:13], v[16:17]
	v_pk_fma_f32 v[4:5], v[22:23], v[38:39], v[4:5]
	v_pk_fma_f32 v[10:11], v[10:11], v[12:13], 0.5 op_sel_hi:[1,1,0] neg_lo:[1,0,0] neg_hi:[1,0,0]
	v_pk_mul_f32 v[8:9], v[4:5], v[4:5]
	v_mul_f32_e64 v12, |v6|, v10
	v_mul_f32_e64 v13, |v7|, v11
	v_pk_mul_f32 v[8:9], v[8:9], s[42:43] op_sel_hi:[1,0]
	s_nop 0
	v_and_b32_e32 v10, 0x7fffffff, v4
	v_exp_f32_e32 v8, v8
	v_pk_fma_f32 v[6:7], v[6:7], 0.5, v[12:13] op_sel_hi:[1,0,1]
	v_and_b32_e32 v11, 0x7fffffff, v5
	v_pk_fma_f32 v[10:11], v[10:11], s[52:53], 1.0 op_sel_hi:[1,0,0]
	v_exp_f32_e32 v9, v9
	v_rcp_f32_e32 v10, v10
	v_rcp_f32_e32 v11, v11
	v_add_u32_e32 v64, 0x21000, v82
	v_pk_mul_f32 v[0:1], v[0:1], v[6:7]
	v_pk_fma_f32 v[12:13], v[10:11], s[54:55], v[14:15] op_sel_hi:[1,0,0]
	v_add_u32_e32 v136, v64, v44
	v_pk_fma_f32 v[12:13], v[10:11], v[12:13], s[58:59] op_sel_hi:[1,1,0]
	v_cvt_pk_bf16_f32 v0, v0, v1
	v_lshlrev_b32_e32 v36, 16, v104
	v_pk_fma_f32 v[12:13], v[10:11], v[12:13], s[60:61] op_sel_hi:[1,1,0]
	v_and_b32_e32 v37, 0xffff0000, v104
	v_pk_fma_f32 v[12:13], v[10:11], v[12:13], s[62:63] op_sel_hi:[1,1,0]
	v_lshlrev_b32_e32 v38, 16, v105
	v_pk_mul_f32 v[10:11], v[10:11], v[12:13]
	v_and_b32_e32 v39, 0xffff0000, v105
	v_pk_fma_f32 v[8:9], v[8:9], v[10:11], 0.5 op_sel_hi:[1,1,0] neg_lo:[1,0,0] neg_hi:[1,0,0]
	s_nop 1
	v_mul_f32_e64 v10, |v4|, v8
	v_mul_f32_e64 v11, |v5|, v9
	v_pk_fma_f32 v[4:5], v[4:5], 0.5, v[10:11] op_sel_hi:[1,0,1]
	v_pk_mul_f32 v[2:3], v[2:3], v[4:5]
	s_nop 1
	v_cvt_pk_bf16_f32 v1, v2, v3
	v_lshl_add_u64 v[2:3], v[136:137], 1, s[26:27]
	global_store_dwordx2 v[2:3], v[0:1], off
	global_load_dwordx4 v[8:11], v[60:61], off
	global_load_dwordx4 v[4:7], v[66:67], off
	s_nop 0
	global_load_dwordx4 v[0:3], v[68:69], off
	global_load_dwordx4 v[12:15], v[70:71], off
	s_nop 1
	v_mov_b32_dpp v93, v36 row_ror:1 row_mask:0xf bank_mask:0xf
	v_mov_b32_dpp v112, v37 row_ror:1 row_mask:0xf bank_mask:0xf
	v_mov_b32_dpp v104, v38 row_ror:1 row_mask:0xf bank_mask:0xf
	v_mov_b32_dpp v114, v39 row_ror:1 row_mask:0xf bank_mask:0xf
	v_mov_b32_dpp v105, v36 row_ror:2 row_mask:0xf bank_mask:0xf
	v_mov_b32_dpp v115, v37 row_ror:2 row_mask:0xf bank_mask:0xf
	v_mov_b32_dpp v117, v38 row_ror:2 row_mask:0xf bank_mask:0xf
	v_mov_b32_dpp v119, v39 row_ror:2 row_mask:0xf bank_mask:0xf
	s_and_saveexec_b64 s[0:1], s[12:13]
	s_cbranch_execz .LBB0_1438
	v_add_u32_e32 v136, v46, v45
	v_lshl_add_u64 v[16:17], v[136:137], 2, s[28:29]
	global_store_dwordx4 v[16:17], v[36:39], off

; __device__ __forceinline__ f32x4 gelu4(f32x4 v) { const f32x2 a = gelu_pk((f32x2){v[0], v[1]}), b = gelu_pk((f32x2){v[2], v[3]}); return (f32x4){a.x, a.y, b.x, b.y}; }
; __device__ __forceinline__ f32x4 ror1v(f32x4 v) { return (f32x4){dpp_ror1(v[0]), dpp_ror1(v[1]), dpp_ror1(v[2]), dpp_ror1(v[3])}; }
; __device__ __forceinline__ f32x4 ror2v(f32x4 v) { return (f32x4){dpp_ror2(v[0]), dpp_ror2(v[1]), dpp_ror2(v[2]), dpp_ror2(v[3])}; }
; __device__ __forceinline__ u32x2 pack4(f32x4 v) { return (u32x2){pk2(v[0], v[1]), pk2(v[2], v[3])}; }
; __device__ __forceinline__ f32x2 gelu_pk(f32x2 v) {
;     const f32x2 av = __builtin_elementwise_abs(v), d = av * 0.2316418882f + 1.0f;
;     f32x2 t; t.x = __builtin_amdgcn_rcpf(d.x); t.y = __builtin_amdgcn_rcpf(d.y);
;     f32x2 q = t * 0.5307027145f + (-0.7265760135f); q = q * t + 0.7107068705f; q = q * t + (-0.142248368f); q = q * t + 0.127414796f; q = q * t;
;     const f32x2 s = (v * v) * (-0.72134752044f);
;     f32x2 e; e.x = __builtin_amdgcn_exp2f(s.x); e.y = __builtin_amdgcn_exp2f(s.y);
;     const f32x2 m = v * (q * e), r = v - m;
;     f32x2 o; o.x = v.x < 0.f ? m.x : r.x; o.y = v.y < 0.f ? m.y : r.y; return o;
;     __device__ __forceinline__ void operator()(AccRef acc, const Unit& u, int wr, int wc, int fr, int fq) const {
;     ...
;                     const f32x4 wg0 = *(const f32x4*)(cw + jn), wg1 = *(const f32x4*)(cw + (UPN + jn)), wg2 = *(const f32x4*)(cw + (2 * UPN + jn)), bg = *(const f32x4*)(cb + jn);
;                     f32x4 pg1 = (f32x4){0.f, 0.f, 0.f, 0.f}, pg2 = pg1;
; #pragma unroll
;                     for (int m = 0; m < 4; ++m) { const int row = rowg + m * 16 + fr;
;                         const f32x4 ag = unpack4(pa[ai][0][m][n]);
;                         const f32x4 rg1 = ror1v(ag), rg2 = ror2v(ag);
;                         const f32x4 g1 = fr >= 1 ? rg1 : pg1, g2 = fr >= 2 ? rg2 : pg2;
;                         if (m == 0 && fr < 2) *(f32x4*)(edge + (unsigned)((grp * 4 + fr) * UPN + jn)) = ag;
;                         if (m == 3 && fr >= 14) *(f32x4*)(edge + (unsigned)((grp * 4 + (fr - 12)) * UPN + jn)) = ag;
;                         const f32x4 o = gelu4(bg + wg0 * g2 + wg1 * g1 + wg2 * ag) * cu[m];
;                         if (!(m == 0 && fr < 2)) *(u32x2*)(act + (unsigned)(row * DFF + jn)) = pack4(o);
;                         pg1 = rg1; pg2 = rg2; }
.LBB0_1440:
	s_or_b64 exec, exec, s[0:1]
	global_load_dwordx4 v[28:31], v[72:73], off
	global_load_dwordx4 v[24:27], v[74:75], off
	global_load_dwordx4 v[20:23], v[76:77], off
	global_load_dwordx4 v[32:35], v[78:79], off
	v_lshlrev_b32_e32 v40, 16, v102
	v_and_b32_e32 v41, 0xffff0000, v102
	v_lshlrev_b32_e32 v42, 16, v103
	v_and_b32_e32 v43, 0xffff0000, v103
	s_nop 1
	v_mov_b32_dpp v54, v40 row_ror:1 row_mask:0xf bank_mask:0xf
	v_mov_b32_dpp v55, v41 row_ror:1 row_mask:0xf bank_mask:0xf
	v_mov_b32_dpp v56, v42 row_ror:1 row_mask:0xf bank_mask:0xf
	v_mov_b32_dpp v57, v43 row_ror:1 row_mask:0xf bank_mask:0xf
	v_mov_b32_dpp v58, v40 row_ror:2 row_mask:0xf bank_mask:0xf
	v_mov_b32_dpp v59, v41 row_ror:2 row_mask:0xf bank_mask:0xf
	v_mov_b32_dpp v60, v42 row_ror:2 row_mask:0xf bank_mask:0xf
	v_mov_b32_dpp v61, v43 row_ror:2 row_mask:0xf bank_mask:0xf
	s_and_saveexec_b64 s[0:1], s[10:11]
	s_xor_b64 s[10:11], exec, s[0:1]
	s_cbranch_execz .LBB0_1442
	v_cndmask_b32_e64 v77, 0, v119, s[6:7]
	v_cndmask_b32_e64 v76, 0, v117, s[6:7]
	v_cndmask_b32_e64 v75, 0, v114, s[8:9]
	v_cndmask_b32_e64 v74, 0, v104, s[8:9]
	s_waitcnt vmcnt(4)
	v_pk_fma_f32 v[76:77], v[10:11], v[76:77], v[14:15]
	v_cndmask_b32_e64 v79, 0, v115, s[6:7]
	v_pk_fma_f32 v[74:75], v[6:7], v[74:75], v[76:77]
	v_cndmask_b32_e64 v78, 0, v105, s[6:7]
	v_pk_fma_f32 v[38:39], v[2:3], v[38:39], v[74:75]
	s_waitcnt vmcnt(0)
	v_pk_fma_f32 v[74:75], v[28:29], v[58:59], v[32:33]
	v_cndmask_b32_e64 v73, 0, v112, s[8:9]
	v_pk_fma_f32 v[74:75], v[24:25], v[54:55], v[74:75]
	v_cndmask_b32_e64 v72, 0, v93, s[8:9]
	v_pk_fma_f32 v[40:41], v[20:21], v[40:41], v[74:75]
	v_pk_fma_f32 v[78:79], v[8:9], v[78:79], v[12:13]
	v_and_b32_e32 v77, 0x7fffffff, v41
	v_and_b32_e32 v76, 0x7fffffff, v40
	v_pk_fma_f32 v[76:77], v[76:77], s[52:53], 1.0 op_sel_hi:[1,0,0]
	v_pk_fma_f32 v[72:73], v[4:5], v[72:73], v[78:79]
	v_rcp_f32_e32 v76, v76
	v_rcp_f32_e32 v77, v77
	v_pk_mul_f32 v[74:75], v[40:41], v[40:41]
	v_mov_b64_e32 v[78:79], s[56:57]
	v_pk_mul_f32 v[74:75], v[74:75], s[42:43] op_sel_hi:[1,0]
	v_pk_fma_f32 v[80:81], v[76:77], s[54:55], v[78:79] op_sel_hi:[1,0,0]
	v_exp_f32_e32 v74, v74
	v_exp_f32_e32 v75, v75
	v_pk_fma_f32 v[80:81], v[76:77], v[80:81], s[58:59] op_sel_hi:[1,1,0]
	v_pk_fma_f32 v[36:37], v[0:1], v[36:37], v[72:73]
	v_pk_fma_f32 v[80:81], v[76:77], v[80:81], s[60:61] op_sel_hi:[1,1,0]
	v_pk_fma_f32 v[72:73], v[30:31], v[60:61], v[34:35]
	v_pk_fma_f32 v[80:81], v[76:77], v[80:81], s[62:63] op_sel_hi:[1,1,0]
	v_pk_fma_f32 v[72:73], v[26:27], v[56:57], v[72:73]
	v_pk_mul_f32 v[76:77], v[76:77], v[80:81]
	s_nop 0
	v_pk_fma_f32 v[74:75], v[74:75], v[76:77], 0.5 op_sel_hi:[1,1,0] neg_lo:[1,0,0] neg_hi:[1,0,0]
	v_pk_fma_f32 v[42:43], v[22:23], v[42:43], v[72:73]
	v_mul_f32_e64 v76, |v40|, v74
	v_mul_f32_e64 v77, |v41|, v75
	v_pk_mul_f32 v[72:73], v[42:43], v[42:43]
	s_nop 0
	v_and_b32_e32 v74, 0x7fffffff, v42
	v_pk_mul_f32 v[72:73], v[72:73], s[42:43] op_sel_hi:[1,0]
	v_pk_fma_f32 v[40:41], v[40:41], 0.5, v[76:77] op_sel_hi:[1,0,1]
	v_and_b32_e32 v75, 0x7fffffff, v43
	v_pk_fma_f32 v[74:75], v[74:75], s[52:53], 1.0 op_sel_hi:[1,0,0]
	v_exp_f32_e32 v72, v72
	v_rcp_f32_e32 v74, v74
	v_rcp_f32_e32 v75, v75
	v_exp_f32_e32 v73, v73
	s_nop 0
	v_pk_mul_f32 v[36:37], v[36:37], v[40:41]
	v_pk_fma_f32 v[76:77], v[74:75], s[54:55], v[78:79] op_sel_hi:[1,0,0]
	v_add_u32_e32 v136, v82, v46
	v_pk_fma_f32 v[76:77], v[74:75], v[76:77], s[58:59] op_sel_hi:[1,1,0]
	v_cvt_pk_bf16_f32 v36, v36, v37
	s_nop 0
	v_pk_fma_f32 v[76:77], v[74:75], v[76:77], s[60:61] op_sel_hi:[1,1,0]
	s_nop 0
	v_pk_fma_f32 v[76:77], v[74:75], v[76:77], s[62:63] op_sel_hi:[1,1,0]
	s_nop 0
	v_pk_mul_f32 v[74:75], v[74:75], v[76:77]
	s_nop 0
	v_pk_fma_f32 v[72:73], v[72:73], v[74:75], 0.5 op_sel_hi:[1,1,0] neg_lo:[1,0,0] neg_hi:[1,0,0]
	s_nop 0
	v_mul_f32_e64 v74, |v42|, v72
	v_mul_f32_e64 v75, |v43|, v73
	v_pk_fma_f32 v[42:43], v[42:43], 0.5, v[74:75] op_sel_hi:[1,0,1]
	v_pk_mul_f32 v[38:39], v[38:39], v[42:43]
	s_nop 0
	v_cvt_pk_bf16_f32 v37, v38, v39
	v_lshl_add_u64 v[38:39], v[136:137], 1, s[26:27]
	global_store_dwordx2 v[38:39], v[36:37], off

; __device__ __forceinline__ f32x2 gelu_pk(f32x2 v) {
;     __device__ __forceinline__ void operator()(AccRef acc, const Unit& u, int wr, int wc, int fr, int fq) const {
;     ...
;             for (int n = 0; n < 2; ++n) { const unsigned jn = (unsigned)(j0 + 4 * n);
;                 f32x4 cu[4];
;                 {
;                     const f32x4 wu0 = *(const f32x4*)(cw + (DFF + jn)), wu1 = *(const f32x4*)(cw + (UPN + DFF + jn)), wu2 = *(const f32x4*)(cw + (2 * UPN + DFF + jn)), bu = *(const f32x4*)(cb + (DFF + jn));
;                     f32x4 pu1 = (f32x4){0.f, 0.f, 0.f, 0.f}, pu2 = pu1;
; #pragma unroll
;                     for (int m = 0; m < 4; ++m) {
;                         const f32x4 au = unpack4(pa[ai][1][m][n]);
;                         const f32x4 ru1 = ror1v(au), ru2 = ror2v(au);
;                         const f32x4 u1 = fr >= 1 ? ru1 : pu1, u2 = fr >= 2 ? ru2 : pu2;
;                         if (m == 0 && fr < 2) *(f32x4*)(edge + (unsigned)((grp * 4 + fr) * UPN + DFF + jn)) = au;
;                         if (m == 3 && fr >= 14) *(f32x4*)(edge + (unsigned)((grp * 4 + (fr - 12)) * UPN + DFF + jn)) = au;
;                         cu[m] = bu + wu0 * u2 + wu1 * u1 + wu2 * au;
;                         pu1 = ru1; pu2 = ru2; }
;                 }
;                 {
;                     const f32x4 wg0 = *(const f32x4*)(cw + jn), wg1 = *(const f32x4*)(cw + (UPN + jn)), wg2 = *(const f32x4*)(cw + (2 * UPN + jn)), bg = *(const f32x4*)(cb + jn);
;                     f32x4 pg1 = (f32x4){0.f, 0.f, 0.f, 0.f}, pg2 = pg1;
; #pragma unroll
;                     for (int m = 0; m < 4; ++m) { const int row = rowg + m * 16 + fr;
;                         const f32x4 ag = unpack4(pa[ai][0][m][n]);
;                         const f32x4 rg1 = ror1v(ag), rg2 = ror2v(ag);
;                         const f32x4 g1 = fr >= 1 ? rg1 : pg1, g2 = fr >= 2 ? rg2 : pg2;
;                         if (m == 0 && fr < 2) *(f32x4*)(edge + (unsigned)((grp * 4 + fr) * UPN + jn)) = ag;
;                         if (m == 3 && fr >= 14) *(f32x4*)(edge + (unsigned)((grp * 4 + (fr - 12)) * UPN + jn)) = ag;
;                         const f32x4 o = gelu4(bg + wg0 * g2 + wg1 * g1 + wg2 * ag) * cu[m];
;                         if (!(m == 0 && fr < 2)) *(u32x2*)(act + (unsigned)(row * DFF + jn)) = pack4(o);
;                         pg1 = rg1; pg2 = rg2; }
.LBB0_1444:
	s_or_b64 exec, exec, s[0:1]
	s_nop 0
	v_cndmask_b32_e64 v43, v115, v113, s[6:7]
	v_cndmask_b32_e64 v42, v105, v95, s[6:7]
	v_cndmask_b32_e64 v37, v112, v106, s[8:9]
	v_cndmask_b32_e64 v36, v93, v92, s[8:9]
	v_cndmask_b32_e64 v41, v119, v118, s[6:7]
	v_cndmask_b32_e64 v40, v117, v116, s[6:7]
	s_waitcnt vmcnt(4)
	v_pk_fma_f32 v[42:43], v[8:9], v[42:43], v[12:13]
	v_cndmask_b32_e64 v39, v114, v107, s[8:9]
	v_cndmask_b32_e64 v38, v104, v94, s[8:9]
	v_pk_fma_f32 v[40:41], v[10:11], v[40:41], v[14:15]
	v_pk_fma_f32 v[36:37], v[4:5], v[36:37], v[42:43]
	v_pk_fma_f32 v[38:39], v[6:7], v[38:39], v[40:41]
	v_pk_fma_f32 v[36:37], v[0:1], v[52:53], v[36:37]
	v_cndmask_b32_e64 v53, v113, v70, s[6:7]
	v_cndmask_b32_e64 v52, v95, v67, s[6:7]
	v_pk_fma_f32 v[38:39], v[2:3], v[50:51], v[38:39]
	v_cndmask_b32_e64 v41, v106, v68, s[8:9]
	v_cndmask_b32_e64 v40, v92, v65, s[8:9]
	v_cndmask_b32_e64 v51, v118, v83, s[6:7]
	v_cndmask_b32_e64 v50, v116, v71, s[6:7]
	v_pk_fma_f32 v[52:53], v[8:9], v[52:53], v[12:13]
	v_cndmask_b32_e64 v43, v107, v69, s[8:9]
	v_cndmask_b32_e64 v42, v94, v66, s[8:9]
	v_pk_fma_f32 v[50:51], v[10:11], v[50:51], v[14:15]
	v_pk_fma_f32 v[40:41], v[4:5], v[40:41], v[52:53]
	v_pk_fma_f32 v[42:43], v[6:7], v[42:43], v[50:51]
	v_pk_fma_f32 v[50:51], v[0:1], v[48:49], v[40:41]
	v_lshlrev_b32_e32 v40, 16, v100
	v_and_b32_e32 v41, 0xffff0000, v100
	s_nop 1
	v_mov_b32_dpp v72, v40 row_ror:1 row_mask:0xf bank_mask:0xf
	v_mov_b32_dpp v73, v41 row_ror:1 row_mask:0xf bank_mask:0xf
	v_mov_b32_dpp v76, v40 row_ror:2 row_mask:0xf bank_mask:0xf
	v_mov_b32_dpp v77, v41 row_ror:2 row_mask:0xf bank_mask:0xf
	v_cndmask_b32_e64 v49, v55, v73, s[8:9]
	v_cndmask_b32_e64 v48, v54, v72, s[8:9]
	v_cndmask_b32_e64 v55, v59, v77, s[6:7]
	v_cndmask_b32_e64 v54, v58, v76, s[6:7]
	s_waitcnt vmcnt(2)
	v_pk_fma_f32 v[54:55], v[28:29], v[54:55], v[32:33]
	v_pk_fma_f32 v[52:53], v[2:3], v[44:45], v[42:43]
	v_pk_fma_f32 v[48:49], v[24:25], v[48:49], v[54:55]
	v_lshlrev_b32_e32 v42, 16, v101
	v_pk_fma_f32 v[40:41], v[20:21], v[40:41], v[48:49]
	v_and_b32_e32 v43, 0xffff0000, v101
	v_and_b32_e32 v55, 0x7fffffff, v41
	v_and_b32_e32 v54, 0x7fffffff, v40
	s_nop 1
	v_pk_fma_f32 v[54:55], v[54:55], s[52:53], 1.0 op_sel_hi:[1,0,0]
	v_mov_b32_dpp v74, v42 row_ror:1 row_mask:0xf bank_mask:0xf
	v_mov_b32_dpp v75, v43 row_ror:1 row_mask:0xf bank_mask:0xf
	v_mov_b32_dpp v78, v42 row_ror:2 row_mask:0xf bank_mask:0xf
	v_mov_b32_dpp v79, v43 row_ror:2 row_mask:0xf bank_mask:0xf
	v_rcp_f32_e32 v54, v54
	v_rcp_f32_e32 v55, v55
	v_cndmask_b32_e64 v45, v57, v75, s[8:9]
	v_cndmask_b32_e64 v44, v56, v74, s[8:9]
	v_cndmask_b32_e64 v57, v61, v79, s[6:7]
	v_cndmask_b32_e64 v56, v60, v78, s[6:7]
	v_pk_fma_f32 v[56:57], v[30:31], v[56:57], v[34:35]
	v_pk_mul_f32 v[48:49], v[40:41], v[40:41]
	v_pk_fma_f32 v[44:45], v[26:27], v[44:45], v[56:57]
	v_mov_b64_e32 v[56:57], s[56:57]
	v_pk_mul_f32 v[48:49], v[48:49], s[42:43] op_sel_hi:[1,0]
	v_pk_fma_f32 v[58:59], v[54:55], s[54:55], v[56:57] op_sel_hi:[1,0,0]
	v_exp_f32_e32 v48, v48
	v_exp_f32_e32 v49, v49
	v_pk_fma_f32 v[58:59], v[54:55], v[58:59], s[58:59] op_sel_hi:[1,1,0]
	s_nop 0
	v_pk_fma_f32 v[58:59], v[54:55], v[58:59], s[60:61] op_sel_hi:[1,1,0]
	v_pk_fma_f32 v[42:43], v[22:23], v[42:43], v[44:45]
	v_pk_fma_f32 v[58:59], v[54:55], v[58:59], s[62:63] op_sel_hi:[1,1,0]
	v_pk_mul_f32 v[44:45], v[42:43], v[42:43]
	v_pk_mul_f32 v[54:55], v[54:55], v[58:59]
	v_pk_mul_f32 v[44:45], v[44:45], s[42:43] op_sel_hi:[1,0]
	v_pk_fma_f32 v[48:49], v[48:49], v[54:55], 0.5 op_sel_hi:[1,1,0] neg_lo:[1,0,0] neg_hi:[1,0,0]
	v_exp_f32_e32 v44, v44
	v_mul_f32_e64 v54, |v40|, v48
	v_mul_f32_e64 v55, |v41|, v49
	v_exp_f32_e32 v45, v45
	v_and_b32_e32 v48, 0x7fffffff, v42
	v_add_u32_e32 v136, v62, v46
	v_pk_fma_f32 v[40:41], v[40:41], 0.5, v[54:55] op_sel_hi:[1,0,1]
	v_and_b32_e32 v49, 0x7fffffff, v43
	v_pk_fma_f32 v[48:49], v[48:49], s[52:53], 1.0 op_sel_hi:[1,0,0]
	s_nop 0
	v_rcp_f32_e32 v48, v48
	v_rcp_f32_e32 v49, v49
	v_pk_mul_f32 v[36:37], v[36:37], v[40:41]
	s_nop 1
	v_cvt_pk_bf16_f32 v36, v36, v37
	v_pk_fma_f32 v[54:55], v[48:49], s[54:55], v[56:57] op_sel_hi:[1,0,0]
	s_nop 1
	v_pk_fma_f32 v[54:55], v[48:49], v[54:55], s[58:59] op_sel_hi:[1,1,0]
	s_nop 0
	v_pk_fma_f32 v[54:55], v[48:49], v[54:55], s[60:61] op_sel_hi:[1,1,0]
	s_nop 0
	v_pk_fma_f32 v[54:55], v[48:49], v[54:55], s[62:63] op_sel_hi:[1,1,0]
	s_nop 0
	v_pk_mul_f32 v[48:49], v[48:49], v[54:55]
	s_nop 0
	v_pk_fma_f32 v[44:45], v[44:45], v[48:49], 0.5 op_sel_hi:[1,1,0] neg_lo:[1,0,0] neg_hi:[1,0,0]
	s_nop 0
	v_mul_f32_e64 v48, |v42|, v44
	v_mul_f32_e64 v49, |v43|, v45
	v_pk_fma_f32 v[42:43], v[42:43], 0.5, v[48:49] op_sel_hi:[1,0,1]
	v_pk_mul_f32 v[38:39], v[38:39], v[42:43]
	s_nop 1
	v_cvt_pk_bf16_f32 v37, v38, v39
	v_lshl_add_u64 v[38:39], v[136:137], 1, s[26:27]
	global_store_dwordx2 v[38:39], v[36:37], off
	v_lshlrev_b32_e32 v36, 16, v98
	v_and_b32_e32 v37, 0xffff0000, v98
	v_lshlrev_b32_e32 v38, 16, v99
	v_mov_b32_dpp v44, v36 row_ror:2 row_mask:0xf bank_mask:0xf
	v_mov_b32_dpp v48, v37 row_ror:2 row_mask:0xf bank_mask:0xf
	v_mov_b32_dpp v40, v36 row_ror:1 row_mask:0xf bank_mask:0xf
	v_mov_b32_dpp v41, v37 row_ror:1 row_mask:0xf bank_mask:0xf
	v_cndmask_b32_e64 v61, v77, v48, s[6:7]
	v_cndmask_b32_e64 v60, v76, v44, s[6:7]
	v_cndmask_b32_e64 v59, v73, v41, s[8:9]
	v_cndmask_b32_e64 v58, v72, v40, s[8:9]
	v_pk_fma_f32 v[60:61], v[28:29], v[60:61], v[32:33]
	v_and_b32_e32 v39, 0xffff0000, v99
	v_pk_fma_f32 v[58:59], v[24:25], v[58:59], v[60:61]
	s_nop 1
	v_pk_fma_f32 v[36:37], v[20:21], v[36:37], v[58:59]
	s_nop 1
	v_and_b32_e32 v61, 0x7fffffff, v37
	v_and_b32_e32 v60, 0x7fffffff, v36
; __device__ __forceinline__ f32x2 gelu_pk(f32x2 v) {
;     const f32x2 av = __builtin_elementwise_abs(v), d = av * 0.2316418882f + 1.0f;
;     __device__ __forceinline__ void operator()(AccRef acc, const Unit& u, int wr, int wc, int fr, int fq) const {
;     ...
;                 {
;                     const f32x4 wu0 = *(const f32x4*)(cw + (DFF + jn)), wu1 = *(const f32x4*)(cw + (UPN + DFF + jn)), wu2 = *(const f32x4*)(cw + (2 * UPN + DFF + jn)), bu = *(const f32x4*)(cb + (DFF + jn));
;                     f32x4 pu1 = (f32x4){0.f, 0.f, 0.f, 0.f}, pu2 = pu1;
; #pragma unroll
;                     for (int m = 0; m < 4; ++m) {
;                         const f32x4 au = unpack4(pa[ai][1][m][n]);
;                         const f32x4 ru1 = ror1v(au), ru2 = ror2v(au);
;                         const f32x4 u1 = fr >= 1 ? ru1 : pu1, u2 = fr >= 2 ? ru2 : pu2;
;                         if (m == 0 && fr < 2) *(f32x4*)(edge + (unsigned)((grp * 4 + fr) * UPN + DFF + jn)) = au;
;                         if (m == 3 && fr >= 14) *(f32x4*)(edge + (unsigned)((grp * 4 + (fr - 12)) * UPN + DFF + jn)) = au;
;                         cu[m] = bu + wu0 * u2 + wu1 * u1 + wu2 * au;
;                         pu1 = ru1; pu2 = ru2; }
;                 }
;                 {
;                     const f32x4 wg0 = *(const f32x4*)(cw + jn), wg1 = *(const f32x4*)(cw + (UPN + jn)), wg2 = *(const f32x4*)(cw + (2 * UPN + jn)), bg = *(const f32x4*)(cb + jn);
;                     f32x4 pg1 = (f32x4){0.f, 0.f, 0.f, 0.f}, pg2 = pg1;
; #pragma unroll
;                     for (int m = 0; m < 4; ++m) { const int row = rowg + m * 16 + fr;
;                         const f32x4 ag = unpack4(pa[ai][0][m][n]);
;                         const f32x4 rg1 = ror1v(ag), rg2 = ror2v(ag);
;                         const f32x4 g1 = fr >= 1 ? rg1 : pg1, g2 = fr >= 2 ? rg2 : pg2;
;                         if (m == 0 && fr < 2) *(f32x4*)(edge + (unsigned)((grp * 4 + fr) * UPN + jn)) = ag;
;                         if (m == 3 && fr >= 14) *(f32x4*)(edge + (unsigned)((grp * 4 + (fr - 12)) * UPN + jn)) = ag;
;                         const f32x4 o = gelu4(bg + wg0 * g2 + wg1 * g1 + wg2 * ag) * cu[m];
;                         if (!(m == 0 && fr < 2)) *(u32x2*)(act + (unsigned)(row * DFF + jn)) = pack4(o);
;                         pg1 = rg1; pg2 = rg2; }
	v_pk_fma_f32 v[60:61], v[60:61], s[52:53], 1.0 op_sel_hi:[1,0,0]
	s_nop 1
	v_rcp_f32_e32 v60, v60
	v_rcp_f32_e32 v61, v61
	v_mov_b32_dpp v45, v38 row_ror:2 row_mask:0xf bank_mask:0xf
	v_mov_b32_dpp v49, v39 row_ror:2 row_mask:0xf bank_mask:0xf
	v_mov_b32_dpp v42, v38 row_ror:1 row_mask:0xf bank_mask:0xf
	v_mov_b32_dpp v43, v39 row_ror:1 row_mask:0xf bank_mask:0xf
	v_cndmask_b32_e64 v73, v79, v49, s[6:7]
	v_cndmask_b32_e64 v72, v78, v45, s[6:7]
	v_cndmask_b32_e64 v55, v75, v43, s[8:9]
	v_cndmask_b32_e64 v54, v74, v42, s[8:9]
	v_pk_fma_f32 v[72:73], v[30:31], v[72:73], v[34:35]
	v_pk_mul_f32 v[58:59], v[36:37], v[36:37]
	v_pk_fma_f32 v[54:55], v[26:27], v[54:55], v[72:73]
	v_pk_mul_f32 v[58:59], v[58:59], s[42:43] op_sel_hi:[1,0]
	v_pk_fma_f32 v[72:73], v[60:61], s[54:55], v[56:57] op_sel_hi:[1,0,0]
	v_exp_f32_e32 v58, v58
	v_exp_f32_e32 v59, v59
	v_pk_fma_f32 v[72:73], v[60:61], v[72:73], s[58:59] op_sel_hi:[1,1,0]
	s_nop 0
	v_pk_fma_f32 v[72:73], v[60:61], v[72:73], s[60:61] op_sel_hi:[1,1,0]
	v_pk_fma_f32 v[38:39], v[22:23], v[38:39], v[54:55]
	v_pk_fma_f32 v[72:73], v[60:61], v[72:73], s[62:63] op_sel_hi:[1,1,0]
	v_pk_mul_f32 v[54:55], v[38:39], v[38:39]
	v_pk_mul_f32 v[60:61], v[60:61], v[72:73]
	v_pk_mul_f32 v[54:55], v[54:55], s[42:43] op_sel_hi:[1,0]
	v_pk_fma_f32 v[58:59], v[58:59], v[60:61], 0.5 op_sel_hi:[1,1,0] neg_lo:[1,0,0] neg_hi:[1,0,0]
	v_exp_f32_e32 v54, v54
	v_mul_f32_e64 v60, |v36|, v58
	v_mul_f32_e64 v61, |v37|, v59
	v_exp_f32_e32 v55, v55
	v_and_b32_e32 v58, 0x7fffffff, v38
	v_add_u32_e32 v136, v63, v46
	v_pk_fma_f32 v[36:37], v[36:37], 0.5, v[60:61] op_sel_hi:[1,0,1]
	v_and_b32_e32 v59, 0x7fffffff, v39
	v_pk_fma_f32 v[58:59], v[58:59], s[52:53], 1.0 op_sel_hi:[1,0,0]
	s_nop 0
	v_rcp_f32_e32 v58, v58
	v_rcp_f32_e32 v59, v59
	v_pk_mul_f32 v[36:37], v[50:51], v[36:37]
	s_nop 1
	v_cvt_pk_bf16_f32 v36, v36, v37
	v_pk_fma_f32 v[56:57], v[58:59], s[54:55], v[56:57] op_sel_hi:[1,0,0]
	s_nop 1
	v_pk_fma_f32 v[56:57], v[58:59], v[56:57], s[58:59] op_sel_hi:[1,1,0]
	s_nop 0
	v_pk_fma_f32 v[56:57], v[58:59], v[56:57], s[60:61] op_sel_hi:[1,1,0]
	s_nop 0
	v_pk_fma_f32 v[56:57], v[58:59], v[56:57], s[62:63] op_sel_hi:[1,1,0]
	s_nop 0
	v_pk_mul_f32 v[56:57], v[58:59], v[56:57]
	s_nop 0
	v_pk_fma_f32 v[54:55], v[54:55], v[56:57], 0.5 op_sel_hi:[1,1,0] neg_lo:[1,0,0] neg_hi:[1,0,0]
	s_nop 0
	v_mul_f32_e64 v56, |v38|, v54
	v_mul_f32_e64 v57, |v39|, v55
	v_pk_fma_f32 v[38:39], v[38:39], 0.5, v[56:57] op_sel_hi:[1,0,1]
	v_pk_mul_f32 v[38:39], v[52:53], v[38:39]
	s_nop 1
	v_cvt_pk_bf16_f32 v37, v38, v39
	v_lshl_add_u64 v[38:39], v[136:137], 1, s[26:27]
	global_store_dwordx2 v[38:39], v[36:37], off
	v_lshlrev_b32_e32 v36, 16, v96
	v_and_b32_e32 v37, 0xffff0000, v96
	v_lshlrev_b32_e32 v38, 16, v97
	v_and_b32_e32 v39, 0xffff0000, v97
	s_nop 1
	v_mov_b32_dpp v50, v36 row_ror:1 row_mask:0xf bank_mask:0xf
	v_mov_b32_dpp v51, v37 row_ror:1 row_mask:0xf bank_mask:0xf
	v_mov_b32_dpp v52, v38 row_ror:1 row_mask:0xf bank_mask:0xf
	v_mov_b32_dpp v53, v39 row_ror:1 row_mask:0xf bank_mask:0xf
	v_mov_b32_dpp v54, v36 row_ror:2 row_mask:0xf bank_mask:0xf
	v_mov_b32_dpp v56, v37 row_ror:2 row_mask:0xf bank_mask:0xf
	v_mov_b32_dpp v55, v38 row_ror:2 row_mask:0xf bank_mask:0xf
	v_mov_b32_dpp v57, v39 row_ror:2 row_mask:0xf bank_mask:0xf
	s_and_saveexec_b64 s[0:1], vcc
	s_cbranch_execz .LBB0_1446
	v_add_u32_e32 v136, v46, v47
	v_lshl_add_u64 v[58:59], v[136:137], 2, s[28:29]
	global_store_dwordx4 v[58:59], v[36:39], off
.LBB0_1446:
	s_or_b64 exec, exec, s[0:1]
	v_cndmask_b32_e64 v43, v43, v53, s[8:9]
	v_cndmask_b32_e64 v42, v42, v52, s[8:9]
	v_cndmask_b32_e64 v53, v83, v91, s[6:7]
	v_cndmask_b32_e64 v52, v71, v90, s[6:7]
	v_cndmask_b32_e64 v41, v41, v51, s[8:9]
	v_cndmask_b32_e64 v40, v40, v50, s[8:9]
	v_cndmask_b32_e64 v51, v69, v88, s[8:9]
	v_cndmask_b32_e64 v50, v66, v85, s[8:9]
	v_pk_fma_f32 v[10:11], v[10:11], v[52:53], v[14:15]
	v_cndmask_b32_e64 v59, v48, v56, s[6:7]
	v_cndmask_b32_e64 v58, v44, v54, s[6:7]
	v_pk_fma_f32 v[6:7], v[6:7], v[50:51], v[10:11]
	v_cndmask_b32_e64 v48, v45, v55, s[6:7]
	v_pk_fma_f32 v[2:3], v[2:3], v[18:19], v[6:7]
	v_pk_fma_f32 v[6:7], v[28:29], v[58:59], v[32:33]
	v_cndmask_b32_e64 v55, v70, v89, s[6:7]
	v_pk_fma_f32 v[6:7], v[24:25], v[40:41], v[6:7]
	v_cndmask_b32_e64 v54, v67, v86, s[6:7]
	v_pk_fma_f32 v[6:7], v[20:21], v[36:37], v[6:7]
	v_pk_fma_f32 v[8:9], v[8:9], v[54:55], v[12:13]
	v_and_b32_e32 v13, 0x7fffffff, v7
	v_and_b32_e32 v12, 0x7fffffff, v6
	v_pk_fma_f32 v[12:13], v[12:13], s[52:53], 1.0 op_sel_hi:[1,0,0]
	v_cndmask_b32_e64 v45, v68, v87, s[8:9]
	v_rcp_f32_e32 v12, v12
	v_rcp_f32_e32 v13, v13
	v_cndmask_b32_e64 v44, v65, v84, s[8:9]
	v_pk_fma_f32 v[4:5], v[4:5], v[44:45], v[8:9]
	v_pk_mul_f32 v[10:11], v[6:7], v[6:7]
	v_mov_b64_e32 v[14:15], s[56:57]
	v_pk_fma_f32 v[0:1], v[0:1], v[16:17], v[4:5]
	v_pk_mul_f32 v[10:11], v[10:11], s[42:43] op_sel_hi:[1,0]
	v_pk_fma_f32 v[16:17], v[12:13], s[54:55], v[14:15] op_sel_hi:[1,0,0]
	v_exp_f32_e32 v10, v10
	v_exp_f32_e32 v11, v11
	v_pk_fma_f32 v[16:17], v[12:13], v[16:17], s[58:59] op_sel_hi:[1,1,0]
	v_cndmask_b32_e64 v49, v49, v57, s[6:7]
	v_pk_fma_f32 v[16:17], v[12:13], v[16:17], s[60:61] op_sel_hi:[1,1,0]
	v_pk_fma_f32 v[4:5], v[30:31], v[48:49], v[34:35]
	v_pk_fma_f32 v[16:17], v[12:13], v[16:17], s[62:63] op_sel_hi:[1,1,0]
	v_pk_fma_f32 v[4:5], v[26:27], v[42:43], v[4:5]
	v_pk_mul_f32 v[12:13], v[12:13], v[16:17]
	s_nop 0
	v_pk_fma_f32 v[10:11], v[10:11], v[12:13], 0.5 op_sel_hi:[1,1,0] neg_lo:[1,0,0] neg_hi:[1,0,0]
	v_pk_fma_f32 v[4:5], v[22:23], v[38:39], v[4:5]
	v_mul_f32_e64 v12, |v6|, v10
	v_mul_f32_e64 v13, |v7|, v11
	v_pk_mul_f32 v[8:9], v[4:5], v[4:5]
	s_nop 0
	v_and_b32_e32 v10, 0x7fffffff, v4
	v_pk_mul_f32 v[8:9], v[8:9], s[42:43] op_sel_hi:[1,0]
	v_pk_fma_f32 v[6:7], v[6:7], 0.5, v[12:13] op_sel_hi:[1,0,1]
	v_and_b32_e32 v11, 0x7fffffff, v5
	v_pk_fma_f32 v[10:11], v[10:11], s[52:53], 1.0 op_sel_hi:[1,0,0]
	v_exp_f32_e32 v8, v8
	v_rcp_f32_e32 v10, v10
	v_rcp_f32_e32 v11, v11
	v_exp_f32_e32 v9, v9
	s_nop 0
	v_pk_mul_f32 v[0:1], v[0:1], v[6:7]
	v_pk_fma_f32 v[12:13], v[10:11], s[54:55], v[14:15] op_sel_hi:[1,0,0]
	v_add_u32_e32 v136, v64, v46
	v_pk_fma_f32 v[12:13], v[10:11], v[12:13], s[58:59] op_sel_hi:[1,1,0]
	v_cvt_pk_bf16_f32 v0, v0, v1
	s_mov_b64 s[0:1], -1
	v_pk_fma_f32 v[12:13], v[10:11], v[12:13], s[60:61] op_sel_hi:[1,1,0]
	s_nop 0
	v_pk_fma_f32 v[12:13], v[10:11], v[12:13], s[62:63] op_sel_hi:[1,1,0]
	s_nop 0
	v_pk_mul_f32 v[10:11], v[10:11], v[12:13]
	s_nop 0
	v_pk_fma_f32 v[8:9], v[8:9], v[10:11], 0.5 op_sel_hi:[1,1,0] neg_lo:[1,0,0] neg_hi:[1,0,0]
	s_nop 0
	v_mul_f32_e64 v10, |v4|, v8
	v_mul_f32_e64 v11, |v5|, v9
	v_pk_fma_f32 v[4:5], v[4:5], 0.5, v[10:11] op_sel_hi:[1,0,1]
	v_pk_mul_f32 v[2:3], v[2:3], v[4:5]
	s_andn2_b64 vcc, exec, s[4:5]
	v_cvt_pk_bf16_f32 v1, v2, v3
	v_lshl_add_u64 v[2:3], v[136:137], 1, s[26:27]
	global_store_dwordx2 v[2:3], v[0:1], off
	s_cbranch_vccnz .LBB0_1399
	s_andn2_b64 vcc, exec, s[16:17]
	s_cbranch_vccnz .LBB0_1398
	s_barrier
	s_branch .LBB0_1398
